# wr=1 deferred barrier now executes after tile-loop header and accumulator zeroing (right before K-loop entry)
# speedup vs baseline: 1.0161x; 1.0005x over previous
; #define LAS __attribute__((address_space(3)))
; __device__ __forceinline__ unsigned xb_add(unsigned* p, unsigned v) { return __hip_atomic_fetch_add(p, v, __ATOMIC_RELAXED, __HIP_MEMORY_SCOPE_AGENT); }
; __device__ __forceinline__ unsigned xb_xcc_id() { return (unsigned)__builtin_amdgcn_s_getreg((3 << 11) | 20) & 0xFu; }
; __device__ __forceinline__ XcdBarrier xcd_barrier_post(unsigned* bar, volatile LAS unsigned* st) {
;     XcdBarrier b; b.bar = bar; b.x = xb_xcc_id(); b.st = st;
;     if (threadIdx.x == 0) (void)xb_add(&bar[XB_XCNT(b.x)], 1u);
;     return b;
; }
; __global__ void __launch_bounds__(NTHREADS, 2) fwd_megakernel(Params p) {
;     extern __shared__ __attribute__((aligned(16))) unsigned char lds_raw[];
;     LAS unsigned char* lds = (LAS unsigned char*)lds_raw;
;     const int G = gridDim.x, c = blockIdx.x;
;     volatile LAS unsigned* xst = (volatile LAS unsigned*)(lds + STAGE_BYTES);
;     unsigned* barw = (unsigned*)(p.ws + WS_BAR);
;     if (threadIdx.x < 2) xst[threadIdx.x] = 0u;
;     __syncthreads();
;     const XcdBarrier xb = xcd_barrier_post(barw, xst);
_Z14fwd_megakernel6Params:
	s_load_dwordx16 s[12:27], s[0:1], 0x40
	s_load_dword s33, s[0:1], 0x80
	s_mov_b32 s8, s2
	s_mov_b32 s101, 0
	s_add_u32 s2, s0, 0x80
	s_addc_u32 s3, s1, 0
	v_cmp_gt_u32_e32 vcc, 2, v0
	v_writelane_b32 v230, s2, 0
	s_nop 1
	v_writelane_b32 v230, s3, 1
	s_and_saveexec_b64 s[2:3], vcc
	v_lshl_add_u32 v1, v0, 2, 0
	v_add_u32_e32 v1, 0x20000, v1
	v_mov_b32_e32 v2, 0
	ds_write_b32 v1, v2
	s_or_b64 exec, exec, s[2:3]
	s_load_dwordx16 s[36:51], s[0:1], 0x0
	s_waitcnt lgkmcnt(0)
	s_add_u32 s88, s26, 0x2f040000
	s_barrier
	s_getreg_b32 s0, hwreg(HW_REG_XCC_ID, 0, 4)
	s_addc_u32 s89, s27, 0
	s_and_b32 s0, s0, 15
	v_writelane_b32 v230, s0, 2
	v_cmp_eq_u32_e64 s[0:1], 0, v0
	s_mov_b64 s[2:3], exec
	s_nop 0
	v_writelane_b32 v230, s0, 3
	s_nop 1
	v_writelane_b32 v230, s1, 4
	s_and_b64 s[0:1], s[2:3], s[0:1]
	s_mov_b64 exec, s[0:1]
	s_cbranch_execz .LBB0_5
	s_mov_b64 s[4:5], exec
	v_mbcnt_lo_u32_b32 v1, s4, 0
	v_mbcnt_hi_u32_b32 v1, s5, v1
	v_cmp_eq_u32_e32 vcc, 0, v1
	s_and_b64 s[0:1], exec, vcc
	s_mov_b64 exec, s[0:1]
	s_cbranch_execz .LBB0_5
	v_readlane_b32 s0, v230, 2
	s_lshl_b32 s0, s0, 8
	s_bcnt1_i32_b64 s1, s[4:5]
	v_mov_b32_e32 v1, s0
	v_mov_b32_e32 v2, s1
	global_atomic_add v1, v2, s[88:89] offset:1024

; #define G_STAGE(bufoff, gbase, voff) do { _Pragma("unroll") for (int _i = 0; _i < 2; ++_i) \
;         __builtin_amdgcn_global_load_lds((const unsigned*)((const char*)(gbase) + (voff)[_i]), (LAS unsigned*)(lds + (bufoff) + ldsw + _i * 8192), 16, 0, 0); } while (0)
; #define G_WAIT_V(n) asm volatile("s_waitcnt vmcnt(" #n ")" ::: "memory")
; #define G_BAR __builtin_amdgcn_s_barrier()
;     __device__ __forceinline__ bool next(int i, Unit& u) const { const int L = i * G + (G - 1 - c); if (L >= 3264) return false; tile_map(L, 136, 24, u.pm, u.pn); u.pn += 4;     u.kh = 0; u.type = 0; return true; }
;     __device__ __forceinline__ bool next(int i, Unit& u) const { const int L = i * G + (G - 1 - c); if (L >= 2176) return false; tile_map(L, 136, 16, u.pm, u.pn); u.pn += 24; u.kh = 0; u.type = 0; return true; }
;     __device__ __forceinline__ bool next(int i, Unit& u) const { const int L = (i >> 1) * G + c; if (L >= 1024) return false; tile_map(L, 128, 8, u.pm, u.pn); u.kh = i & 1; u.type = 0; return true; }
;     __device__ __forceinline__ bool next(int i, Unit& u) const { const int L = (i >> 1) * G + c; if (L >= 128) return false; tile_map(L, 16, 8, u.pm, u.pn); u.pm += 120; u.kh = i & 1; u.type = 1; return true; }
; template <int MODE  , class Epi, class Sched>
; __device__ __forceinline__ void gemm_phase(LAS unsigned char* lds, const GemmDesc g, const Sched& S, const Epi& E) {
;     ...
;     G_WAIT_V(4); G_BAR;
;     G_STAGE(G_SB(1, 0), cB + kstep, voffB); G_STAGE(G_SA(1, 0), cA + kstep, voffA); G_STAGE(G_SB(1, 1), cB + hstepB + kstep, voffB);
;     G_WAIT_V(6); G_BAR;
;     for (;;) {
;         const bool has_next = S.next(ui + 1, nxt);
;         const char* nA = has_next ? (const char*)(nxt.type ? g.A2 : g.A) + (size_t)nxt.pm * 2 * hstepA + (size_t)nxt.kh * khb : cA;
.LBB0_518:
	s_add_u32 s4, s26, 0x39615000
	s_addc_u32 s5, s27, 0
	s_lshl_b32 s2, s2, 5
	s_mov_b64 s[16:17], 0x80
	s_and_b32 s11, s2, 0x60
	s_add_i32 m0, s55, 0x18000
	v_lshl_add_u64 v[8:9], v[8:9], 0, s[16:17]
	s_lshl_b32 s10, s0, 13
	s_lshl_b32 s18, s11, 7
	s_waitcnt vmcnt(4)
	s_barrier
	global_load_lds_dwordx4 v[8:9], off
	v_lshl_add_u64 v[6:7], v[6:7], 0, s[16:17]
	s_add_i32 m0, s55, 0x1a000
	s_add_i32 s60, s55, 0x8000
	s_add_i32 s61, s55, 0xa000
	global_load_lds_dwordx4 v[6:7], off
	v_lshl_add_u64 v[4:5], v[4:5], 0, s[16:17]
	s_mov_b32 m0, s60
	s_add_u32 s2, s40, 0x44080
	global_load_lds_dwordx4 v[4:5], off
	v_lshl_add_u64 v[2:3], v[2:3], 0, s[16:17]
	s_mov_b32 m0, s61
	s_addc_u32 s3, s41, 0
	global_load_lds_dwordx4 v[2:3], off
	s_add_i32 m0, s55, 0x1c000
	v_lshl_add_u64 v[2:3], s[2:3], 0, v[148:149]
	global_load_lds_dwordx4 v[2:3], off
	v_lshl_add_u64 v[2:3], s[2:3], 0, v[152:153]
	s_add_i32 m0, s55, 0x1e000
	s_mov_b64 s[2:3], 0x44080
	global_load_lds_dwordx4 v[2:3], off
	v_lshrrev_b32_e32 v3, 1, v10
	v_and_b32_e32 v3, 24, v3
	v_and_b32_e32 v2, 15, v10
	v_lshlrev_b32_e32 v4, 1, v3
	v_lshl_or_b32 v1, s0, 6, v2
	v_lshl_or_b32 v2, v2, 6, v4
	v_lshlrev_b32_e32 v4, 2, v10
	v_or_b32_e32 v192, s11, v3
	v_and_b32_e32 v4, 32, v4
	v_lshlrev_b32_e32 v154, 2, v192
	v_bitop3_b32 v5, v2, s10, v4 bitop3:0xde
	v_bitop3_b32 v191, v2, s18, v4 bitop3:0xde
	v_lshl_add_u64 v[2:3], s[26:27], 0, v[154:155]
	s_mov_b64 s[10:11], 0x3960f000
	v_lshl_add_u64 v[156:157], v[2:3], 0, s[10:11]
	v_lshrrev_b32_e32 v3, 1, v11
	v_mul_lo_u32 v2, v13, s1
	s_movk_i32 s0, 0x4400
	v_mad_u64_u32 v[2:3], s[10:11], v3, s0, v[2:3]
	v_or_b32_e32 v2, v2, v12
	v_add_lshl_u32 v154, v2, v14, 1
	v_lshrrev_b32_e32 v3, 1, v15
	v_mul_lo_u32 v2, v16, s1
	v_mad_u64_u32 v[2:3], s[0:1], v3, s0, v[2:3]
	s_waitcnt vmcnt(6)
	v_or_b32_e32 v2, v2, v17
	s_add_i32 s66, 0, 0x10000
	s_add_i32 s68, 0, 0x14000
	v_lshl_add_u64 v[158:159], v[154:155], 0, s[2:3]
	v_add_lshl_u32 v154, v2, v18, 1
	v_add_u32_e32 v193, s66, v191
	v_add_u32_e32 v195, s68, v191
	s_add_i32 s66, s66, s54
	s_add_i32 s68, s68, s54
	v_lshl_add_u64 v[160:161], v[154:155], 0, s[2:3]
	s_movk_i32 s62, 0x199
	v_add_u32_e32 v194, 0, v5
	s_mov_b32 s63, 0xc2200000
	s_add_i32 s64, s55, 0xc000
	s_add_i32 s65, s55, 0xe000
	s_add_i32 s67, s66, 0x2000
	s_add_i32 s69, s68, 0x2000
	v_mov_b32_e32 v196, 0x42200000
	s_waitcnt vmcnt(0)
	s_barrier
	ds_read_b128 v[232:235], v193
	ds_read_b128 v[236:239], v193 offset:1024
	ds_read_b128 v[240:243], v193 offset:2048
	ds_read_b128 v[244:247], v193 offset:3072
	s_branch .LBB0_520
.LBB0_519:
	s_and_b64 vcc, exec, s[18:19]
	s_mov_b32 s75, s71
	s_mov_b32 s73, s70
	s_mov_b64 s[40:41], s[2:3]
	s_mov_b64 s[34:35], s[20:21]
	s_cbranch_vccnz .LBB0_634

; #define G_STAGE(bufoff, gbase, voff) do { _Pragma("unroll") for (int _i = 0; _i < 2; ++_i) \
;         __builtin_amdgcn_global_load_lds((const unsigned*)((const char*)(gbase) + (voff)[_i]), (LAS unsigned*)(lds + (bufoff) + ldsw + _i * 8192), 16, 0, 0); } while (0)
; #define G_WAIT_L(n) asm volatile("s_waitcnt lgkmcnt(" #n ")" ::: "memory")
; #define G_BAR __builtin_amdgcn_s_barrier()
; #define G_SCHED __builtin_amdgcn_sched_barrier(0)
; template <int MODE  , class Epi, class Sched>
; __device__ __forceinline__ void gemm_phase(LAS unsigned char* lds, const GemmDesc g, const Sched& S, const Epi& E) {
;     ...
;             G_LDB(B0, 0, 0); G_SCHED; G_LDA(At, 0, 0); G_STAGE(G_SA(1, 1), a1 + hstepA, voffA);
;             G_WAIT_L(8); G_BAR; G_WAIT_L(0); G_MMA(0, 0, At, B0); G_BAR; G_SCHED;
;             G_LDB(B1, 0, 1); G_STAGE(G_SB(0, 0), b2, voffB);
;             G_BAR; G_WAIT_L(0); G_MMA(0, 1, At, B1); G_BAR;
;     ...
;         if (zero) {
; #pragma unroll
;             for (int a = 0; a < 2; ++a)
; #pragma unroll
;                 for (int b = 0; b < 2; ++b)
; #pragma unroll
;                     for (int m = 0; m < 4; ++m)
; #pragma unroll
;                         for (int n = 0; n < 2; ++n) acc[a][b][m][n] = (f32x4){0.f, 0.f, 0.f, 0.f};
.LBB0_526:
	s_add_u32 s72, s40, 0x100
	v_mov_b32_e32 v10, 0
	s_addc_u32 s76, s41, 0
	s_mov_b32 s77, -2
	v_lshl_add_u32 v198, s73, 8, v1
	v_ashrrev_i32_e32 v199, 31, v198
	v_lshl_add_u64 v[198:199], v[198:199], 2, s[4:5]
	global_load_dword v248, v[198:199], off
	global_load_dword v249, v[198:199], off offset:64
	global_load_dword v250, v[198:199], off offset:128
	global_load_dword v251, v[198:199], off offset:192
	global_load_dword v252, v[198:199], off offset:512
	global_load_dword v253, v[198:199], off offset:576
	global_load_dword v254, v[198:199], off offset:640
	global_load_dword v255, v[198:199], off offset:704
	v_mov_b32_e32 v11, v10
	v_mov_b64_e32 v[12:13], v[10:11]
	v_mov_b64_e32 v[14:15], v[10:11]
	v_mov_b64_e32 v[16:17], v[10:11]
	v_mov_b64_e32 v[26:27], v[10:11]
	v_mov_b64_e32 v[28:29], v[10:11]
	v_mov_b64_e32 v[30:31], v[10:11]
	v_mov_b64_e32 v[32:33], v[10:11]
	v_mov_b64_e32 v[58:59], v[10:11]
	v_mov_b64_e32 v[60:61], v[10:11]
	v_mov_b64_e32 v[62:63], v[10:11]
	v_mov_b64_e32 v[64:65], v[10:11]
	v_mov_b64_e32 v[74:75], v[10:11]
	v_mov_b64_e32 v[76:77], v[10:11]
	v_mov_b64_e32 v[78:79], v[10:11]
	v_mov_b64_e32 v[80:81], v[10:11]
	v_mov_b64_e32 v[2:3], v[10:11]
	v_mov_b64_e32 v[4:5], v[10:11]
	v_mov_b64_e32 v[6:7], v[10:11]
	v_mov_b64_e32 v[8:9], v[10:11]
	v_mov_b64_e32 v[18:19], v[10:11]
	v_mov_b64_e32 v[20:21], v[10:11]
	v_mov_b64_e32 v[22:23], v[10:11]
	v_mov_b64_e32 v[24:25], v[10:11]
	v_mov_b64_e32 v[50:51], v[10:11]
	v_mov_b64_e32 v[52:53], v[10:11]
	v_mov_b64_e32 v[54:55], v[10:11]
	v_mov_b64_e32 v[56:57], v[10:11]
	v_mov_b64_e32 v[66:67], v[10:11]
	v_mov_b64_e32 v[68:69], v[10:11]
	v_mov_b64_e32 v[70:71], v[10:11]
	v_mov_b64_e32 v[72:73], v[10:11]
	v_mov_b64_e32 v[90:91], v[10:11]
	v_mov_b64_e32 v[92:93], v[10:11]
	v_mov_b64_e32 v[94:95], v[10:11]
	v_mov_b64_e32 v[96:97], v[10:11]
	v_mov_b64_e32 v[106:107], v[10:11]
	v_mov_b64_e32 v[108:109], v[10:11]
	v_mov_b64_e32 v[110:111], v[10:11]
	v_mov_b64_e32 v[112:113], v[10:11]
	v_mov_b64_e32 v[122:123], v[10:11]
	v_mov_b64_e32 v[124:125], v[10:11]
	v_mov_b64_e32 v[126:127], v[10:11]
	v_mov_b64_e32 v[128:129], v[10:11]
	v_mov_b64_e32 v[138:139], v[10:11]
	v_mov_b64_e32 v[140:141], v[10:11]
	v_mov_b64_e32 v[142:143], v[10:11]
	v_mov_b64_e32 v[144:145], v[10:11]
	v_mov_b64_e32 v[82:83], v[10:11]
	v_mov_b64_e32 v[84:85], v[10:11]
	v_mov_b64_e32 v[86:87], v[10:11]
	v_mov_b64_e32 v[88:89], v[10:11]
	v_mov_b64_e32 v[98:99], v[10:11]
	v_mov_b64_e32 v[100:101], v[10:11]
	v_mov_b64_e32 v[102:103], v[10:11]
	v_mov_b64_e32 v[104:105], v[10:11]
	v_mov_b64_e32 v[114:115], v[10:11]
	v_mov_b64_e32 v[116:117], v[10:11]
	v_mov_b64_e32 v[118:119], v[10:11]
	v_mov_b64_e32 v[120:121], v[10:11]
	v_mov_b64_e32 v[130:131], v[10:11]
	v_mov_b64_e32 v[132:133], v[10:11]
	v_mov_b64_e32 v[134:135], v[10:11]
	v_mov_b64_e32 v[136:137], v[10:11]
	s_cmp_eq_u32 s101, 1
	s_cbranch_scc0 .Lnodb_p1c
	s_barrier
	s_mov_b32 s101, 0
.Lnodb_p1c:
.LBB0_527:
	s_add_u32 s40, s34, 0x100
	s_addc_u32 s41, s35, 0
	s_cmp_eq_u32 s77, 12
	s_cselect_b32 s47, s21, s41
	s_cselect_b32 s46, s20, s40
	s_cselect_b32 s45, s3, s76
	s_cselect_b32 s44, s2, s72
	s_mov_b32 m0, s64
	s_add_u32 s98, s34, 0x44080
	s_addc_u32 s99, s35, 0
	ds_read_b128 v[162:165], v194
	ds_read_b128 v[166:169], v194 offset:1024
	ds_read_b128 v[170:173], v194 offset:2048
	ds_read_b128 v[174:177], v194 offset:3072
	ds_read_b128 v[178:181], v194 offset:4096
	ds_read_b128 v[182:185], v194 offset:5120
	ds_read_b128 v[186:189], v194 offset:6144
	ds_read_b128 v[198:201], v194 offset:7168
	global_load_lds_dwordx4 v146, s[98:99]
	s_mov_b32 m0, s65
	s_nop 0
	global_load_lds_dwordx4 v150, s[98:99]
	s_waitcnt lgkmcnt(8)
	s_barrier
	s_waitcnt lgkmcnt(0)
	s_setprio 1
	s_waitcnt lgkmcnt(0)
	v_mfma_i32_16x16x64_i8 v[134:137], v[232:235], v[162:165], v[134:137]
	v_mfma_i32_16x16x64_i8 v[130:133], v[240:243], v[162:165], v[130:133]
	v_mfma_i32_16x16x64_i8 v[118:121], v[232:235], v[170:173], v[118:121]
	v_mfma_i32_16x16x64_i8 v[114:117], v[240:243], v[170:173], v[114:117]
	v_mfma_i32_16x16x64_i8 v[102:105], v[232:235], v[178:181], v[102:105]
	v_mfma_i32_16x16x64_i8 v[98:101], v[240:243], v[178:181], v[98:101]
	v_mfma_i32_16x16x64_i8 v[86:89], v[232:235], v[186:189], v[86:89]
	v_mfma_i32_16x16x64_i8 v[82:85], v[240:243], v[186:189], v[82:85]
	v_mfma_i32_16x16x64_i8 v[134:137], v[236:239], v[166:169], v[134:137]
	v_mfma_i32_16x16x64_i8 v[130:133], v[244:247], v[166:169], v[130:133]
	v_mfma_i32_16x16x64_i8 v[118:121], v[236:239], v[174:177], v[118:121]
	v_mfma_i32_16x16x64_i8 v[114:117], v[244:247], v[174:177], v[114:117]
	v_mfma_i32_16x16x64_i8 v[102:105], v[236:239], v[182:185], v[102:105]
	v_mfma_i32_16x16x64_i8 v[98:101], v[244:247], v[182:185], v[98:101]
	v_mfma_i32_16x16x64_i8 v[86:89], v[236:239], v[198:201], v[86:89]
	v_mfma_i32_16x16x64_i8 v[82:85], v[244:247], v[198:201], v[82:85]
	s_setprio 0
	s_barrier
	s_mov_b32 m0, s66
	ds_read_b128 v[202:205], v195
	ds_read_b128 v[206:209], v195 offset:1024
	ds_read_b128 v[210:213], v195 offset:2048
	ds_read_b128 v[214:217], v195 offset:3072
	global_load_lds_dwordx4 v148, s[44:45]
	s_mov_b32 m0, s67
	s_nop 0
	global_load_lds_dwordx4 v152, s[44:45]
	s_barrier
; #define G_STAGE(bufoff, gbase, voff) do { _Pragma("unroll") for (int _i = 0; _i < 2; ++_i) \
;         __builtin_amdgcn_global_load_lds((const unsigned*)((const char*)(gbase) + (voff)[_i]), (LAS unsigned*)(lds + (bufoff) + ldsw + _i * 8192), 16, 0, 0); } while (0)
; #define G_WAIT_V(n) asm volatile("s_waitcnt vmcnt(" #n ")" ::: "memory")
; #define G_WAIT_L(n) asm volatile("s_waitcnt lgkmcnt(" #n ")" ::: "memory")
; #define G_BAR __builtin_amdgcn_s_barrier()
; #define G_SCHED __builtin_amdgcn_sched_barrier(0)
; template <int MODE  , class Epi, class Sched>
; __device__ __forceinline__ void gemm_phase(LAS unsigned char* lds, const GemmDesc g, const Sched& S, const Epi& E) {
;     ...
;             G_BAR; G_WAIT_L(0); G_MMA(0, 1, At, B1); G_BAR;
;             G_LDA(At, 0, 1); G_STAGE(G_SA(0, 0), a2, voffA);
;             G_BAR; G_WAIT_L(0); G_MMA(1, 0, At, B0); G_BAR; G_SCHED;
;             G_STAGE(G_SB(0, 1), b2 + hstepB, voffB);
;             G_WAIT_V(6); G_BAR; G_MMA(1, 1, At, B1); G_BAR;
;             G_LDB(B0, 1, 0); G_SCHED; G_LDA(At, 1, 0); G_STAGE(G_SA(0, 1), a2 + hstepA, voffA);
;             G_WAIT_L(8); G_BAR; G_WAIT_L(0); G_MMA(0, 0, At, B0); G_BAR; G_SCHED;
	s_waitcnt lgkmcnt(0)
	s_setprio 1
	s_waitcnt lgkmcnt(0)
	v_mfma_i32_16x16x64_i8 v[142:145], v[202:205], v[162:165], v[142:145]
	v_mfma_i32_16x16x64_i8 v[138:141], v[210:213], v[162:165], v[138:141]
	v_mfma_i32_16x16x64_i8 v[126:129], v[202:205], v[170:173], v[126:129]
	v_mfma_i32_16x16x64_i8 v[122:125], v[210:213], v[170:173], v[122:125]
	v_mfma_i32_16x16x64_i8 v[110:113], v[202:205], v[178:181], v[110:113]
	v_mfma_i32_16x16x64_i8 v[106:109], v[210:213], v[178:181], v[106:109]
	v_mfma_i32_16x16x64_i8 v[94:97], v[202:205], v[186:189], v[94:97]
	v_mfma_i32_16x16x64_i8 v[90:93], v[210:213], v[186:189], v[90:93]
	v_mfma_i32_16x16x64_i8 v[142:145], v[206:209], v[166:169], v[142:145]
	v_mfma_i32_16x16x64_i8 v[138:141], v[214:217], v[166:169], v[138:141]
	v_mfma_i32_16x16x64_i8 v[126:129], v[206:209], v[174:177], v[126:129]
	v_mfma_i32_16x16x64_i8 v[122:125], v[214:217], v[174:177], v[122:125]
	v_mfma_i32_16x16x64_i8 v[110:113], v[206:209], v[182:185], v[110:113]
	v_mfma_i32_16x16x64_i8 v[106:109], v[214:217], v[182:185], v[106:109]
	v_mfma_i32_16x16x64_i8 v[94:97], v[206:209], v[198:201], v[94:97]
	v_mfma_i32_16x16x64_i8 v[90:93], v[214:217], v[198:201], v[90:93]
	s_setprio 0
	s_mov_b32 m0, s55
	s_barrier
	ds_read_b128 v[162:165], v194 offset:16384
	ds_read_b128 v[166:169], v194 offset:17408
	ds_read_b128 v[170:173], v194 offset:18432
	ds_read_b128 v[174:177], v194 offset:19456
	ds_read_b128 v[178:181], v194 offset:20480
	ds_read_b128 v[182:185], v194 offset:21504
	ds_read_b128 v[186:189], v194 offset:22528
	ds_read_b128 v[198:201], v194 offset:23552
	global_load_lds_dwordx4 v146, s[46:47]
	s_mov_b32 m0, s56
	s_nop 0
	global_load_lds_dwordx4 v150, s[46:47]
	s_barrier
	s_waitcnt lgkmcnt(0)
	s_setprio 1
	s_waitcnt lgkmcnt(0)
	v_mfma_i32_16x16x64_i8 v[70:73], v[232:235], v[162:165], v[70:73]
	v_mfma_i32_16x16x64_i8 v[66:69], v[240:243], v[162:165], v[66:69]
	v_mfma_i32_16x16x64_i8 v[54:57], v[232:235], v[170:173], v[54:57]
	v_mfma_i32_16x16x64_i8 v[50:53], v[240:243], v[170:173], v[50:53]
	v_mfma_i32_16x16x64_i8 v[22:25], v[232:235], v[178:181], v[22:25]
	v_mfma_i32_16x16x64_i8 v[18:21], v[240:243], v[178:181], v[18:21]
	v_mfma_i32_16x16x64_i8 v[6:9], v[232:235], v[186:189], v[6:9]
	v_mfma_i32_16x16x64_i8 v[2:5], v[240:243], v[186:189], v[2:5]
	v_mfma_i32_16x16x64_i8 v[70:73], v[236:239], v[166:169], v[70:73]
	v_mfma_i32_16x16x64_i8 v[66:69], v[244:247], v[166:169], v[66:69]
	v_mfma_i32_16x16x64_i8 v[54:57], v[236:239], v[174:177], v[54:57]
	v_mfma_i32_16x16x64_i8 v[50:53], v[244:247], v[174:177], v[50:53]
	v_mfma_i32_16x16x64_i8 v[22:25], v[236:239], v[182:185], v[22:25]
	v_mfma_i32_16x16x64_i8 v[18:21], v[244:247], v[182:185], v[18:21]
	v_mfma_i32_16x16x64_i8 v[6:9], v[236:239], v[198:201], v[6:9]
	v_mfma_i32_16x16x64_i8 v[2:5], v[244:247], v[198:201], v[2:5]
	s_setprio 0
	s_barrier
	s_mov_b32 m0, s68
	s_add_u32 s0, s44, 0x44000
	s_addc_u32 s1, s45, 0
	global_load_lds_dwordx4 v148, s[0:1]
	s_mov_b32 m0, s69
	s_nop 0
	global_load_lds_dwordx4 v152, s[0:1]
	s_waitcnt vmcnt(6)
	s_barrier
	s_setprio 1
	v_mfma_i32_16x16x64_i8 v[30:33], v[202:205], v[178:181], v[30:33]
	v_mfma_i32_16x16x64_i8 v[26:29], v[210:213], v[178:181], v[26:29]
	v_mfma_i32_16x16x64_i8 v[14:17], v[202:205], v[186:189], v[14:17]
	v_mfma_i32_16x16x64_i8 v[10:13], v[210:213], v[186:189], v[10:13]
	v_mfma_i32_16x16x64_i8 v[34:37], v[202:205], v[162:165], v[78:81]
	v_mfma_i32_16x16x64_i8 v[38:41], v[210:213], v[162:165], v[74:77]
	v_mfma_i32_16x16x64_i8 v[42:45], v[202:205], v[170:173], v[62:65]
	v_mfma_i32_16x16x64_i8 v[46:49], v[210:213], v[170:173], v[58:61]
	v_mfma_i32_16x16x64_i8 v[30:33], v[206:209], v[182:185], v[30:33]
	v_mfma_i32_16x16x64_i8 v[26:29], v[214:217], v[182:185], v[26:29]
	v_mfma_i32_16x16x64_i8 v[14:17], v[206:209], v[198:201], v[14:17]
	v_mfma_i32_16x16x64_i8 v[10:13], v[214:217], v[198:201], v[10:13]
	v_mfma_i32_16x16x64_i8 v[34:37], v[206:209], v[166:169], v[34:37]
	v_mfma_i32_16x16x64_i8 v[38:41], v[214:217], v[166:169], v[38:41]
	v_mfma_i32_16x16x64_i8 v[42:45], v[206:209], v[174:177], v[42:45]
	v_mfma_i32_16x16x64_i8 v[46:49], v[214:217], v[174:177], v[46:49]
	s_setprio 0
	s_add_i32 s10, 0, 0x18000
	v_add_u32_e32 v78, s10, v191
	s_barrier
	ds_read_b128 v[58:61], v78
	ds_read_b128 v[62:65], v78 offset:1024
	ds_read_b128 v[74:77], v78 offset:2048
	ds_read_b128 v[78:81], v78 offset:3072
	s_add_u32 s0, s46, 0x44000
	s_addc_u32 s1, s47, 0
	s_mov_b32 m0, s57
	ds_read_b128 v[162:165], v194 offset:32768
	ds_read_b128 v[166:169], v194 offset:33792
	ds_read_b128 v[170:173], v194 offset:34816
	ds_read_b128 v[174:177], v194 offset:35840
	ds_read_b128 v[178:181], v194 offset:36864
	ds_read_b128 v[182:185], v194 offset:37888
	ds_read_b128 v[186:189], v194 offset:38912
	ds_read_b128 v[198:201], v194 offset:39936
	global_load_lds_dwordx4 v146, s[0:1]
	s_mov_b32 m0, s58
	s_nop 0
	global_load_lds_dwordx4 v150, s[0:1]
	s_waitcnt lgkmcnt(8)
	s_barrier
	s_waitcnt lgkmcnt(0)
	s_setprio 1
	s_waitcnt lgkmcnt(0)
	v_mfma_i32_16x16x64_i8 v[134:137], v[58:61], v[162:165], v[134:137]
	v_mfma_i32_16x16x64_i8 v[130:133], v[74:77], v[162:165], v[130:133]
	v_mfma_i32_16x16x64_i8 v[118:121], v[58:61], v[170:173], v[118:121]
	v_mfma_i32_16x16x64_i8 v[114:117], v[74:77], v[170:173], v[114:117]
	v_mfma_i32_16x16x64_i8 v[102:105], v[58:61], v[178:181], v[102:105]
	v_mfma_i32_16x16x64_i8 v[98:101], v[74:77], v[178:181], v[98:101]
	v_mfma_i32_16x16x64_i8 v[86:89], v[58:61], v[186:189], v[86:89]
	v_mfma_i32_16x16x64_i8 v[82:85], v[74:77], v[186:189], v[82:85]
	v_mfma_i32_16x16x64_i8 v[134:137], v[62:65], v[166:169], v[134:137]
	v_mfma_i32_16x16x64_i8 v[130:133], v[78:81], v[166:169], v[130:133]
	v_mfma_i32_16x16x64_i8 v[118:121], v[62:65], v[174:177], v[118:121]
	v_mfma_i32_16x16x64_i8 v[114:117], v[78:81], v[174:177], v[114:117]
	v_mfma_i32_16x16x64_i8 v[102:105], v[62:65], v[182:185], v[102:105]
	v_mfma_i32_16x16x64_i8 v[98:101], v[78:81], v[182:185], v[98:101]
	v_mfma_i32_16x16x64_i8 v[86:89], v[62:65], v[198:201], v[86:89]
	v_mfma_i32_16x16x64_i8 v[82:85], v[78:81], v[198:201], v[82:85]
	s_setprio 0
	s_barrier
; #define G_STAGE(bufoff, gbase, voff) do { _Pragma("unroll") for (int _i = 0; _i < 2; ++_i) \
;         __builtin_amdgcn_global_load_lds((const unsigned*)((const char*)(gbase) + (voff)[_i]), (LAS unsigned*)(lds + (bufoff) + ldsw + _i * 8192), 16, 0, 0); } while (0)
; #define G_WAIT_V(n) asm volatile("s_waitcnt vmcnt(" #n ")" ::: "memory")
; #define G_WAIT_L(n) asm volatile("s_waitcnt lgkmcnt(" #n ")" ::: "memory")
; #define G_BAR __builtin_amdgcn_s_barrier()
; #define G_SCHED __builtin_amdgcn_sched_barrier(0)
; template <int MODE  , class Epi, class Sched>
; __device__ __forceinline__ void gemm_phase(LAS unsigned char* lds, const GemmDesc g, const Sched& S, const Epi& E) {
;     ...
;             G_LDB(B1, 1, 1); G_STAGE(G_SB(1, 0), b3, voffB);
;             G_BAR; G_WAIT_L(0); G_MMA(0, 1, At, B1); G_BAR;
;             G_LDA(At, 1, 1); G_STAGE(G_SA(1, 0), a3, voffA);
;             G_BAR; G_WAIT_L(0); G_MMA(1, 0, At, B0); G_BAR; G_SCHED;
;             G_STAGE(G_SB(1, 1), b3 + hstepB, voffB);
;             G_WAIT_V(6); G_BAR; G_MMA(1, 1, At, B1); G_BAR;
	s_add_i32 s11, 0, 0x1c000
	s_add_i32 s0, s10, s54
	v_add_u32_e32 v154, s11, v191
	s_add_u32 s98, s44, 0x80
	s_addc_u32 s99, s45, 0
	s_mov_b32 m0, s0
	ds_read_b128 v[202:205], v154
	ds_read_b128 v[206:209], v154 offset:1024
	ds_read_b128 v[210:213], v154 offset:2048
	ds_read_b128 v[214:217], v154 offset:3072
	global_load_lds_dwordx4 v148, s[98:99]
	s_add_i32 m0, s0, 0x2000
	s_nop 0
	global_load_lds_dwordx4 v152, s[98:99]
	s_barrier
	s_waitcnt lgkmcnt(0)
	s_setprio 1
	s_waitcnt lgkmcnt(0)
	v_mfma_i32_16x16x64_i8 v[142:145], v[202:205], v[162:165], v[142:145]
	v_mfma_i32_16x16x64_i8 v[138:141], v[210:213], v[162:165], v[138:141]
	v_mfma_i32_16x16x64_i8 v[126:129], v[202:205], v[170:173], v[126:129]
	v_mfma_i32_16x16x64_i8 v[122:125], v[210:213], v[170:173], v[122:125]
	v_mfma_i32_16x16x64_i8 v[110:113], v[202:205], v[178:181], v[110:113]
	v_mfma_i32_16x16x64_i8 v[106:109], v[210:213], v[178:181], v[106:109]
	v_mfma_i32_16x16x64_i8 v[94:97], v[202:205], v[186:189], v[94:97]
	v_mfma_i32_16x16x64_i8 v[90:93], v[210:213], v[186:189], v[90:93]
	v_mfma_i32_16x16x64_i8 v[142:145], v[206:209], v[166:169], v[142:145]
	v_mfma_i32_16x16x64_i8 v[138:141], v[214:217], v[166:169], v[138:141]
	v_mfma_i32_16x16x64_i8 v[126:129], v[206:209], v[174:177], v[126:129]
	v_mfma_i32_16x16x64_i8 v[122:125], v[214:217], v[174:177], v[122:125]
	v_mfma_i32_16x16x64_i8 v[110:113], v[206:209], v[182:185], v[110:113]
	v_mfma_i32_16x16x64_i8 v[106:109], v[214:217], v[182:185], v[106:109]
	v_mfma_i32_16x16x64_i8 v[94:97], v[206:209], v[198:201], v[94:97]
	v_mfma_i32_16x16x64_i8 v[90:93], v[214:217], v[198:201], v[90:93]
	s_setprio 0
	s_mov_b32 m0, s60
	s_barrier
	ds_read_b128 v[162:165], v194 offset:49152
	ds_read_b128 v[166:169], v194 offset:50176
	ds_read_b128 v[170:173], v194 offset:51200
	ds_read_b128 v[174:177], v194 offset:52224
	ds_read_b128 v[178:181], v194 offset:53248
	ds_read_b128 v[182:185], v194 offset:54272
	ds_read_b128 v[186:189], v194 offset:55296
	ds_read_b128 v[198:201], v194 offset:56320
	s_add_u32 s98, s46, 0x80
	s_addc_u32 s99, s47, 0
	global_load_lds_dwordx4 v146, s[98:99]
	s_mov_b32 m0, s61
	s_nop 0
	global_load_lds_dwordx4 v150, s[98:99]
	s_barrier
	s_waitcnt lgkmcnt(0)
	s_setprio 1
	s_waitcnt lgkmcnt(0)
	v_mfma_i32_16x16x64_i8 v[70:73], v[58:61], v[162:165], v[70:73]
	v_mfma_i32_16x16x64_i8 v[66:69], v[74:77], v[162:165], v[66:69]
	v_mfma_i32_16x16x64_i8 v[54:57], v[58:61], v[170:173], v[54:57]
	v_mfma_i32_16x16x64_i8 v[50:53], v[74:77], v[170:173], v[50:53]
	v_mfma_i32_16x16x64_i8 v[22:25], v[58:61], v[178:181], v[22:25]
	v_mfma_i32_16x16x64_i8 v[18:21], v[74:77], v[178:181], v[18:21]
	v_mfma_i32_16x16x64_i8 v[6:9], v[58:61], v[186:189], v[6:9]
	v_mfma_i32_16x16x64_i8 v[2:5], v[74:77], v[186:189], v[2:5]
	v_mfma_i32_16x16x64_i8 v[70:73], v[62:65], v[166:169], v[70:73]
	v_mfma_i32_16x16x64_i8 v[66:69], v[78:81], v[166:169], v[66:69]
	v_mfma_i32_16x16x64_i8 v[54:57], v[62:65], v[174:177], v[54:57]
	v_mfma_i32_16x16x64_i8 v[50:53], v[78:81], v[174:177], v[50:53]
	v_mfma_i32_16x16x64_i8 v[22:25], v[62:65], v[182:185], v[22:25]
	v_mfma_i32_16x16x64_i8 v[18:21], v[78:81], v[182:185], v[18:21]
	v_mfma_i32_16x16x64_i8 v[6:9], v[62:65], v[198:201], v[6:9]
	v_mfma_i32_16x16x64_i8 v[2:5], v[78:81], v[198:201], v[2:5]
	s_setprio 0
	s_barrier
	ds_read_b128 v[232:235], v193
	ds_read_b128 v[236:239], v193 offset:1024
	ds_read_b128 v[240:243], v193 offset:2048
	ds_read_b128 v[244:247], v193 offset:3072
	s_add_u32 s0, s44, 0x44080
	s_addc_u32 s1, s45, 0
	s_add_i32 s10, s11, s54
	s_mov_b32 m0, s10
	s_nop 0
	global_load_lds_dwordx4 v148, s[0:1]
	s_add_i32 m0, s10, 0x2000
	s_nop 0
	global_load_lds_dwordx4 v152, s[0:1]
	s_waitcnt vmcnt(6)
	s_barrier
	s_setprio 1
	v_mfma_i32_16x16x64_i8 v[34:37], v[202:205], v[162:165], v[34:37]
	v_mfma_i32_16x16x64_i8 v[78:81], v[206:209], v[166:169], v[34:37]
	v_mfma_i32_16x16x64_i8 v[34:37], v[210:213], v[162:165], v[38:41]
	v_mfma_i32_16x16x64_i8 v[74:77], v[214:217], v[166:169], v[34:37]
	v_mfma_i32_16x16x64_i8 v[34:37], v[202:205], v[170:173], v[42:45]
	v_mfma_i32_16x16x64_i8 v[62:65], v[206:209], v[174:177], v[34:37]
	v_mfma_i32_16x16x64_i8 v[34:37], v[210:213], v[170:173], v[46:49]
	v_mfma_i32_16x16x64_i8 v[30:33], v[202:205], v[178:181], v[30:33]
	v_mfma_i32_16x16x64_i8 v[26:29], v[210:213], v[178:181], v[26:29]
	v_mfma_i32_16x16x64_i8 v[14:17], v[202:205], v[186:189], v[14:17]
	v_mfma_i32_16x16x64_i8 v[10:13], v[210:213], v[186:189], v[10:13]
	v_mfma_i32_16x16x64_i8 v[58:61], v[214:217], v[174:177], v[34:37]
	v_mfma_i32_16x16x64_i8 v[30:33], v[206:209], v[182:185], v[30:33]
	v_mfma_i32_16x16x64_i8 v[26:29], v[214:217], v[182:185], v[26:29]
	v_mfma_i32_16x16x64_i8 v[14:17], v[206:209], v[198:201], v[14:17]
	v_mfma_i32_16x16x64_i8 v[10:13], v[214:217], v[198:201], v[10:13]
	s_setprio 0
	s_add_i32 s77, s77, 2
	s_add_u32 s72, s72, 0x100
	s_addc_u32 s76, s76, 0
	s_cmp_gt_u32 s77, 13
	s_mov_b64 s[34:35], s[40:41]
	s_cbranch_scc1 .Lkdone_p1c
	s_barrier
	s_branch .LBB0_527
.Lkdone_p1c:
	s_cmpk_gt_u32 s31, 0xff
	s_cselect_b32 s101, 1, 0
	s_cbranch_scc1 .Lkepi_p1c
	s_barrier

; #define G_WAIT_V(n) asm volatile("s_waitcnt vmcnt(" #n ")" ::: "memory")
; #define G_BAR __builtin_amdgcn_s_barrier()
; template <int MODE  , class Epi, class Sched>
; __device__ __forceinline__ void gemm_phase(LAS unsigned char* lds, const GemmDesc g, const Sched& S, const Epi& E) {
;     ...
;     G_WAIT_V(0);
;     if (wr == 0) G_BAR;
;     G_BAR;
.LBB0_634:
	s_cmp_eq_u32 s101, 1
	s_cbranch_scc0 .Lnodx_p1c
	s_barrier
	s_mov_b32 s101, 0

; #define G_STAGE(bufoff, gbase, voff) do { _Pragma("unroll") for (int _i = 0; _i < 2; ++_i) \
;         __builtin_amdgcn_global_load_lds((const unsigned*)((const char*)(gbase) + (voff)[_i]), (LAS unsigned*)(lds + (bufoff) + ldsw + _i * 8192), 16, 0, 0); } while (0)
; #define G_WAIT_L(n) asm volatile("s_waitcnt lgkmcnt(" #n ")" ::: "memory")
; #define G_BAR __builtin_amdgcn_s_barrier()
; #define G_SCHED __builtin_amdgcn_sched_barrier(0)
; template <int MODE  , class Epi, class Sched>
; __device__ __forceinline__ void gemm_phase(LAS unsigned char* lds, const GemmDesc g, const Sched& S, const Epi& E) {
;     ...
;             G_LDB(B0, 0, 0); G_SCHED; G_LDA(At, 0, 0); G_STAGE(G_SA(1, 1), a1 + hstepA, voffA);
;             G_WAIT_L(8); G_BAR; G_WAIT_L(0); G_MMA(0, 0, At, B0); G_BAR; G_SCHED;
;             G_LDB(B1, 0, 1); G_STAGE(G_SB(0, 0), b2, voffB);
;             G_BAR; G_WAIT_L(0); G_MMA(0, 1, At, B1); G_BAR;
;     ...
;         if (zero) {
; #pragma unroll
;             for (int a = 0; a < 2; ++a)
; #pragma unroll
;                 for (int b = 0; b < 2; ++b)
; #pragma unroll
;                     for (int m = 0; m < 4; ++m)
; #pragma unroll
;                         for (int n = 0; n < 2; ++n) acc[a][b][m][n] = (f32x4){0.f, 0.f, 0.f, 0.f};
.LBB0_736:
	s_add_u32 s77, s46, 0x100
	v_mov_b32_e32 v18, 0
	s_addc_u32 s78, s47, 0
	s_mov_b32 s79, -2
	v_mov_b32_e32 v19, v18
	v_mov_b64_e32 v[20:21], v[18:19]
	v_mov_b64_e32 v[22:23], v[18:19]
	v_mov_b64_e32 v[24:25], v[18:19]
	v_mov_b64_e32 v[34:35], v[18:19]
	v_mov_b64_e32 v[36:37], v[18:19]
	v_mov_b64_e32 v[38:39], v[18:19]
	v_mov_b64_e32 v[40:41], v[18:19]
	v_mov_b64_e32 v[50:51], v[18:19]
	v_mov_b64_e32 v[52:53], v[18:19]
	v_mov_b64_e32 v[54:55], v[18:19]
	v_mov_b64_e32 v[56:57], v[18:19]
	v_mov_b64_e32 v[66:67], v[18:19]
	v_mov_b64_e32 v[68:69], v[18:19]
	v_mov_b64_e32 v[70:71], v[18:19]
	v_mov_b64_e32 v[72:73], v[18:19]
	v_mov_b64_e32 v[26:27], v[18:19]
	v_mov_b64_e32 v[28:29], v[18:19]
	v_mov_b64_e32 v[30:31], v[18:19]
	v_mov_b64_e32 v[32:33], v[18:19]
	v_mov_b64_e32 v[42:43], v[18:19]
	v_mov_b64_e32 v[44:45], v[18:19]
	v_mov_b64_e32 v[46:47], v[18:19]
	v_mov_b64_e32 v[48:49], v[18:19]
	v_mov_b64_e32 v[58:59], v[18:19]
	v_mov_b64_e32 v[60:61], v[18:19]
	v_mov_b64_e32 v[62:63], v[18:19]
	v_mov_b64_e32 v[64:65], v[18:19]
	v_mov_b64_e32 v[74:75], v[18:19]
	v_mov_b64_e32 v[76:77], v[18:19]
	v_mov_b64_e32 v[78:79], v[18:19]
	v_mov_b64_e32 v[80:81], v[18:19]
	v_mov_b64_e32 v[82:83], v[18:19]
	v_mov_b64_e32 v[84:85], v[18:19]
	v_mov_b64_e32 v[86:87], v[18:19]
	v_mov_b64_e32 v[88:89], v[18:19]
	v_mov_b64_e32 v[98:99], v[18:19]
	v_mov_b64_e32 v[100:101], v[18:19]
	v_mov_b64_e32 v[102:103], v[18:19]
	v_mov_b64_e32 v[104:105], v[18:19]
	v_mov_b64_e32 v[114:115], v[18:19]
	v_mov_b64_e32 v[116:117], v[18:19]
	v_mov_b64_e32 v[118:119], v[18:19]
	v_mov_b64_e32 v[120:121], v[18:19]
	v_mov_b64_e32 v[130:131], v[18:19]
	v_mov_b64_e32 v[132:133], v[18:19]
	v_mov_b64_e32 v[134:135], v[18:19]
	v_mov_b64_e32 v[136:137], v[18:19]
	v_mov_b64_e32 v[90:91], v[18:19]
	v_mov_b64_e32 v[92:93], v[18:19]
	v_mov_b64_e32 v[94:95], v[18:19]
	v_mov_b64_e32 v[96:97], v[18:19]
	v_mov_b64_e32 v[106:107], v[18:19]
	v_mov_b64_e32 v[108:109], v[18:19]
	v_mov_b64_e32 v[110:111], v[18:19]
	v_mov_b64_e32 v[112:113], v[18:19]
	v_mov_b64_e32 v[122:123], v[18:19]
	v_mov_b64_e32 v[124:125], v[18:19]
	v_mov_b64_e32 v[126:127], v[18:19]
	v_mov_b64_e32 v[128:129], v[18:19]
	v_mov_b64_e32 v[138:139], v[18:19]
	v_mov_b64_e32 v[140:141], v[18:19]
	v_mov_b64_e32 v[142:143], v[18:19]
	v_mov_b64_e32 v[144:145], v[18:19]
	s_cmp_eq_u32 s101, 1
	s_cbranch_scc0 .Lnodb_p1b
	s_barrier
	s_mov_b32 s101, 0
.Lnodb_p1b:
.LBB0_737:
	ds_read_b128 v[2:5], v168
	ds_read_b128 v[6:9], v168 offset:1024
	ds_read_b128 v[10:13], v168 offset:2048
	ds_read_b128 v[14:17], v168 offset:3072
	s_add_u32 s46, s50, 0x100
	s_addc_u32 s47, s51, 0
	s_cmp_eq_u32 s79, 12
	s_cselect_b32 s55, s45, s47
	s_cselect_b32 s54, s44, s46
	s_cselect_b32 s53, s3, s78
	s_cselect_b32 s52, s2, s77
	v_lshl_add_u64 v[158:159], s[50:51], 0, v[154:155]
	s_add_i32 m0, s62, 0xc000
	ds_read_b128 v[174:177], v169
	ds_read_b128 v[178:181], v169 offset:1024
	ds_read_b128 v[182:185], v169 offset:2048
	ds_read_b128 v[186:189], v169 offset:3072
	ds_read_b128 v[192:195], v169 offset:4096
	ds_read_b128 v[196:199], v169 offset:5120
	ds_read_b128 v[200:203], v169 offset:6144
	ds_read_b128 v[204:207], v169 offset:7168
	global_load_lds_dwordx4 v[158:159], off
	v_lshl_add_u64 v[158:159], s[50:51], 0, v[156:157]
	s_add_i32 m0, s62, 0xe000
	s_nop 0
	global_load_lds_dwordx4 v[158:159], off
	s_waitcnt lgkmcnt(8)
	s_barrier
	s_waitcnt lgkmcnt(0)
	s_setprio 1
	s_waitcnt lgkmcnt(0)
	v_mfma_scale_f32_16x16x128_f8f6f4 v[142:145], v[2:9], v[174:181], v[142:145], v170, v170 op_sel_hi:[0,0,0]
	v_mfma_scale_f32_16x16x128_f8f6f4 v[138:141], v[10:17], v[174:181], v[138:141], v170, v170 op_sel_hi:[0,0,0]
	v_mfma_scale_f32_16x16x128_f8f6f4 v[126:129], v[2:9], v[182:189], v[126:129], v170, v170 op_sel_hi:[0,0,0]
	v_mfma_scale_f32_16x16x128_f8f6f4 v[122:125], v[10:17], v[182:189], v[122:125], v170, v170 op_sel_hi:[0,0,0]
	v_mfma_scale_f32_16x16x128_f8f6f4 v[110:113], v[2:9], v[192:199], v[110:113], v170, v170 op_sel_hi:[0,0,0]
	v_mfma_scale_f32_16x16x128_f8f6f4 v[106:109], v[10:17], v[192:199], v[106:109], v170, v170 op_sel_hi:[0,0,0]
	v_mfma_scale_f32_16x16x128_f8f6f4 v[94:97], v[2:9], v[200:207], v[94:97], v170, v170 op_sel_hi:[0,0,0]
	v_mfma_scale_f32_16x16x128_f8f6f4 v[90:93], v[10:17], v[200:207], v[90:93], v170, v170 op_sel_hi:[0,0,0]
	s_setprio 0
	s_barrier
	s_add_i32 s0, s69, s60
	v_lshl_add_u64 v[158:159], s[52:53], 0, v[150:151]
	s_mov_b32 m0, s0
	ds_read_b128 v[208:211], v171
	ds_read_b128 v[212:215], v171 offset:1024
	ds_read_b128 v[216:219], v171 offset:2048
	ds_read_b128 v[220:223], v171 offset:3072
	global_load_lds_dwordx4 v[158:159], off
	v_lshl_add_u64 v[160:161], s[52:53], 0, v[146:147]
	s_add_i32 m0, s0, 0x2000
	s_nop 0
	global_load_lds_dwordx4 v[160:161], off
	s_barrier
	s_waitcnt lgkmcnt(0)
	s_setprio 1
	s_waitcnt lgkmcnt(0)
	v_mfma_scale_f32_16x16x128_f8f6f4 v[134:137], v[208:215], v[174:181], v[134:137], v170, v170 op_sel_hi:[0,0,0]
	v_mfma_scale_f32_16x16x128_f8f6f4 v[130:133], v[216:223], v[174:181], v[130:133], v170, v170 op_sel_hi:[0,0,0]
	v_mfma_scale_f32_16x16x128_f8f6f4 v[118:121], v[208:215], v[182:189], v[118:121], v170, v170 op_sel_hi:[0,0,0]
	v_mfma_scale_f32_16x16x128_f8f6f4 v[114:117], v[216:223], v[182:189], v[114:117], v170, v170 op_sel_hi:[0,0,0]
	v_mfma_scale_f32_16x16x128_f8f6f4 v[102:105], v[208:215], v[192:199], v[102:105], v170, v170 op_sel_hi:[0,0,0]
	v_mfma_scale_f32_16x16x128_f8f6f4 v[98:101], v[216:223], v[192:199], v[98:101], v170, v170 op_sel_hi:[0,0,0]
	v_mfma_scale_f32_16x16x128_f8f6f4 v[86:89], v[208:215], v[200:207], v[86:89], v170, v170 op_sel_hi:[0,0,0]
	v_mfma_scale_f32_16x16x128_f8f6f4 v[82:85], v[216:223], v[200:207], v[82:85], v170, v170 op_sel_hi:[0,0,0]
	s_setprio 0
	s_mov_b32 m0, s62
	v_lshl_add_u64 v[162:163], s[54:55], 0, v[152:153]
	s_barrier
; #define G_STAGE(bufoff, gbase, voff) do { _Pragma("unroll") for (int _i = 0; _i < 2; ++_i) \
;         __builtin_amdgcn_global_load_lds((const unsigned*)((const char*)(gbase) + (voff)[_i]), (LAS unsigned*)(lds + (bufoff) + ldsw + _i * 8192), 16, 0, 0); } while (0)
; #define G_WAIT_V(n) asm volatile("s_waitcnt vmcnt(" #n ")" ::: "memory")
; #define G_WAIT_L(n) asm volatile("s_waitcnt lgkmcnt(" #n ")" ::: "memory")
; #define G_BAR __builtin_amdgcn_s_barrier()
; #define G_SCHED __builtin_amdgcn_sched_barrier(0)
; template <int MODE  , class Epi, class Sched>
; __device__ __forceinline__ void gemm_phase(LAS unsigned char* lds, const GemmDesc g, const Sched& S, const Epi& E) {
;     ...
;             G_LDA(At, 0, 1); G_STAGE(G_SA(0, 0), a2, voffA);
;             G_BAR; G_WAIT_L(0); G_MMA(1, 0, At, B0); G_BAR; G_SCHED;
;             G_STAGE(G_SB(0, 1), b2 + hstepB, voffB);
;             G_WAIT_V(6); G_BAR; G_MMA(1, 1, At, B1); G_BAR;
;             G_LDB(B0, 1, 0); G_SCHED; G_LDA(At, 1, 0); G_STAGE(G_SA(0, 1), a2 + hstepA, voffA);
;             G_WAIT_L(8); G_BAR; G_WAIT_L(0); G_MMA(0, 0, At, B0); G_BAR; G_SCHED;
	ds_read_b128 v[174:177], v169 offset:16384
	ds_read_b128 v[178:181], v169 offset:17408
	ds_read_b128 v[182:185], v169 offset:18432
	ds_read_b128 v[186:189], v169 offset:19456
	ds_read_b128 v[192:195], v169 offset:20480
	ds_read_b128 v[196:199], v169 offset:21504
	ds_read_b128 v[200:203], v169 offset:22528
	ds_read_b128 v[204:207], v169 offset:23552
	global_load_lds_dwordx4 v[162:163], off
	v_lshl_add_u64 v[164:165], s[54:55], 0, v[148:149]
	s_mov_b32 m0, s63
	s_nop 0
	global_load_lds_dwordx4 v[164:165], off
	s_barrier
	s_waitcnt lgkmcnt(0)
	s_setprio 1
	s_waitcnt lgkmcnt(0)
	v_mfma_scale_f32_16x16x128_f8f6f4 v[78:81], v[2:9], v[174:181], v[78:81], v170, v170 op_sel_hi:[0,0,0]
	v_mfma_scale_f32_16x16x128_f8f6f4 v[74:77], v[10:17], v[174:181], v[74:77], v170, v170 op_sel_hi:[0,0,0]
	v_mfma_scale_f32_16x16x128_f8f6f4 v[62:65], v[2:9], v[182:189], v[62:65], v170, v170 op_sel_hi:[0,0,0]
	v_mfma_scale_f32_16x16x128_f8f6f4 v[58:61], v[10:17], v[182:189], v[58:61], v170, v170 op_sel_hi:[0,0,0]
	v_mfma_scale_f32_16x16x128_f8f6f4 v[46:49], v[2:9], v[192:199], v[46:49], v170, v170 op_sel_hi:[0,0,0]
	v_mfma_scale_f32_16x16x128_f8f6f4 v[42:45], v[10:17], v[192:199], v[42:45], v170, v170 op_sel_hi:[0,0,0]
	v_mfma_scale_f32_16x16x128_f8f6f4 v[30:33], v[2:9], v[200:207], v[30:33], v170, v170 op_sel_hi:[0,0,0]
	v_mfma_scale_f32_16x16x128_f8f6f4 v[26:29], v[10:17], v[200:207], v[26:29], v170, v170 op_sel_hi:[0,0,0]
	s_setprio 0
	s_barrier
	s_add_u32 s0, s52, 0x44000
	s_addc_u32 s1, s53, 0
	s_add_i32 s10, s70, s60
	v_lshl_add_u64 v[2:3], s[0:1], 0, v[150:151]
	s_mov_b32 m0, s10
	s_nop 0
	global_load_lds_dwordx4 v[2:3], off
	v_lshl_add_u64 v[2:3], s[0:1], 0, v[146:147]
	s_add_i32 m0, s10, 0x2000
	s_nop 0
	global_load_lds_dwordx4 v[2:3], off
	s_waitcnt vmcnt(6)
	s_barrier
	s_setprio 1
	v_mfma_scale_f32_16x16x128_f8f6f4 v[70:73], v[208:215], v[174:181], v[70:73], v170, v170 op_sel_hi:[0,0,0]
	v_mfma_scale_f32_16x16x128_f8f6f4 v[66:69], v[216:223], v[174:181], v[66:69], v170, v170 op_sel_hi:[0,0,0]
	v_mfma_scale_f32_16x16x128_f8f6f4 v[54:57], v[208:215], v[182:189], v[54:57], v170, v170 op_sel_hi:[0,0,0]
	v_mfma_scale_f32_16x16x128_f8f6f4 v[50:53], v[216:223], v[182:189], v[50:53], v170, v170 op_sel_hi:[0,0,0]
	v_mfma_scale_f32_16x16x128_f8f6f4 v[38:41], v[208:215], v[192:199], v[38:41], v170, v170 op_sel_hi:[0,0,0]
	v_mfma_scale_f32_16x16x128_f8f6f4 v[34:37], v[216:223], v[192:199], v[34:37], v170, v170 op_sel_hi:[0,0,0]
	v_mfma_scale_f32_16x16x128_f8f6f4 v[22:25], v[208:215], v[200:207], v[22:25], v170, v170 op_sel_hi:[0,0,0]
	v_mfma_scale_f32_16x16x128_f8f6f4 v[18:21], v[216:223], v[200:207], v[18:21], v170, v170 op_sel_hi:[0,0,0]
	s_setprio 0
	s_add_i32 s10, 0, 0x18000
	v_add_u32_e32 v14, s10, v166
	s_barrier
	ds_read_b128 v[2:5], v14
	ds_read_b128 v[6:9], v14 offset:1024
	ds_read_b128 v[10:13], v14 offset:2048
	ds_read_b128 v[14:17], v14 offset:3072
	s_add_u32 s0, s54, 0x44000
	s_addc_u32 s1, s55, 0
	s_mov_b32 m0, s64
	v_lshl_add_u64 v[208:209], s[0:1], 0, v[152:153]
	ds_read_b128 v[174:177], v169 offset:32768
	ds_read_b128 v[178:181], v169 offset:33792
	ds_read_b128 v[182:185], v169 offset:34816
	ds_read_b128 v[186:189], v169 offset:35840
	ds_read_b128 v[192:195], v169 offset:36864
	ds_read_b128 v[196:199], v169 offset:37888
	ds_read_b128 v[200:203], v169 offset:38912
	ds_read_b128 v[204:207], v169 offset:39936
	global_load_lds_dwordx4 v[208:209], off
	v_lshl_add_u64 v[208:209], s[0:1], 0, v[148:149]
	s_mov_b32 m0, s65
	s_nop 0
	global_load_lds_dwordx4 v[208:209], off
	s_waitcnt lgkmcnt(8)
	s_barrier
	s_waitcnt lgkmcnt(0)
	s_setprio 1
	s_waitcnt lgkmcnt(0)
	v_mfma_scale_f32_16x16x128_f8f6f4 v[142:145], v[2:9], v[174:181], v[142:145], v170, v170 op_sel_hi:[0,0,0]
	v_mfma_scale_f32_16x16x128_f8f6f4 v[138:141], v[10:17], v[174:181], v[138:141], v170, v170 op_sel_hi:[0,0,0]
	v_mfma_scale_f32_16x16x128_f8f6f4 v[126:129], v[2:9], v[182:189], v[126:129], v170, v170 op_sel_hi:[0,0,0]
	v_mfma_scale_f32_16x16x128_f8f6f4 v[122:125], v[10:17], v[182:189], v[122:125], v170, v170 op_sel_hi:[0,0,0]
	v_mfma_scale_f32_16x16x128_f8f6f4 v[110:113], v[2:9], v[192:199], v[110:113], v170, v170 op_sel_hi:[0,0,0]
	v_mfma_scale_f32_16x16x128_f8f6f4 v[106:109], v[10:17], v[192:199], v[106:109], v170, v170 op_sel_hi:[0,0,0]
	v_mfma_scale_f32_16x16x128_f8f6f4 v[94:97], v[2:9], v[200:207], v[94:97], v170, v170 op_sel_hi:[0,0,0]
	v_mfma_scale_f32_16x16x128_f8f6f4 v[90:93], v[10:17], v[200:207], v[90:93], v170, v170 op_sel_hi:[0,0,0]
	s_setprio 0
	s_barrier
; #define G_STAGE(bufoff, gbase, voff) do { _Pragma("unroll") for (int _i = 0; _i < 2; ++_i) \
;         __builtin_amdgcn_global_load_lds((const unsigned*)((const char*)(gbase) + (voff)[_i]), (LAS unsigned*)(lds + (bufoff) + ldsw + _i * 8192), 16, 0, 0); } while (0)
; #define G_WAIT_V(n) asm volatile("s_waitcnt vmcnt(" #n ")" ::: "memory")
; #define G_WAIT_L(n) asm volatile("s_waitcnt lgkmcnt(" #n ")" ::: "memory")
; #define G_BAR __builtin_amdgcn_s_barrier()
; #define G_SCHED __builtin_amdgcn_sched_barrier(0)
; template <int MODE  , class Epi, class Sched>
; __device__ __forceinline__ void gemm_phase(LAS unsigned char* lds, const GemmDesc g, const Sched& S, const Epi& E) {
;     ...
;             G_LDB(B1, 1, 1); G_STAGE(G_SB(1, 0), b3, voffB);
;             G_BAR; G_WAIT_L(0); G_MMA(0, 1, At, B1); G_BAR;
;             G_LDA(At, 1, 1); G_STAGE(G_SA(1, 0), a3, voffA);
;             G_BAR; G_WAIT_L(0); G_MMA(1, 0, At, B0); G_BAR; G_SCHED;
;             G_STAGE(G_SB(1, 1), b3 + hstepB, voffB);
;             G_WAIT_V(6); G_BAR; G_MMA(1, 1, At, B1); G_BAR;
	s_add_i32 s11, 0, 0x1c000
	s_add_i32 s0, s10, s60
	v_add_u32_e32 v173, s11, v166
	v_lshl_add_u64 v[158:159], v[158:159], 0, s[12:13]
	s_mov_b32 m0, s0
	ds_read_b128 v[208:211], v173
	ds_read_b128 v[212:215], v173 offset:1024
	ds_read_b128 v[216:219], v173 offset:2048
	ds_read_b128 v[220:223], v173 offset:3072
	global_load_lds_dwordx4 v[158:159], off
	v_lshl_add_u64 v[158:159], v[160:161], 0, s[12:13]
	s_add_i32 m0, s0, 0x2000
	s_nop 0
	global_load_lds_dwordx4 v[158:159], off
	s_barrier
	s_waitcnt lgkmcnt(0)
	s_setprio 1
	s_waitcnt lgkmcnt(0)
	v_mfma_scale_f32_16x16x128_f8f6f4 v[134:137], v[208:215], v[174:181], v[134:137], v170, v170 op_sel_hi:[0,0,0]
	v_mfma_scale_f32_16x16x128_f8f6f4 v[130:133], v[216:223], v[174:181], v[130:133], v170, v170 op_sel_hi:[0,0,0]
	v_mfma_scale_f32_16x16x128_f8f6f4 v[118:121], v[208:215], v[182:189], v[118:121], v170, v170 op_sel_hi:[0,0,0]
	v_mfma_scale_f32_16x16x128_f8f6f4 v[114:117], v[216:223], v[182:189], v[114:117], v170, v170 op_sel_hi:[0,0,0]
	v_mfma_scale_f32_16x16x128_f8f6f4 v[102:105], v[208:215], v[192:199], v[102:105], v170, v170 op_sel_hi:[0,0,0]
	v_mfma_scale_f32_16x16x128_f8f6f4 v[98:101], v[216:223], v[192:199], v[98:101], v170, v170 op_sel_hi:[0,0,0]
	v_mfma_scale_f32_16x16x128_f8f6f4 v[86:89], v[208:215], v[200:207], v[86:89], v170, v170 op_sel_hi:[0,0,0]
	v_mfma_scale_f32_16x16x128_f8f6f4 v[82:85], v[216:223], v[200:207], v[82:85], v170, v170 op_sel_hi:[0,0,0]
	s_setprio 0
	s_mov_b32 m0, s67
	v_lshl_add_u64 v[158:159], v[162:163], 0, s[12:13]
	s_barrier
	ds_read_b128 v[174:177], v169 offset:49152
	ds_read_b128 v[178:181], v169 offset:50176
	ds_read_b128 v[182:185], v169 offset:51200
	ds_read_b128 v[186:189], v169 offset:52224
	ds_read_b128 v[192:195], v169 offset:53248
	ds_read_b128 v[196:199], v169 offset:54272
	ds_read_b128 v[200:203], v169 offset:55296
	ds_read_b128 v[204:207], v169 offset:56320
	global_load_lds_dwordx4 v[158:159], off
	v_lshl_add_u64 v[158:159], v[164:165], 0, s[12:13]
	s_mov_b32 m0, s68
	s_nop 0
	global_load_lds_dwordx4 v[158:159], off
	s_barrier
	s_waitcnt lgkmcnt(0)
	s_setprio 1
	s_waitcnt lgkmcnt(0)
	v_mfma_scale_f32_16x16x128_f8f6f4 v[78:81], v[2:9], v[174:181], v[78:81], v170, v170 op_sel_hi:[0,0,0]
	v_mfma_scale_f32_16x16x128_f8f6f4 v[74:77], v[10:17], v[174:181], v[74:77], v170, v170 op_sel_hi:[0,0,0]
	v_mfma_scale_f32_16x16x128_f8f6f4 v[62:65], v[2:9], v[182:189], v[62:65], v170, v170 op_sel_hi:[0,0,0]
	v_mfma_scale_f32_16x16x128_f8f6f4 v[58:61], v[10:17], v[182:189], v[58:61], v170, v170 op_sel_hi:[0,0,0]
	v_mfma_scale_f32_16x16x128_f8f6f4 v[46:49], v[2:9], v[192:199], v[46:49], v170, v170 op_sel_hi:[0,0,0]
	v_mfma_scale_f32_16x16x128_f8f6f4 v[42:45], v[10:17], v[192:199], v[42:45], v170, v170 op_sel_hi:[0,0,0]
	v_mfma_scale_f32_16x16x128_f8f6f4 v[30:33], v[2:9], v[200:207], v[30:33], v170, v170 op_sel_hi:[0,0,0]
	v_mfma_scale_f32_16x16x128_f8f6f4 v[26:29], v[10:17], v[200:207], v[26:29], v170, v170 op_sel_hi:[0,0,0]
	s_setprio 0
	s_barrier
	s_add_u32 s0, s52, 0x44080
	s_addc_u32 s1, s53, 0
	s_add_i32 s10, s11, s60
	v_lshl_add_u64 v[2:3], s[0:1], 0, v[150:151]
	s_mov_b32 m0, s10
	s_nop 0
	global_load_lds_dwordx4 v[2:3], off
	v_lshl_add_u64 v[2:3], s[0:1], 0, v[146:147]
	s_add_i32 m0, s10, 0x2000
	s_nop 0
	global_load_lds_dwordx4 v[2:3], off
	s_waitcnt vmcnt(6)
	s_barrier
	s_setprio 1
	v_mfma_scale_f32_16x16x128_f8f6f4 v[70:73], v[208:215], v[174:181], v[70:73], v170, v170 op_sel_hi:[0,0,0]
	v_mfma_scale_f32_16x16x128_f8f6f4 v[66:69], v[216:223], v[174:181], v[66:69], v170, v170 op_sel_hi:[0,0,0]
	v_mfma_scale_f32_16x16x128_f8f6f4 v[54:57], v[208:215], v[182:189], v[54:57], v170, v170 op_sel_hi:[0,0,0]
	v_mfma_scale_f32_16x16x128_f8f6f4 v[50:53], v[216:223], v[182:189], v[50:53], v170, v170 op_sel_hi:[0,0,0]
	v_mfma_scale_f32_16x16x128_f8f6f4 v[38:41], v[208:215], v[192:199], v[38:41], v170, v170 op_sel_hi:[0,0,0]
	v_mfma_scale_f32_16x16x128_f8f6f4 v[34:37], v[216:223], v[192:199], v[34:37], v170, v170 op_sel_hi:[0,0,0]
	v_mfma_scale_f32_16x16x128_f8f6f4 v[22:25], v[208:215], v[200:207], v[22:25], v170, v170 op_sel_hi:[0,0,0]
	v_mfma_scale_f32_16x16x128_f8f6f4 v[18:21], v[216:223], v[200:207], v[18:21], v170, v170 op_sel_hi:[0,0,0]
	s_setprio 0
	s_add_i32 s79, s79, 2
	s_add_u32 s77, s77, 0x100
	s_addc_u32 s78, s78, 0
	s_cmp_gt_u32 s79, 13
	s_mov_b64 s[50:51], s[46:47]
	s_cbranch_scc1 .Lkdone_p1b
	s_barrier
	s_branch .LBB0_737

; __device__ __forceinline__ unsigned pk_bf16(float lo, float hi) { const f32x2_t v = {lo, hi}; return __builtin_bit_cast(unsigned, __builtin_convertvector(v, bf16x2_t)); }
;     __device__ __forceinline__ bool operator()(f32x4 (&acc)[2][2][4][2], const Unit& u, int wr, int wc, int fr, int fq) const {
;         const int pn = u.pn, r0 = u.pm * BM + wr * 64 + fr, cl = wc * 32 + fq * 8;
;         {
;             const int ch0 = (pn - 24) * 128 + cl;
;             const f32x4 ba0 = *(const f32x4*)(bgate + ch0), ba1 = *(const f32x4*)(bgate + ch0 + 4), bb0 = *(const f32x4*)(bgate + D + ch0), bb1 = *(const f32x4*)(bgate + D + ch0 + 4);
; #pragma unroll
;             for (int ai = 0; ai < 2; ++ai)
; #pragma unroll
;                 for (int m = 0; m < 4; ++m) { const int row = r0 + ai * HALF + m * 16;
;                     const f32x4 a0 = acc[ai][0][m][0] * gsc + ba0, a1 = acc[ai][0][m][1] * gsc + ba1, b0 = acc[ai][1][m][0] * gsc + bb0, b1 = acc[ai][1][m][1] * gsc + bb1;
;                     f32x4 r0v, r1v, s0v, s1v;
; #pragma unroll
;                     for (int j = 0; j < 4; ++j) {
;                         const float ea0 = __builtin_amdgcn_exp2f(-1.44269504f * fminf(fmaxf(a0[j], -40.f), 40.f)), eb0 = __builtin_amdgcn_exp2f(-1.44269504f * fminf(fmaxf(b0[j], -40.f), 40.f));
;                         const float ea1 = __builtin_amdgcn_exp2f(-1.44269504f * fminf(fmaxf(a1[j], -40.f), 40.f)), eb1 = __builtin_amdgcn_exp2f(-1.44269504f * fminf(fmaxf(b1[j], -40.f), 40.f));
;                         s0v[j] = __builtin_amdgcn_rcpf(1.0f + eb0); s1v[j] = __builtin_amdgcn_rcpf(1.0f + eb1);
;                         r0v[j] = (1.0f + eb0) * __builtin_amdgcn_rcpf(1.0f + ea0); r1v[j] = (1.0f + eb1) * __builtin_amdgcn_rcpf(1.0f + ea1); }
;                     u32x4 w; w.x = pk_bf16(r0v[0], r0v[1]); w.y = pk_bf16(r0v[2], r0v[3]); w.z = pk_bf16(r1v[0], r1v[1]); w.w = pk_bf16(r1v[2], r1v[3]);
;                     *(u32x4*)(SGR + (size_t)row * D + ch0) = w;
;                     w.x = pk_bf16(s0v[0], s0v[1]); w.y = pk_bf16(s0v[2], s0v[3]); w.z = pk_bf16(s1v[0], s1v[1]); w.w = pk_bf16(s1v[2], s1v[3]);
;                     *(u32x4*)(SGB + (size_t)row * D + ch0) = w; }
.Lkepi_p1b:
	v_lshl_add_u32 v160, s76, 7, v167
	v_ashrrev_i32_e32 v161, 31, v160
	v_lshlrev_b64 v[2:3], 2, v[160:161]
	s_nop 15
	s_nop 15
	v_lshl_add_u64 v[4:5], s[48:49], 0, v[2:3]
	global_load_dwordx4 v[14:17], v[4:5], off
	v_lshl_add_u64 v[2:3], s[16:17], 0, v[2:3]
	global_load_dwordx4 v[10:13], v[2:3], off
	global_load_dwordx4 v[6:9], v[4:5], off offset:16
	s_nop 0
	global_load_dwordx4 v[2:5], v[2:3], off offset:16
	v_lshl_add_u32 v158, s75, 8, v1
	s_and_b64 vcc, exec, s[42:43]
	s_mov_b32 s76, s73
	s_mov_b32 s75, s72
	s_mov_b64 s[46:47], s[2:3]
	s_mov_b64 s[50:51], s[44:45]
	s_waitcnt vmcnt(0)
	v_fmamk_f32 v134, v134, 0x3c800000, v10
	v_fmamk_f32 v142, v142, 0x3c800000, v14
	v_fmamk_f32 v138, v138, 0x3c800000, v6
	v_fmamk_f32 v143, v143, 0x3c800000, v15
	v_fmamk_f32 v144, v144, 0x3c800000, v16
	v_fmamk_f32 v145, v145, 0x3c800000, v17
	v_fmamk_f32 v139, v139, 0x3c800000, v7
	v_fmamk_f32 v140, v140, 0x3c800000, v8
	v_med3_f32 v142, v142, s71, v172
	v_med3_f32 v138, v138, s71, v172
	v_med3_f32 v143, v143, s71, v172
	v_med3_f32 v144, v144, s71, v172
	v_med3_f32 v145, v145, s71, v172
	v_med3_f32 v139, v139, s71, v172
	v_med3_f32 v140, v140, s71, v172
	v_mul_f32_e32 v142, 0xbfb8aa3b, v142
	v_mul_f32_e32 v138, 0xbfb8aa3b, v138
	v_mul_f32_e32 v143, 0xbfb8aa3b, v143
	v_mul_f32_e32 v144, 0xbfb8aa3b, v144
	v_mul_f32_e32 v145, 0xbfb8aa3b, v145
	v_mul_f32_e32 v139, 0xbfb8aa3b, v139
	v_mul_f32_e32 v140, 0xbfb8aa3b, v140
	v_exp_f32_e32 v142, v142
	v_exp_f32_e32 v138, v138
	v_exp_f32_e32 v143, v143
	v_exp_f32_e32 v144, v144
	v_exp_f32_e32 v145, v145
	v_fmamk_f32 v130, v130, 0x3c800000, v2
	v_fmamk_f32 v135, v135, 0x3c800000, v11
	v_fmamk_f32 v136, v136, 0x3c800000, v12
	v_fmamk_f32 v137, v137, 0x3c800000, v13
	v_fmamk_f32 v141, v141, 0x3c800000, v9
	v_exp_f32_e32 v139, v139
	v_exp_f32_e32 v140, v140
	v_fmamk_f32 v131, v131, 0x3c800000, v3
	v_fmamk_f32 v132, v132, 0x3c800000, v4
	v_med3_f32 v134, v134, s71, v172
	v_med3_f32 v130, v130, s71, v172
	v_med3_f32 v135, v135, s71, v172
	v_med3_f32 v136, v136, s71, v172
	v_med3_f32 v137, v137, s71, v172
	v_med3_f32 v141, v141, s71, v172
	v_fmamk_f32 v133, v133, 0x3c800000, v5
	v_med3_f32 v131, v131, s71, v172
	v_med3_f32 v132, v132, s71, v172
	v_mul_f32_e32 v134, 0xbfb8aa3b, v134
	v_mul_f32_e32 v159, 0xbfb8aa3b, v130
	v_mul_f32_e32 v135, 0xbfb8aa3b, v135
	v_mul_f32_e32 v136, 0xbfb8aa3b, v136
	v_mul_f32_e32 v137, 0xbfb8aa3b, v137
	v_mul_f32_e32 v141, 0xbfb8aa3b, v141
	v_med3_f32 v133, v133, s71, v172
	v_mul_f32_e32 v162, 0xbfb8aa3b, v131
	v_mul_f32_e32 v163, 0xbfb8aa3b, v132
	v_exp_f32_e32 v130, v134
	v_exp_f32_e32 v132, v159
	v_exp_f32_e32 v131, v135
	v_exp_f32_e32 v134, v136
	v_exp_f32_e32 v135, v137
	v_exp_f32_e32 v159, v141
	v_add_f32_e32 v141, 1.0, v142
	v_add_f32_e32 v142, 1.0, v138
	v_add_f32_e32 v143, 1.0, v143
	v_add_f32_e32 v144, 1.0, v144
	v_add_f32_e32 v145, 1.0, v145
	v_mul_f32_e32 v164, 0xbfb8aa3b, v133
	v_exp_f32_e32 v133, v162
	v_exp_f32_e32 v136, v163
	v_add_f32_e32 v162, 1.0, v139
	v_add_f32_e32 v163, 1.0, v140
	v_rcp_f32_e32 v138, v141
	v_rcp_f32_e32 v140, v142
	v_rcp_f32_e32 v139, v143
	v_rcp_f32_e32 v142, v144
	v_rcp_f32_e32 v143, v145
	v_pk_add_f32 v[130:131], v[130:131], 1.0 op_sel_hi:[1,0]
	v_pk_add_f32 v[134:135], v[134:135], 1.0 op_sel_hi:[1,0]
	v_exp_f32_e32 v137, v164
	v_rcp_f32_e32 v164, v130
	v_rcp_f32_e32 v165, v131
	v_rcp_f32_e32 v141, v162
	v_rcp_f32_e32 v144, v163
	v_pk_mul_f32 v[130:131], v[138:139], v[130:131]
	v_rcp_f32_e32 v163, v134
	v_pk_mul_f32 v[138:139], v[142:143], v[134:135]
	v_add_f32_e32 v134, 1.0, v159
	v_rcp_f32_e32 v145, v134
	v_pk_add_f32 v[132:133], v[132:133], 1.0 op_sel_hi:[1,0]
	v_rcp_f32_e32 v142, v135
	v_rcp_f32_e32 v162, v132
	v_rcp_f32_e32 v173, v133
	v_pk_mul_f32 v[132:133], v[140:141], v[132:133]
	v_pk_add_f32 v[134:135], v[136:137], 1.0 op_sel_hi:[1,0]
	v_ashrrev_i32_e32 v159, 31, v158
	v_rcp_f32_e32 v143, v134
	v_pk_mul_f32 v[140:141], v[144:145], v[134:135]
	v_rcp_f32_e32 v144, v135
	v_cvt_pk_bf16_f32 v136, v132, v133
	v_lshlrev_b64 v[132:133], 12, v[158:159]
	v_cvt_pk_bf16_f32 v134, v130, v131
	v_cvt_pk_bf16_f32 v135, v138, v139
	v_lshl_add_u64 v[138:139], s[4:5], 0, v[132:133]
	v_lshlrev_b64 v[130:131], 1, v[160:161]
	v_cvt_pk_bf16_f32 v137, v140, v141
	v_lshl_add_u64 v[138:139], v[138:139], 0, v[130:131]
	v_fmamk_f32 v126, v126, 0x3c800000, v14
	v_fmamk_f32 v122, v122, 0x3c800000, v6
	v_fmamk_f32 v127, v127, 0x3c800000, v15
	global_store_dwordx4 v[138:139], v[134:137], off
	v_lshl_add_u64 v[138:139], s[14:15], 0, v[132:133]
	v_med3_f32 v126, v126, s71, v172
	v_med3_f32 v122, v122, s71, v172
	v_med3_f32 v127, v127, s71, v172
	v_cvt_pk_bf16_f32 v134, v164, v165
	v_cvt_pk_bf16_f32 v135, v163, v142
	v_cvt_pk_bf16_f32 v136, v162, v173
	v_cvt_pk_bf16_f32 v137, v143, v144
	v_lshl_add_u64 v[138:139], v[138:139], 0, v[130:131]
	v_mul_f32_e32 v126, 0xbfb8aa3b, v126
	v_mul_f32_e32 v122, 0xbfb8aa3b, v122
	v_mul_f32_e32 v127, 0xbfb8aa3b, v127
	global_store_dwordx4 v[138:139], v[134:137], off
	v_exp_f32_e32 v126, v126
	v_exp_f32_e32 v127, v127
	v_exp_f32_e32 v134, v122
	v_fmamk_f32 v118, v118, 0x3c800000, v10
	v_fmamk_f32 v119, v119, 0x3c800000, v11
	v_fmamk_f32 v123, v123, 0x3c800000, v7
	v_med3_f32 v118, v118, s71, v172
	v_med3_f32 v119, v119, s71, v172
	v_med3_f32 v123, v123, s71, v172
	v_mul_f32_e32 v118, 0xbfb8aa3b, v118
	v_mul_f32_e32 v119, 0xbfb8aa3b, v119
	v_mul_f32_e32 v123, 0xbfb8aa3b, v123
	v_exp_f32_e32 v118, v118
	v_add_f32_e32 v122, 1.0, v126
	v_add_f32_e32 v126, 1.0, v134
	v_exp_f32_e32 v119, v119
	v_exp_f32_e32 v134, v123
	v_add_f32_e32 v123, 1.0, v127
	v_rcp_f32_e32 v122, v122
	v_rcp_f32_e32 v123, v123
	v_fmamk_f32 v114, v114, 0x3c800000, v2
; __device__ __forceinline__ unsigned pk_bf16(float lo, float hi) { const f32x2_t v = {lo, hi}; return __builtin_bit_cast(unsigned, __builtin_convertvector(v, bf16x2_t)); }
;     __device__ __forceinline__ bool operator()(f32x4 (&acc)[2][2][4][2], const Unit& u, int wr, int wc, int fr, int fq) const {
;     ...
;                 for (int m = 0; m < 4; ++m) { const int row = r0 + ai * HALF + m * 16;
;                     const f32x4 a0 = acc[ai][0][m][0] * gsc + ba0, a1 = acc[ai][0][m][1] * gsc + ba1, b0 = acc[ai][1][m][0] * gsc + bb0, b1 = acc[ai][1][m][1] * gsc + bb1;
;                     f32x4 r0v, r1v, s0v, s1v;
; #pragma unroll
;                     for (int j = 0; j < 4; ++j) {
;                         const float ea0 = __builtin_amdgcn_exp2f(-1.44269504f * fminf(fmaxf(a0[j], -40.f), 40.f)), eb0 = __builtin_amdgcn_exp2f(-1.44269504f * fminf(fmaxf(b0[j], -40.f), 40.f));
;                         const float ea1 = __builtin_amdgcn_exp2f(-1.44269504f * fminf(fmaxf(a1[j], -40.f), 40.f)), eb1 = __builtin_amdgcn_exp2f(-1.44269504f * fminf(fmaxf(b1[j], -40.f), 40.f));
;                         s0v[j] = __builtin_amdgcn_rcpf(1.0f + eb0); s1v[j] = __builtin_amdgcn_rcpf(1.0f + eb1);
;                         r0v[j] = (1.0f + eb0) * __builtin_amdgcn_rcpf(1.0f + ea0); r1v[j] = (1.0f + eb1) * __builtin_amdgcn_rcpf(1.0f + ea1); }
;                     u32x4 w; w.x = pk_bf16(r0v[0], r0v[1]); w.y = pk_bf16(r0v[2], r0v[3]); w.z = pk_bf16(r1v[0], r1v[1]); w.w = pk_bf16(r1v[2], r1v[3]);
;                     *(u32x4*)(SGR + (size_t)row * D + ch0) = w;
;                     w.x = pk_bf16(s0v[0], s0v[1]); w.y = pk_bf16(s0v[2], s0v[3]); w.z = pk_bf16(s1v[0], s1v[1]); w.w = pk_bf16(s1v[2], s1v[3]);
;                     *(u32x4*)(SGB + (size_t)row * D + ch0) = w; }
	v_fmamk_f32 v115, v115, 0x3c800000, v3
	v_med3_f32 v114, v114, s71, v172
	v_med3_f32 v115, v115, s71, v172
	v_mul_f32_e32 v114, 0xbfb8aa3b, v114
	v_mul_f32_e32 v115, 0xbfb8aa3b, v115
	v_pk_add_f32 v[118:119], v[118:119], 1.0 op_sel_hi:[1,0]
	v_exp_f32_e32 v114, v114
	v_exp_f32_e32 v115, v115
	v_rcp_f32_e32 v135, v118
	v_pk_mul_f32 v[122:123], v[122:123], v[118:119]
	v_add_f32_e32 v118, 1.0, v134
	v_rcp_f32_e32 v126, v126
	v_rcp_f32_e32 v127, v118
	v_pk_add_f32 v[114:115], v[114:115], 1.0 op_sel_hi:[1,0]
	v_rcp_f32_e32 v134, v119
	v_rcp_f32_e32 v136, v114
	v_pk_mul_f32 v[118:119], v[126:127], v[114:115]
	v_fmamk_f32 v114, v128, 0x3c800000, v16
	v_med3_f32 v114, v114, s71, v172
	v_mul_f32_e32 v114, 0xbfb8aa3b, v114
	v_rcp_f32_e32 v137, v115
	v_exp_f32_e32 v115, v114
	v_fmamk_f32 v114, v120, 0x3c800000, v12
	v_fmamk_f32 v120, v124, 0x3c800000, v8
	v_med3_f32 v120, v120, s71, v172
	v_mul_f32_e32 v120, 0xbfb8aa3b, v120
	v_exp_f32_e32 v124, v120
	v_add_f32_e32 v115, 1.0, v115
	v_rcp_f32_e32 v120, v115
	v_med3_f32 v114, v114, s71, v172
	v_add_f32_e32 v115, 1.0, v124
	v_rcp_f32_e32 v124, v115
	v_fmamk_f32 v115, v129, 0x3c800000, v17
	v_med3_f32 v115, v115, s71, v172
	v_mul_f32_e32 v115, 0xbfb8aa3b, v115
	v_exp_f32_e32 v126, v115
	v_fmamk_f32 v115, v121, 0x3c800000, v13
	v_fmamk_f32 v121, v125, 0x3c800000, v9
	v_med3_f32 v115, v115, s71, v172
	v_med3_f32 v121, v121, s71, v172
	v_mul_f32_e32 v114, 0xbfb8aa3b, v114
	v_mul_f32_e32 v115, 0xbfb8aa3b, v115
	v_mul_f32_e32 v121, 0xbfb8aa3b, v121
	v_exp_f32_e32 v114, v114
	v_fmamk_f32 v116, v116, 0x3c800000, v4
	v_exp_f32_e32 v115, v115
	v_exp_f32_e32 v125, v121
	v_fmamk_f32 v117, v117, 0x3c800000, v5
	v_add_f32_e32 v121, 1.0, v126
	v_med3_f32 v116, v116, s71, v172
	v_med3_f32 v117, v117, s71, v172
	v_rcp_f32_e32 v121, v121
	v_mul_f32_e32 v116, 0xbfb8aa3b, v116
	v_mul_f32_e32 v117, 0xbfb8aa3b, v117
	v_exp_f32_e32 v116, v116
	v_exp_f32_e32 v117, v117
	v_pk_add_f32 v[114:115], v[114:115], 1.0 op_sel_hi:[1,0]
	v_or_b32_e32 v126, 16, v158
	v_rcp_f32_e32 v128, v114
	v_pk_mul_f32 v[120:121], v[120:121], v[114:115]
	v_add_f32_e32 v114, 1.0, v125
	v_rcp_f32_e32 v125, v114
	v_rcp_f32_e32 v129, v115
	v_pk_add_f32 v[114:115], v[116:117], 1.0 op_sel_hi:[1,0]
	v_ashrrev_i32_e32 v127, 31, v126
	v_rcp_f32_e32 v138, v114
	v_rcp_f32_e32 v139, v115
	v_cvt_pk_bf16_f32 v116, v118, v119
	v_lshlrev_b64 v[118:119], 12, v[126:127]
	v_pk_mul_f32 v[124:125], v[124:125], v[114:115]
	v_cvt_pk_bf16_f32 v115, v120, v121
	v_lshl_add_u64 v[120:121], s[4:5], 0, v[118:119]
	v_fmamk_f32 v110, v110, 0x3c800000, v14
	v_fmamk_f32 v106, v106, 0x3c800000, v6
	v_fmamk_f32 v111, v111, 0x3c800000, v15
	v_cvt_pk_bf16_f32 v114, v122, v123
	v_cvt_pk_bf16_f32 v117, v124, v125
	v_lshl_add_u64 v[120:121], v[120:121], 0, v[130:131]
	v_lshl_add_u64 v[118:119], s[14:15], 0, v[118:119]
	v_med3_f32 v110, v110, s71, v172
	v_med3_f32 v106, v106, s71, v172
	v_med3_f32 v111, v111, s71, v172
	global_store_dwordx4 v[120:121], v[114:117], off
	v_lshl_add_u64 v[118:119], v[118:119], 0, v[130:131]
	v_mul_f32_e32 v110, 0xbfb8aa3b, v110
	v_cvt_pk_bf16_f32 v114, v135, v134
	v_cvt_pk_bf16_f32 v115, v128, v129
	v_cvt_pk_bf16_f32 v116, v136, v137
	v_cvt_pk_bf16_f32 v117, v138, v139
	v_mul_f32_e32 v106, 0xbfb8aa3b, v106
	v_mul_f32_e32 v111, 0xbfb8aa3b, v111
	global_store_dwordx4 v[118:119], v[114:117], off
	v_exp_f32_e32 v110, v110
	v_exp_f32_e32 v111, v111
	v_exp_f32_e32 v114, v106
	v_fmamk_f32 v102, v102, 0x3c800000, v10
	v_fmamk_f32 v103, v103, 0x3c800000, v11
	v_fmamk_f32 v107, v107, 0x3c800000, v7
	v_med3_f32 v102, v102, s71, v172
	v_med3_f32 v103, v103, s71, v172
	v_med3_f32 v107, v107, s71, v172
	v_mul_f32_e32 v102, 0xbfb8aa3b, v102
	v_mul_f32_e32 v103, 0xbfb8aa3b, v103
	v_mul_f32_e32 v107, 0xbfb8aa3b, v107
	v_exp_f32_e32 v102, v102
	v_add_f32_e32 v106, 1.0, v110
	v_add_f32_e32 v110, 1.0, v114
	v_exp_f32_e32 v103, v103
	v_exp_f32_e32 v114, v107
	v_add_f32_e32 v107, 1.0, v111
	v_rcp_f32_e32 v106, v106
	v_rcp_f32_e32 v107, v107
	v_fmamk_f32 v98, v98, 0x3c800000, v2
	v_fmamk_f32 v99, v99, 0x3c800000, v3
	v_med3_f32 v98, v98, s71, v172
	v_med3_f32 v99, v99, s71, v172
	v_mul_f32_e32 v98, 0xbfb8aa3b, v98
	v_mul_f32_e32 v99, 0xbfb8aa3b, v99
	v_pk_add_f32 v[102:103], v[102:103], 1.0 op_sel_hi:[1,0]
	v_exp_f32_e32 v98, v98
	v_exp_f32_e32 v99, v99
	v_rcp_f32_e32 v115, v102
	v_pk_mul_f32 v[106:107], v[106:107], v[102:103]
	v_add_f32_e32 v102, 1.0, v114
	v_rcp_f32_e32 v110, v110
	v_rcp_f32_e32 v111, v102
	v_pk_add_f32 v[98:99], v[98:99], 1.0 op_sel_hi:[1,0]
	v_rcp_f32_e32 v114, v103
	v_rcp_f32_e32 v116, v98
	v_pk_mul_f32 v[102:103], v[110:111], v[98:99]
	v_fmamk_f32 v98, v112, 0x3c800000, v16
	v_med3_f32 v98, v98, s71, v172
	v_mul_f32_e32 v98, 0xbfb8aa3b, v98
	v_rcp_f32_e32 v117, v99
	v_exp_f32_e32 v99, v98
	v_fmamk_f32 v98, v104, 0x3c800000, v12
	v_fmamk_f32 v104, v108, 0x3c800000, v8
	v_med3_f32 v104, v104, s71, v172
	v_mul_f32_e32 v104, 0xbfb8aa3b, v104
	v_exp_f32_e32 v108, v104
	v_add_f32_e32 v99, 1.0, v99
	v_rcp_f32_e32 v104, v99
	v_med3_f32 v98, v98, s71, v172
	v_add_f32_e32 v99, 1.0, v108
	v_rcp_f32_e32 v108, v99
	v_fmamk_f32 v99, v113, 0x3c800000, v17
	v_med3_f32 v99, v99, s71, v172
	v_mul_f32_e32 v99, 0xbfb8aa3b, v99
	v_exp_f32_e32 v110, v99
	v_fmamk_f32 v99, v105, 0x3c800000, v13
	v_fmamk_f32 v105, v109, 0x3c800000, v9
	v_med3_f32 v99, v99, s71, v172
	v_med3_f32 v105, v105, s71, v172
	v_mul_f32_e32 v98, 0xbfb8aa3b, v98
	v_mul_f32_e32 v99, 0xbfb8aa3b, v99
	v_mul_f32_e32 v105, 0xbfb8aa3b, v105
	v_exp_f32_e32 v98, v98
	v_fmamk_f32 v100, v100, 0x3c800000, v4
	v_exp_f32_e32 v99, v99
	v_exp_f32_e32 v109, v105
	v_fmamk_f32 v101, v101, 0x3c800000, v5
	v_add_f32_e32 v105, 1.0, v110
; __device__ __forceinline__ unsigned pk_bf16(float lo, float hi) { const f32x2_t v = {lo, hi}; return __builtin_bit_cast(unsigned, __builtin_convertvector(v, bf16x2_t)); }
;     __device__ __forceinline__ bool operator()(f32x4 (&acc)[2][2][4][2], const Unit& u, int wr, int wc, int fr, int fq) const {
;     ...
;                 for (int m = 0; m < 4; ++m) { const int row = r0 + ai * HALF + m * 16;
;                     const f32x4 a0 = acc[ai][0][m][0] * gsc + ba0, a1 = acc[ai][0][m][1] * gsc + ba1, b0 = acc[ai][1][m][0] * gsc + bb0, b1 = acc[ai][1][m][1] * gsc + bb1;
;                     f32x4 r0v, r1v, s0v, s1v;
; #pragma unroll
;                     for (int j = 0; j < 4; ++j) {
;                         const float ea0 = __builtin_amdgcn_exp2f(-1.44269504f * fminf(fmaxf(a0[j], -40.f), 40.f)), eb0 = __builtin_amdgcn_exp2f(-1.44269504f * fminf(fmaxf(b0[j], -40.f), 40.f));
;                         const float ea1 = __builtin_amdgcn_exp2f(-1.44269504f * fminf(fmaxf(a1[j], -40.f), 40.f)), eb1 = __builtin_amdgcn_exp2f(-1.44269504f * fminf(fmaxf(b1[j], -40.f), 40.f));
;                         s0v[j] = __builtin_amdgcn_rcpf(1.0f + eb0); s1v[j] = __builtin_amdgcn_rcpf(1.0f + eb1);
;                         r0v[j] = (1.0f + eb0) * __builtin_amdgcn_rcpf(1.0f + ea0); r1v[j] = (1.0f + eb1) * __builtin_amdgcn_rcpf(1.0f + ea1); }
;                     u32x4 w; w.x = pk_bf16(r0v[0], r0v[1]); w.y = pk_bf16(r0v[2], r0v[3]); w.z = pk_bf16(r1v[0], r1v[1]); w.w = pk_bf16(r1v[2], r1v[3]);
;                     *(u32x4*)(SGR + (size_t)row * D + ch0) = w;
;                     w.x = pk_bf16(s0v[0], s0v[1]); w.y = pk_bf16(s0v[2], s0v[3]); w.z = pk_bf16(s1v[0], s1v[1]); w.w = pk_bf16(s1v[2], s1v[3]);
;                     *(u32x4*)(SGB + (size_t)row * D + ch0) = w; }
	v_med3_f32 v100, v100, s71, v172
	v_med3_f32 v101, v101, s71, v172
	v_rcp_f32_e32 v105, v105
	v_mul_f32_e32 v100, 0xbfb8aa3b, v100
	v_mul_f32_e32 v101, 0xbfb8aa3b, v101
	v_exp_f32_e32 v100, v100
	v_exp_f32_e32 v101, v101
	v_pk_add_f32 v[98:99], v[98:99], 1.0 op_sel_hi:[1,0]
	v_or_b32_e32 v110, 32, v158
	v_rcp_f32_e32 v112, v98
	v_pk_mul_f32 v[104:105], v[104:105], v[98:99]
	v_add_f32_e32 v98, 1.0, v109
	v_rcp_f32_e32 v109, v98
	v_rcp_f32_e32 v113, v99
	v_pk_add_f32 v[98:99], v[100:101], 1.0 op_sel_hi:[1,0]
	v_ashrrev_i32_e32 v111, 31, v110
	v_rcp_f32_e32 v118, v98
	v_rcp_f32_e32 v119, v99
	v_cvt_pk_bf16_f32 v100, v102, v103
	v_lshlrev_b64 v[102:103], 12, v[110:111]
	v_pk_mul_f32 v[108:109], v[108:109], v[98:99]
	v_cvt_pk_bf16_f32 v99, v104, v105
	v_lshl_add_u64 v[104:105], s[4:5], 0, v[102:103]
	v_fmamk_f32 v94, v94, 0x3c800000, v14
	v_fmamk_f32 v90, v90, 0x3c800000, v6
	v_fmamk_f32 v95, v95, 0x3c800000, v15
	v_cvt_pk_bf16_f32 v98, v106, v107
	v_cvt_pk_bf16_f32 v101, v108, v109
	v_lshl_add_u64 v[104:105], v[104:105], 0, v[130:131]
	v_lshl_add_u64 v[102:103], s[14:15], 0, v[102:103]
	v_med3_f32 v94, v94, s71, v172
	v_med3_f32 v90, v90, s71, v172
	v_med3_f32 v95, v95, s71, v172
	global_store_dwordx4 v[104:105], v[98:101], off
	v_lshl_add_u64 v[102:103], v[102:103], 0, v[130:131]
	v_mul_f32_e32 v94, 0xbfb8aa3b, v94
	v_cvt_pk_bf16_f32 v98, v115, v114
	v_cvt_pk_bf16_f32 v99, v112, v113
	v_cvt_pk_bf16_f32 v100, v116, v117
	v_cvt_pk_bf16_f32 v101, v118, v119
	v_mul_f32_e32 v90, 0xbfb8aa3b, v90
	v_mul_f32_e32 v95, 0xbfb8aa3b, v95
	global_store_dwordx4 v[102:103], v[98:101], off
	v_exp_f32_e32 v94, v94
	v_exp_f32_e32 v95, v95
	v_exp_f32_e32 v98, v90
	v_fmamk_f32 v86, v86, 0x3c800000, v10
	v_fmamk_f32 v87, v87, 0x3c800000, v11
	v_fmamk_f32 v91, v91, 0x3c800000, v7
	v_med3_f32 v86, v86, s71, v172
	v_med3_f32 v87, v87, s71, v172
	v_med3_f32 v91, v91, s71, v172
	v_mul_f32_e32 v86, 0xbfb8aa3b, v86
	v_mul_f32_e32 v87, 0xbfb8aa3b, v87
	v_mul_f32_e32 v91, 0xbfb8aa3b, v91
	v_exp_f32_e32 v86, v86
	v_add_f32_e32 v90, 1.0, v94
	v_add_f32_e32 v94, 1.0, v98
	v_exp_f32_e32 v87, v87
	v_exp_f32_e32 v98, v91
	v_add_f32_e32 v91, 1.0, v95
	v_rcp_f32_e32 v90, v90
	v_rcp_f32_e32 v91, v91
	v_fmamk_f32 v82, v82, 0x3c800000, v2
	v_fmamk_f32 v83, v83, 0x3c800000, v3
	v_med3_f32 v82, v82, s71, v172
	v_med3_f32 v83, v83, s71, v172
	v_mul_f32_e32 v82, 0xbfb8aa3b, v82
	v_mul_f32_e32 v83, 0xbfb8aa3b, v83
	v_pk_add_f32 v[86:87], v[86:87], 1.0 op_sel_hi:[1,0]
	v_exp_f32_e32 v82, v82
	v_exp_f32_e32 v83, v83
	v_rcp_f32_e32 v99, v86
	v_pk_mul_f32 v[90:91], v[90:91], v[86:87]
	v_add_f32_e32 v86, 1.0, v98
	v_rcp_f32_e32 v94, v94
	v_rcp_f32_e32 v95, v86
	v_pk_add_f32 v[82:83], v[82:83], 1.0 op_sel_hi:[1,0]
	v_rcp_f32_e32 v98, v87
	v_rcp_f32_e32 v100, v82
	v_pk_mul_f32 v[86:87], v[94:95], v[82:83]
	v_fmamk_f32 v82, v96, 0x3c800000, v16
	v_med3_f32 v82, v82, s71, v172
	v_mul_f32_e32 v82, 0xbfb8aa3b, v82
	v_rcp_f32_e32 v101, v83
	v_exp_f32_e32 v83, v82
	v_fmamk_f32 v82, v88, 0x3c800000, v12
	v_fmamk_f32 v88, v92, 0x3c800000, v8
	v_med3_f32 v88, v88, s71, v172
	v_mul_f32_e32 v88, 0xbfb8aa3b, v88
	v_exp_f32_e32 v92, v88
	v_add_f32_e32 v83, 1.0, v83
	v_rcp_f32_e32 v88, v83
	v_med3_f32 v82, v82, s71, v172
	v_add_f32_e32 v83, 1.0, v92
	v_rcp_f32_e32 v92, v83
	v_fmamk_f32 v83, v97, 0x3c800000, v17
	v_med3_f32 v83, v83, s71, v172
	v_mul_f32_e32 v83, 0xbfb8aa3b, v83
	v_exp_f32_e32 v94, v83
	v_fmamk_f32 v83, v89, 0x3c800000, v13
	v_fmamk_f32 v89, v93, 0x3c800000, v9
	v_med3_f32 v83, v83, s71, v172
	v_med3_f32 v89, v89, s71, v172
	v_mul_f32_e32 v82, 0xbfb8aa3b, v82
	v_mul_f32_e32 v83, 0xbfb8aa3b, v83
	v_mul_f32_e32 v89, 0xbfb8aa3b, v89
	v_exp_f32_e32 v82, v82
	v_fmamk_f32 v84, v84, 0x3c800000, v4
	v_exp_f32_e32 v83, v83
	v_exp_f32_e32 v93, v89
	v_fmamk_f32 v85, v85, 0x3c800000, v5
	v_add_f32_e32 v89, 1.0, v94
	v_med3_f32 v84, v84, s71, v172
	v_med3_f32 v85, v85, s71, v172
	v_rcp_f32_e32 v89, v89
	v_mul_f32_e32 v84, 0xbfb8aa3b, v84
	v_mul_f32_e32 v85, 0xbfb8aa3b, v85
	v_exp_f32_e32 v84, v84
	v_exp_f32_e32 v85, v85
	v_pk_add_f32 v[82:83], v[82:83], 1.0 op_sel_hi:[1,0]
	v_or_b32_e32 v94, 48, v158
	v_rcp_f32_e32 v96, v82
	v_pk_mul_f32 v[88:89], v[88:89], v[82:83]
	v_add_f32_e32 v82, 1.0, v93
	v_rcp_f32_e32 v93, v82
	v_rcp_f32_e32 v97, v83
	v_pk_add_f32 v[82:83], v[84:85], 1.0 op_sel_hi:[1,0]
	v_ashrrev_i32_e32 v95, 31, v94
	v_rcp_f32_e32 v102, v82
	v_rcp_f32_e32 v103, v83
	v_cvt_pk_bf16_f32 v84, v86, v87
	v_lshlrev_b64 v[86:87], 12, v[94:95]
	v_pk_mul_f32 v[92:93], v[92:93], v[82:83]
	v_cvt_pk_bf16_f32 v83, v88, v89
	v_lshl_add_u64 v[88:89], s[4:5], 0, v[86:87]
	v_fmamk_f32 v78, v78, 0x3c800000, v14
	v_fmamk_f32 v74, v74, 0x3c800000, v6
	v_fmamk_f32 v79, v79, 0x3c800000, v15
	v_cvt_pk_bf16_f32 v82, v90, v91
	v_cvt_pk_bf16_f32 v85, v92, v93
	v_lshl_add_u64 v[88:89], v[88:89], 0, v[130:131]
	v_lshl_add_u64 v[86:87], s[14:15], 0, v[86:87]
	v_med3_f32 v78, v78, s71, v172
	v_med3_f32 v74, v74, s71, v172
	v_med3_f32 v79, v79, s71, v172
	global_store_dwordx4 v[88:89], v[82:85], off
	v_lshl_add_u64 v[86:87], v[86:87], 0, v[130:131]
	v_mul_f32_e32 v78, 0xbfb8aa3b, v78
	v_cvt_pk_bf16_f32 v82, v99, v98
	v_cvt_pk_bf16_f32 v83, v96, v97
	v_cvt_pk_bf16_f32 v84, v100, v101
	v_cvt_pk_bf16_f32 v85, v102, v103
	v_mul_f32_e32 v74, 0xbfb8aa3b, v74
	v_mul_f32_e32 v79, 0xbfb8aa3b, v79
	global_store_dwordx4 v[86:87], v[82:85], off
	v_exp_f32_e32 v78, v78
	v_exp_f32_e32 v79, v79
	v_exp_f32_e32 v82, v74
	v_fmamk_f32 v70, v70, 0x3c800000, v10
	v_fmamk_f32 v71, v71, 0x3c800000, v11
	v_fmamk_f32 v75, v75, 0x3c800000, v7
	v_med3_f32 v70, v70, s71, v172
	v_med3_f32 v71, v71, s71, v172
	v_med3_f32 v75, v75, s71, v172
; __device__ __forceinline__ unsigned pk_bf16(float lo, float hi) { const f32x2_t v = {lo, hi}; return __builtin_bit_cast(unsigned, __builtin_convertvector(v, bf16x2_t)); }
;     __device__ __forceinline__ bool operator()(f32x4 (&acc)[2][2][4][2], const Unit& u, int wr, int wc, int fr, int fq) const {
;     ...
;             for (int ai = 0; ai < 2; ++ai)
; #pragma unroll
;                 for (int m = 0; m < 4; ++m) { const int row = r0 + ai * HALF + m * 16;
;                     const f32x4 a0 = acc[ai][0][m][0] * gsc + ba0, a1 = acc[ai][0][m][1] * gsc + ba1, b0 = acc[ai][1][m][0] * gsc + bb0, b1 = acc[ai][1][m][1] * gsc + bb1;
;                     f32x4 r0v, r1v, s0v, s1v;
; #pragma unroll
;                     for (int j = 0; j < 4; ++j) {
;                         const float ea0 = __builtin_amdgcn_exp2f(-1.44269504f * fminf(fmaxf(a0[j], -40.f), 40.f)), eb0 = __builtin_amdgcn_exp2f(-1.44269504f * fminf(fmaxf(b0[j], -40.f), 40.f));
;                         const float ea1 = __builtin_amdgcn_exp2f(-1.44269504f * fminf(fmaxf(a1[j], -40.f), 40.f)), eb1 = __builtin_amdgcn_exp2f(-1.44269504f * fminf(fmaxf(b1[j], -40.f), 40.f));
;                         s0v[j] = __builtin_amdgcn_rcpf(1.0f + eb0); s1v[j] = __builtin_amdgcn_rcpf(1.0f + eb1);
;                         r0v[j] = (1.0f + eb0) * __builtin_amdgcn_rcpf(1.0f + ea0); r1v[j] = (1.0f + eb1) * __builtin_amdgcn_rcpf(1.0f + ea1); }
;                     u32x4 w; w.x = pk_bf16(r0v[0], r0v[1]); w.y = pk_bf16(r0v[2], r0v[3]); w.z = pk_bf16(r1v[0], r1v[1]); w.w = pk_bf16(r1v[2], r1v[3]);
;                     *(u32x4*)(SGR + (size_t)row * D + ch0) = w;
;                     w.x = pk_bf16(s0v[0], s0v[1]); w.y = pk_bf16(s0v[2], s0v[3]); w.z = pk_bf16(s1v[0], s1v[1]); w.w = pk_bf16(s1v[2], s1v[3]);
;                     *(u32x4*)(SGB + (size_t)row * D + ch0) = w; }
	v_mul_f32_e32 v70, 0xbfb8aa3b, v70
	v_mul_f32_e32 v71, 0xbfb8aa3b, v71
	v_mul_f32_e32 v75, 0xbfb8aa3b, v75
	v_exp_f32_e32 v70, v70
	v_add_f32_e32 v74, 1.0, v78
	v_add_f32_e32 v78, 1.0, v82
	v_exp_f32_e32 v71, v71
	v_exp_f32_e32 v82, v75
	v_add_f32_e32 v75, 1.0, v79
	v_rcp_f32_e32 v74, v74
	v_rcp_f32_e32 v75, v75
	v_fmamk_f32 v66, v66, 0x3c800000, v2
	v_fmamk_f32 v67, v67, 0x3c800000, v3
	v_med3_f32 v66, v66, s71, v172
	v_med3_f32 v67, v67, s71, v172
	v_mul_f32_e32 v66, 0xbfb8aa3b, v66
	v_mul_f32_e32 v67, 0xbfb8aa3b, v67
	v_pk_add_f32 v[70:71], v[70:71], 1.0 op_sel_hi:[1,0]
	v_exp_f32_e32 v66, v66
	v_exp_f32_e32 v67, v67
	v_rcp_f32_e32 v83, v70
	v_pk_mul_f32 v[74:75], v[74:75], v[70:71]
	v_add_f32_e32 v70, 1.0, v82
	v_rcp_f32_e32 v78, v78
	v_rcp_f32_e32 v79, v70
	v_pk_add_f32 v[66:67], v[66:67], 1.0 op_sel_hi:[1,0]
	v_rcp_f32_e32 v82, v71
	v_rcp_f32_e32 v84, v66
	v_pk_mul_f32 v[70:71], v[78:79], v[66:67]
	v_fmamk_f32 v66, v80, 0x3c800000, v16
	v_med3_f32 v66, v66, s71, v172
	v_mul_f32_e32 v66, 0xbfb8aa3b, v66
	v_rcp_f32_e32 v78, v67
	v_exp_f32_e32 v67, v66
	v_fmamk_f32 v66, v72, 0x3c800000, v12
	v_fmamk_f32 v72, v76, 0x3c800000, v8
	v_med3_f32 v72, v72, s71, v172
	v_mul_f32_e32 v72, 0xbfb8aa3b, v72
	v_exp_f32_e32 v76, v72
	v_add_f32_e32 v67, 1.0, v67
	v_rcp_f32_e32 v72, v67
	v_med3_f32 v66, v66, s71, v172
	v_add_f32_e32 v67, 1.0, v76
	v_rcp_f32_e32 v76, v67
	v_fmamk_f32 v67, v81, 0x3c800000, v17
	v_med3_f32 v67, v67, s71, v172
	v_mul_f32_e32 v67, 0xbfb8aa3b, v67
	v_exp_f32_e32 v79, v67
	v_fmamk_f32 v67, v73, 0x3c800000, v13
	v_fmamk_f32 v73, v77, 0x3c800000, v9
	v_med3_f32 v67, v67, s71, v172
	v_med3_f32 v73, v73, s71, v172
	v_mul_f32_e32 v66, 0xbfb8aa3b, v66
	v_mul_f32_e32 v67, 0xbfb8aa3b, v67
	v_mul_f32_e32 v73, 0xbfb8aa3b, v73
	v_exp_f32_e32 v66, v66
	v_fmamk_f32 v68, v68, 0x3c800000, v4
	v_exp_f32_e32 v67, v67
	v_exp_f32_e32 v77, v73
	v_fmamk_f32 v69, v69, 0x3c800000, v5
	v_add_f32_e32 v73, 1.0, v79
	v_med3_f32 v68, v68, s71, v172
	v_med3_f32 v69, v69, s71, v172
	v_rcp_f32_e32 v73, v73
	v_mul_f32_e32 v68, 0xbfb8aa3b, v68
	v_mul_f32_e32 v69, 0xbfb8aa3b, v69
	v_exp_f32_e32 v68, v68
	v_exp_f32_e32 v69, v69
	v_pk_add_f32 v[66:67], v[66:67], 1.0 op_sel_hi:[1,0]
	v_fmamk_f32 v62, v62, 0x3c800000, v14
	v_rcp_f32_e32 v79, v66
	v_pk_mul_f32 v[72:73], v[72:73], v[66:67]
	v_add_f32_e32 v66, 1.0, v77
	v_rcp_f32_e32 v77, v66
	v_rcp_f32_e32 v80, v67
	v_pk_add_f32 v[66:67], v[68:69], 1.0 op_sel_hi:[1,0]
	v_cvt_pk_bf16_f32 v68, v70, v71
	v_rcp_f32_e32 v81, v66
	v_rcp_f32_e32 v85, v67
	v_lshl_add_u64 v[70:71], v[132:133], 0, s[18:19]
	v_pk_mul_f32 v[76:77], v[76:77], v[66:67]
	v_cvt_pk_bf16_f32 v67, v72, v73
	v_lshl_add_u64 v[72:73], s[4:5], 0, v[70:71]
	v_fmamk_f32 v58, v58, 0x3c800000, v6
	v_fmamk_f32 v63, v63, 0x3c800000, v15
	v_cvt_pk_bf16_f32 v66, v74, v75
	v_cvt_pk_bf16_f32 v69, v76, v77
	v_lshl_add_u64 v[72:73], v[72:73], 0, v[130:131]
	v_lshl_add_u64 v[70:71], s[14:15], 0, v[70:71]
	v_med3_f32 v62, v62, s71, v172
	v_med3_f32 v58, v58, s71, v172
	v_med3_f32 v63, v63, s71, v172
	global_store_dwordx4 v[72:73], v[66:69], off
	v_lshl_add_u64 v[70:71], v[70:71], 0, v[130:131]
	v_mul_f32_e32 v62, 0xbfb8aa3b, v62
	v_cvt_pk_bf16_f32 v66, v83, v82
	v_cvt_pk_bf16_f32 v67, v79, v80
	v_cvt_pk_bf16_f32 v68, v84, v78
	v_cvt_pk_bf16_f32 v69, v81, v85
	v_mul_f32_e32 v58, 0xbfb8aa3b, v58
	v_mul_f32_e32 v63, 0xbfb8aa3b, v63
	global_store_dwordx4 v[70:71], v[66:69], off
	v_exp_f32_e32 v62, v62
	v_exp_f32_e32 v63, v63
	v_exp_f32_e32 v66, v58
	v_fmamk_f32 v54, v54, 0x3c800000, v10
	v_fmamk_f32 v55, v55, 0x3c800000, v11
	v_fmamk_f32 v59, v59, 0x3c800000, v7
	v_med3_f32 v54, v54, s71, v172
	v_med3_f32 v55, v55, s71, v172
	v_med3_f32 v59, v59, s71, v172
	v_mul_f32_e32 v54, 0xbfb8aa3b, v54
	v_mul_f32_e32 v55, 0xbfb8aa3b, v55
	v_mul_f32_e32 v59, 0xbfb8aa3b, v59
	v_exp_f32_e32 v54, v54
	v_add_f32_e32 v58, 1.0, v62
	v_add_f32_e32 v62, 1.0, v66
	v_exp_f32_e32 v55, v55
	v_exp_f32_e32 v66, v59
	v_add_f32_e32 v59, 1.0, v63
	v_rcp_f32_e32 v58, v58
	v_rcp_f32_e32 v59, v59
	v_fmamk_f32 v50, v50, 0x3c800000, v2
	v_fmamk_f32 v51, v51, 0x3c800000, v3
	v_med3_f32 v50, v50, s71, v172
	v_med3_f32 v51, v51, s71, v172
	v_mul_f32_e32 v50, 0xbfb8aa3b, v50
	v_mul_f32_e32 v51, 0xbfb8aa3b, v51
	v_pk_add_f32 v[54:55], v[54:55], 1.0 op_sel_hi:[1,0]
	v_exp_f32_e32 v50, v50
	v_exp_f32_e32 v51, v51
	v_rcp_f32_e32 v67, v54
	v_pk_mul_f32 v[58:59], v[58:59], v[54:55]
	v_add_f32_e32 v54, 1.0, v66
	v_rcp_f32_e32 v62, v62
	v_rcp_f32_e32 v63, v54
	v_pk_add_f32 v[50:51], v[50:51], 1.0 op_sel_hi:[1,0]
	v_rcp_f32_e32 v66, v55
	v_rcp_f32_e32 v68, v50
	v_pk_mul_f32 v[54:55], v[62:63], v[50:51]
	v_fmamk_f32 v50, v64, 0x3c800000, v16
	v_med3_f32 v50, v50, s71, v172
	v_mul_f32_e32 v50, 0xbfb8aa3b, v50
	v_rcp_f32_e32 v62, v51
	v_exp_f32_e32 v51, v50
	v_fmamk_f32 v50, v56, 0x3c800000, v12
	v_fmamk_f32 v56, v60, 0x3c800000, v8
	v_med3_f32 v56, v56, s71, v172
	v_mul_f32_e32 v56, 0xbfb8aa3b, v56
	v_exp_f32_e32 v60, v56
	v_add_f32_e32 v51, 1.0, v51
	v_rcp_f32_e32 v56, v51
	v_med3_f32 v50, v50, s71, v172
	v_add_f32_e32 v51, 1.0, v60
	v_rcp_f32_e32 v60, v51
	v_fmamk_f32 v51, v65, 0x3c800000, v17
	v_med3_f32 v51, v51, s71, v172
	v_mul_f32_e32 v51, 0xbfb8aa3b, v51
	v_exp_f32_e32 v63, v51
	v_fmamk_f32 v51, v57, 0x3c800000, v13
	v_fmamk_f32 v57, v61, 0x3c800000, v9
	v_med3_f32 v51, v51, s71, v172
	v_med3_f32 v57, v57, s71, v172
	v_mul_f32_e32 v50, 0xbfb8aa3b, v50
	v_mul_f32_e32 v51, 0xbfb8aa3b, v51
	v_mul_f32_e32 v57, 0xbfb8aa3b, v57
	v_exp_f32_e32 v50, v50
	v_fmamk_f32 v52, v52, 0x3c800000, v4
	v_exp_f32_e32 v51, v51
	v_exp_f32_e32 v61, v57
	v_fmamk_f32 v53, v53, 0x3c800000, v5
	v_add_f32_e32 v57, 1.0, v63
; __device__ __forceinline__ unsigned pk_bf16(float lo, float hi) { const f32x2_t v = {lo, hi}; return __builtin_bit_cast(unsigned, __builtin_convertvector(v, bf16x2_t)); }
;     __device__ __forceinline__ bool operator()(f32x4 (&acc)[2][2][4][2], const Unit& u, int wr, int wc, int fr, int fq) const {
;     ...
;             for (int ai = 0; ai < 2; ++ai)
; #pragma unroll
;                 for (int m = 0; m < 4; ++m) { const int row = r0 + ai * HALF + m * 16;
;                     const f32x4 a0 = acc[ai][0][m][0] * gsc + ba0, a1 = acc[ai][0][m][1] * gsc + ba1, b0 = acc[ai][1][m][0] * gsc + bb0, b1 = acc[ai][1][m][1] * gsc + bb1;
;                     f32x4 r0v, r1v, s0v, s1v;
; #pragma unroll
;                     for (int j = 0; j < 4; ++j) {
;                         const float ea0 = __builtin_amdgcn_exp2f(-1.44269504f * fminf(fmaxf(a0[j], -40.f), 40.f)), eb0 = __builtin_amdgcn_exp2f(-1.44269504f * fminf(fmaxf(b0[j], -40.f), 40.f));
;                         const float ea1 = __builtin_amdgcn_exp2f(-1.44269504f * fminf(fmaxf(a1[j], -40.f), 40.f)), eb1 = __builtin_amdgcn_exp2f(-1.44269504f * fminf(fmaxf(b1[j], -40.f), 40.f));
;                         s0v[j] = __builtin_amdgcn_rcpf(1.0f + eb0); s1v[j] = __builtin_amdgcn_rcpf(1.0f + eb1);
;                         r0v[j] = (1.0f + eb0) * __builtin_amdgcn_rcpf(1.0f + ea0); r1v[j] = (1.0f + eb1) * __builtin_amdgcn_rcpf(1.0f + ea1); }
;                     u32x4 w; w.x = pk_bf16(r0v[0], r0v[1]); w.y = pk_bf16(r0v[2], r0v[3]); w.z = pk_bf16(r1v[0], r1v[1]); w.w = pk_bf16(r1v[2], r1v[3]);
;                     *(u32x4*)(SGR + (size_t)row * D + ch0) = w;
;                     w.x = pk_bf16(s0v[0], s0v[1]); w.y = pk_bf16(s0v[2], s0v[3]); w.z = pk_bf16(s1v[0], s1v[1]); w.w = pk_bf16(s1v[2], s1v[3]);
;                     *(u32x4*)(SGB + (size_t)row * D + ch0) = w; }
	v_med3_f32 v52, v52, s71, v172
	v_med3_f32 v53, v53, s71, v172
	v_rcp_f32_e32 v57, v57
	v_mul_f32_e32 v52, 0xbfb8aa3b, v52
	v_mul_f32_e32 v53, 0xbfb8aa3b, v53
	v_exp_f32_e32 v52, v52
	v_exp_f32_e32 v53, v53
	v_pk_add_f32 v[50:51], v[50:51], 1.0 op_sel_hi:[1,0]
	v_fmamk_f32 v46, v46, 0x3c800000, v14
	v_rcp_f32_e32 v63, v50
	v_pk_mul_f32 v[56:57], v[56:57], v[50:51]
	v_add_f32_e32 v50, 1.0, v61
	v_rcp_f32_e32 v61, v50
	v_rcp_f32_e32 v64, v51
	v_pk_add_f32 v[50:51], v[52:53], 1.0 op_sel_hi:[1,0]
	v_cvt_pk_bf16_f32 v52, v54, v55
	v_rcp_f32_e32 v65, v50
	v_rcp_f32_e32 v69, v51
	v_lshl_add_u64 v[54:55], v[132:133], 0, s[20:21]
	v_pk_mul_f32 v[60:61], v[60:61], v[50:51]
	v_cvt_pk_bf16_f32 v51, v56, v57
	v_lshl_add_u64 v[56:57], s[4:5], 0, v[54:55]
	v_fmamk_f32 v42, v42, 0x3c800000, v6
	v_fmamk_f32 v47, v47, 0x3c800000, v15
	v_cvt_pk_bf16_f32 v50, v58, v59
	v_cvt_pk_bf16_f32 v53, v60, v61
	v_lshl_add_u64 v[56:57], v[56:57], 0, v[130:131]
	v_lshl_add_u64 v[54:55], s[14:15], 0, v[54:55]
	v_med3_f32 v46, v46, s71, v172
	v_med3_f32 v42, v42, s71, v172
	v_med3_f32 v47, v47, s71, v172
	global_store_dwordx4 v[56:57], v[50:53], off
	v_lshl_add_u64 v[54:55], v[54:55], 0, v[130:131]
	v_mul_f32_e32 v46, 0xbfb8aa3b, v46
	v_cvt_pk_bf16_f32 v50, v67, v66
	v_cvt_pk_bf16_f32 v51, v63, v64
	v_cvt_pk_bf16_f32 v52, v68, v62
	v_cvt_pk_bf16_f32 v53, v65, v69
	v_mul_f32_e32 v42, 0xbfb8aa3b, v42
	v_mul_f32_e32 v47, 0xbfb8aa3b, v47
	global_store_dwordx4 v[54:55], v[50:53], off
	v_exp_f32_e32 v46, v46
	v_exp_f32_e32 v47, v47
	v_exp_f32_e32 v50, v42
	v_fmamk_f32 v14, v30, 0x3c800000, v14
	v_fmamk_f32 v15, v31, 0x3c800000, v15
	v_fmamk_f32 v38, v38, 0x3c800000, v10
	v_fmamk_f32 v39, v39, 0x3c800000, v11
	v_fmamk_f32 v43, v43, 0x3c800000, v7
	v_med3_f32 v14, v14, s71, v172
	v_med3_f32 v15, v15, s71, v172
	v_med3_f32 v38, v38, s71, v172
	v_med3_f32 v39, v39, s71, v172
	v_med3_f32 v43, v43, s71, v172
	v_mul_f32_e32 v14, 0xbfb8aa3b, v14
	v_mul_f32_e32 v15, 0xbfb8aa3b, v15
	v_mul_f32_e32 v38, 0xbfb8aa3b, v38
	v_mul_f32_e32 v39, 0xbfb8aa3b, v39
	v_mul_f32_e32 v43, 0xbfb8aa3b, v43
	v_exp_f32_e32 v14, v14
	v_exp_f32_e32 v15, v15
	v_exp_f32_e32 v38, v38
	v_add_f32_e32 v42, 1.0, v46
	v_add_f32_e32 v46, 1.0, v50
	v_exp_f32_e32 v39, v39
	v_exp_f32_e32 v50, v43
	v_add_f32_e32 v43, 1.0, v47
	v_fmamk_f32 v10, v22, 0x3c800000, v10
	v_fmamk_f32 v6, v26, 0x3c800000, v6
	v_fmamk_f32 v11, v23, 0x3c800000, v11
	v_fmamk_f32 v7, v27, 0x3c800000, v7
	v_rcp_f32_e32 v42, v42
	v_rcp_f32_e32 v43, v43
	v_med3_f32 v10, v10, s71, v172
	v_med3_f32 v6, v6, s71, v172
	v_med3_f32 v11, v11, s71, v172
	v_med3_f32 v7, v7, s71, v172
	v_fmamk_f32 v34, v34, 0x3c800000, v2
	v_fmamk_f32 v35, v35, 0x3c800000, v3
	v_mul_f32_e32 v10, 0xbfb8aa3b, v10
	v_mul_f32_e32 v6, 0xbfb8aa3b, v6
	v_mul_f32_e32 v11, 0xbfb8aa3b, v11
	v_mul_f32_e32 v7, 0xbfb8aa3b, v7
	v_med3_f32 v34, v34, s71, v172
	v_med3_f32 v35, v35, s71, v172
	v_exp_f32_e32 v10, v10
	v_exp_f32_e32 v22, v6
	v_fmamk_f32 v2, v18, 0x3c800000, v2
	v_add_f32_e32 v6, 1.0, v14
	v_exp_f32_e32 v11, v11
	v_exp_f32_e32 v18, v7
	v_add_f32_e32 v7, 1.0, v15
	v_mul_f32_e32 v34, 0xbfb8aa3b, v34
	v_mul_f32_e32 v35, 0xbfb8aa3b, v35
	v_pk_add_f32 v[38:39], v[38:39], 1.0 op_sel_hi:[1,0]
	v_rcp_f32_e32 v6, v6
	v_rcp_f32_e32 v7, v7
	v_exp_f32_e32 v34, v34
	v_exp_f32_e32 v35, v35
	v_rcp_f32_e32 v51, v38
	v_pk_mul_f32 v[42:43], v[42:43], v[38:39]
	v_add_f32_e32 v38, 1.0, v50
	v_fmamk_f32 v3, v19, 0x3c800000, v3
	v_rcp_f32_e32 v46, v46
	v_rcp_f32_e32 v47, v38
	v_med3_f32 v2, v2, s71, v172
	v_med3_f32 v3, v3, s71, v172
	v_mul_f32_e32 v2, 0xbfb8aa3b, v2
	v_mul_f32_e32 v3, 0xbfb8aa3b, v3
	v_pk_add_f32 v[10:11], v[10:11], 1.0 op_sel_hi:[1,0]
	v_exp_f32_e32 v2, v2
	v_add_f32_e32 v14, 1.0, v22
	v_exp_f32_e32 v3, v3
	v_rcp_f32_e32 v19, v10
	v_pk_mul_f32 v[6:7], v[6:7], v[10:11]
	v_add_f32_e32 v10, 1.0, v18
	v_pk_add_f32 v[34:35], v[34:35], 1.0 op_sel_hi:[1,0]
	v_rcp_f32_e32 v14, v14
	v_rcp_f32_e32 v15, v10
	v_rcp_f32_e32 v50, v39
	v_rcp_f32_e32 v52, v34
	v_pk_mul_f32 v[38:39], v[46:47], v[34:35]
	v_fmamk_f32 v34, v48, 0x3c800000, v16
	v_med3_f32 v34, v34, s71, v172
	v_mul_f32_e32 v34, 0xbfb8aa3b, v34
	v_pk_add_f32 v[2:3], v[2:3], 1.0 op_sel_hi:[1,0]
	v_rcp_f32_e32 v46, v35
	v_exp_f32_e32 v35, v34
; __device__ __forceinline__ unsigned pk_bf16(float lo, float hi) { const f32x2_t v = {lo, hi}; return __builtin_bit_cast(unsigned, __builtin_convertvector(v, bf16x2_t)); }
; template <int MODE  , class Epi, class Sched>
; __device__ __forceinline__ void gemm_phase(LAS unsigned char* lds, const GemmDesc g, const Sched& S, const Epi& E) {
;     ...
;         if (!has_next) break;
;     __device__ __forceinline__ bool operator()(f32x4 (&acc)[2][2][4][2], const Unit& u, int wr, int wc, int fr, int fq) const {
;     ...
;                 for (int m = 0; m < 4; ++m) { const int row = r0 + ai * HALF + m * 16;
;                     const f32x4 a0 = acc[ai][0][m][0] * gsc + ba0, a1 = acc[ai][0][m][1] * gsc + ba1, b0 = acc[ai][1][m][0] * gsc + bb0, b1 = acc[ai][1][m][1] * gsc + bb1;
;                     f32x4 r0v, r1v, s0v, s1v;
; #pragma unroll
;                     for (int j = 0; j < 4; ++j) {
;                         const float ea0 = __builtin_amdgcn_exp2f(-1.44269504f * fminf(fmaxf(a0[j], -40.f), 40.f)), eb0 = __builtin_amdgcn_exp2f(-1.44269504f * fminf(fmaxf(b0[j], -40.f), 40.f));
;                         const float ea1 = __builtin_amdgcn_exp2f(-1.44269504f * fminf(fmaxf(a1[j], -40.f), 40.f)), eb1 = __builtin_amdgcn_exp2f(-1.44269504f * fminf(fmaxf(b1[j], -40.f), 40.f));
;                         s0v[j] = __builtin_amdgcn_rcpf(1.0f + eb0); s1v[j] = __builtin_amdgcn_rcpf(1.0f + eb1);
;                         r0v[j] = (1.0f + eb0) * __builtin_amdgcn_rcpf(1.0f + ea0); r1v[j] = (1.0f + eb1) * __builtin_amdgcn_rcpf(1.0f + ea1); }
;                     u32x4 w; w.x = pk_bf16(r0v[0], r0v[1]); w.y = pk_bf16(r0v[2], r0v[3]); w.z = pk_bf16(r1v[0], r1v[1]); w.w = pk_bf16(r1v[2], r1v[3]);
;                     *(u32x4*)(SGR + (size_t)row * D + ch0) = w;
;                     w.x = pk_bf16(s0v[0], s0v[1]); w.y = pk_bf16(s0v[2], s0v[3]); w.z = pk_bf16(s1v[0], s1v[1]); w.w = pk_bf16(s1v[2], s1v[3]);
;                     *(u32x4*)(SGB + (size_t)row * D + ch0) = w; }
	v_fmamk_f32 v34, v40, 0x3c800000, v12
	v_fmamk_f32 v40, v44, 0x3c800000, v8
	v_rcp_f32_e32 v18, v11
	v_rcp_f32_e32 v22, v2
	v_pk_mul_f32 v[10:11], v[14:15], v[2:3]
	v_fmamk_f32 v2, v32, 0x3c800000, v16
	v_med3_f32 v40, v40, s71, v172
	v_med3_f32 v2, v2, s71, v172
	v_fmamk_f32 v8, v28, 0x3c800000, v8
	v_mul_f32_e32 v40, 0xbfb8aa3b, v40
	v_mul_f32_e32 v2, 0xbfb8aa3b, v2
	v_med3_f32 v8, v8, s71, v172
	v_exp_f32_e32 v44, v40
	v_rcp_f32_e32 v14, v3
	v_exp_f32_e32 v3, v2
	v_mul_f32_e32 v8, 0xbfb8aa3b, v8
	v_fmamk_f32 v2, v24, 0x3c800000, v12
	v_exp_f32_e32 v12, v8
	v_add_f32_e32 v35, 1.0, v35
	v_rcp_f32_e32 v40, v35
	v_add_f32_e32 v35, 1.0, v44
	v_add_f32_e32 v3, 1.0, v3
	v_rcp_f32_e32 v44, v35
	v_fmamk_f32 v35, v49, 0x3c800000, v17
	v_rcp_f32_e32 v8, v3
	v_add_f32_e32 v3, 1.0, v12
	v_fmac_f32_e32 v17, 0x3c800000, v33
	v_rcp_f32_e32 v12, v3
	v_med3_f32 v3, v17, s71, v172
	v_med3_f32 v35, v35, s71, v172
	v_mul_f32_e32 v3, 0xbfb8aa3b, v3
	v_mul_f32_e32 v35, 0xbfb8aa3b, v35
	v_exp_f32_e32 v15, v3
	v_exp_f32_e32 v47, v35
	v_fmamk_f32 v35, v41, 0x3c800000, v13
	v_fmamk_f32 v41, v45, 0x3c800000, v9
	v_fmac_f32_e32 v13, 0x3c800000, v25
	v_fmac_f32_e32 v9, 0x3c800000, v29
	v_med3_f32 v2, v2, s71, v172
	v_med3_f32 v3, v13, s71, v172
	v_med3_f32 v9, v9, s71, v172
	v_med3_f32 v34, v34, s71, v172
	v_med3_f32 v35, v35, s71, v172
	v_med3_f32 v41, v41, s71, v172
	v_mul_f32_e32 v2, 0xbfb8aa3b, v2
	v_mul_f32_e32 v3, 0xbfb8aa3b, v3
	v_mul_f32_e32 v9, 0xbfb8aa3b, v9
	v_mul_f32_e32 v34, 0xbfb8aa3b, v34
	v_mul_f32_e32 v35, 0xbfb8aa3b, v35
	v_mul_f32_e32 v41, 0xbfb8aa3b, v41
	v_exp_f32_e32 v2, v2
	v_exp_f32_e32 v3, v3
	v_exp_f32_e32 v13, v9
	v_add_f32_e32 v9, 1.0, v15
	v_exp_f32_e32 v34, v34
	v_fmamk_f32 v36, v36, 0x3c800000, v4
	v_exp_f32_e32 v35, v35
	v_exp_f32_e32 v45, v41
	v_fmamk_f32 v37, v37, 0x3c800000, v5
	v_add_f32_e32 v41, 1.0, v47
	v_fmamk_f32 v4, v20, 0x3c800000, v4
	v_fmac_f32_e32 v5, 0x3c800000, v21
	v_rcp_f32_e32 v9, v9
	v_med3_f32 v36, v36, s71, v172
	v_med3_f32 v37, v37, s71, v172
	v_rcp_f32_e32 v41, v41
	v_med3_f32 v4, v4, s71, v172
	v_med3_f32 v5, v5, s71, v172
	v_mul_f32_e32 v36, 0xbfb8aa3b, v36
	v_mul_f32_e32 v37, 0xbfb8aa3b, v37
	v_mul_f32_e32 v4, 0xbfb8aa3b, v4
	v_mul_f32_e32 v5, 0xbfb8aa3b, v5
	v_exp_f32_e32 v36, v36
	v_exp_f32_e32 v37, v37
	v_exp_f32_e32 v4, v4
	v_exp_f32_e32 v5, v5
	v_pk_add_f32 v[2:3], v[2:3], 1.0 op_sel_hi:[1,0]
	v_pk_add_f32 v[34:35], v[34:35], 1.0 op_sel_hi:[1,0]
	v_rcp_f32_e32 v15, v2
	v_pk_mul_f32 v[8:9], v[8:9], v[2:3]
	v_add_f32_e32 v2, 1.0, v13
	v_rcp_f32_e32 v47, v34
	v_pk_mul_f32 v[40:41], v[40:41], v[34:35]
	v_add_f32_e32 v34, 1.0, v45
	v_rcp_f32_e32 v13, v2
	v_rcp_f32_e32 v45, v34
	v_rcp_f32_e32 v48, v35
	v_pk_add_f32 v[34:35], v[36:37], 1.0 op_sel_hi:[1,0]
	v_rcp_f32_e32 v16, v3
	v_pk_add_f32 v[2:3], v[4:5], 1.0 op_sel_hi:[1,0]
	v_rcp_f32_e32 v49, v34
	v_rcp_f32_e32 v53, v35
	v_rcp_f32_e32 v17, v2
	v_rcp_f32_e32 v20, v3
	v_cvt_pk_bf16_f32 v36, v38, v39
	v_lshl_add_u64 v[38:39], v[132:133], 0, s[34:35]
	v_pk_mul_f32 v[12:13], v[12:13], v[2:3]
	v_cvt_pk_bf16_f32 v2, v6, v7
	v_lshl_add_u64 v[6:7], v[132:133], 0, s[40:41]
	v_pk_mul_f32 v[44:45], v[44:45], v[34:35]
	v_cvt_pk_bf16_f32 v35, v40, v41
	v_lshl_add_u64 v[40:41], s[4:5], 0, v[38:39]
	v_cvt_pk_bf16_f32 v3, v8, v9
	v_lshl_add_u64 v[8:9], s[4:5], 0, v[6:7]
	v_cvt_pk_bf16_f32 v34, v42, v43
	v_cvt_pk_bf16_f32 v37, v44, v45
	v_lshl_add_u64 v[40:41], v[40:41], 0, v[130:131]
	v_lshl_add_u64 v[38:39], s[14:15], 0, v[38:39]
	v_cvt_pk_bf16_f32 v4, v10, v11
	v_cvt_pk_bf16_f32 v5, v12, v13
	v_lshl_add_u64 v[8:9], v[8:9], 0, v[130:131]
	v_lshl_add_u64 v[6:7], s[14:15], 0, v[6:7]
	global_store_dwordx4 v[40:41], v[34:37], off
	v_lshl_add_u64 v[38:39], v[38:39], 0, v[130:131]
	global_store_dwordx4 v[8:9], v[2:5], off
	v_cvt_pk_bf16_f32 v34, v51, v50
	v_cvt_pk_bf16_f32 v35, v47, v48
	v_cvt_pk_bf16_f32 v36, v52, v46
	v_cvt_pk_bf16_f32 v37, v49, v53
	v_cvt_pk_bf16_f32 v2, v19, v18
	v_cvt_pk_bf16_f32 v3, v15, v16
	v_cvt_pk_bf16_f32 v4, v22, v14
	v_cvt_pk_bf16_f32 v5, v17, v20
	v_lshl_add_u64 v[6:7], v[6:7], 0, v[130:131]
	global_store_dwordx4 v[38:39], v[34:37], off
	global_store_dwordx4 v[6:7], v[2:5], off
	s_cbranch_vccz .LBB0_730
	s_cmp_eq_u32 s101, 1
	s_cbranch_scc0 .Lnodx_p1b
	s_barrier
	s_mov_b32 s101, 0

;     __device__ __forceinline__ bool next(int i, Unit& u) const { const int L = i * G + (G - 1 - c); if (L >= 3264) return false; tile_map(L, 136, 24, u.pm, u.pn); u.pn += 4;     u.kh = 0; u.type = 0; return true; }
;     __device__ __forceinline__ bool next(int i, Unit& u) const { const int L = i * G + (G - 1 - c); if (L >= 2176) return false; tile_map(L, 136, 16, u.pm, u.pn); u.pn += 24; u.kh = 0; u.type = 0; return true; }
;     __device__ __forceinline__ bool next(int i, Unit& u) const { const int L = (i >> 1) * G + c; if (L >= 1024) return false; tile_map(L, 128, 8, u.pm, u.pn); u.kh = i & 1; u.type = 0; return true; }
;     __device__ __forceinline__ bool next(int i, Unit& u) const { const int L = (i >> 1) * G + c; if (L >= 128) return false; tile_map(L, 16, 8, u.pm, u.pn); u.pm += 120; u.kh = i & 1; u.type = 1; return true; }
; template <int MODE  , class Epi, class Sched>
; __device__ __forceinline__ void gemm_phase(LAS unsigned char* lds, const GemmDesc g, const Sched& S, const Epi& E) {
;     ...
;     for (;;) {
;         const bool has_next = S.next(ui + 1, nxt);
;         const char* nA = has_next ? (const char*)(nxt.type ? g.A2 : g.A) + (size_t)nxt.pm * 2 * hstepA + (size_t)nxt.kh * khb : cA;
;         const char* nB = has_next ? (const char*)(nxt.type ? g.Bt2 : g.Bt) + (size_t)nxt.pn * 2 * hstepB + (size_t)nxt.kh * khb : cB;
.LBB0_802:
	s_mov_b64 s[44:45], 0
.LBB0_803:
	s_and_b64 vcc, exec, s[44:45]
	s_mov_b32 s65, s20
	s_mov_b32 s66, s62
	s_mov_b32 s64, s63
	s_mov_b64 s[44:45], s[2:3]
	s_mov_b64 s[42:43], s[34:35]
	s_cbranch_vccnz .LBB0_821

; #define G_STAGE(bufoff, gbase, voff) do { _Pragma("unroll") for (int _i = 0; _i < 2; ++_i) \
;         __builtin_amdgcn_global_load_lds((const unsigned*)((const char*)(gbase) + (voff)[_i]), (LAS unsigned*)(lds + (bufoff) + ldsw + _i * 8192), 16, 0, 0); } while (0)
; #define G_WAIT_L(n) asm volatile("s_waitcnt lgkmcnt(" #n ")" ::: "memory")
; #define G_BAR __builtin_amdgcn_s_barrier()
; #define G_SCHED __builtin_amdgcn_sched_barrier(0)
; template <int MODE  , class Epi, class Sched>
; __device__ __forceinline__ void gemm_phase(LAS unsigned char* lds, const GemmDesc g, const Sched& S, const Epi& E) {
;     ...
;         for (int t = 0; t < nt; t += 2) {
;             const bool last = (t == nt - 2);
;             const char* a1 = cA + (size_t)(t + 1) * kstep;
;             const char* a2 = last ? nA : cA + (size_t)(t + 2) * kstep; const char* b2 = last ? nB : cB + (size_t)(t + 2) * kstep;
;             const char* a3 = a2 + kstep; const char* b3 = b2 + kstep;
;             G_LDB(B0, 0, 0); G_SCHED; G_LDA(At, 0, 0); G_STAGE(G_SA(1, 1), a1 + hstepA, voffA);
;             G_WAIT_L(8); G_BAR; G_WAIT_L(0); G_MMA(0, 0, At, B0); G_BAR; G_SCHED;
;             G_LDB(B1, 0, 1); G_STAGE(G_SB(0, 0), b2, voffB);
;             G_BAR; G_WAIT_L(0); G_MMA(0, 1, At, B1); G_BAR;
.LBB0_814:
	s_add_u32 s21, s44, 0x100
	s_addc_u32 s67, s45, 0
	s_mov_b32 s68, -2
	s_cmp_eq_u32 s101, 1
	s_cbranch_scc0 .Lnodb_sa
	s_barrier
	s_mov_b32 s101, 0
.Lnodb_sa:
.LBB0_815:
	v_add_u32_e32 v142, s58, v172
	ds_read_b128 v[130:133], v142
	ds_read_b128 v[134:137], v142 offset:1024
	ds_read_b128 v[138:141], v142 offset:2048
	ds_read_b128 v[142:145], v142 offset:3072
	s_add_u32 s44, s42, 0x100
	s_addc_u32 s45, s43, 0
	s_cmp_eq_u32 s68, 12
	s_cselect_b32 s49, s35, s45
	s_cselect_b32 s48, s34, s44
	s_cselect_b32 s47, s3, s67
	s_cselect_b32 s46, s2, s21
	v_lshl_add_u64 v[170:171], s[42:43], 0, v[154:155]
	s_add_i32 m0, s52, 0xc000
	ds_read_b128 v[158:161], v174
	ds_read_b128 v[162:165], v174 offset:1024
	ds_read_b128 v[166:169], v174 offset:2048
	ds_read_b128 v[176:179], v174 offset:3072
	ds_read_b128 v[180:183], v174 offset:4096
	ds_read_b128 v[184:187], v174 offset:5120
	ds_read_b128 v[192:195], v174 offset:6144
	ds_read_b128 v[196:199], v174 offset:7168
	global_load_lds_dwordx4 v[170:171], off
	v_lshl_add_u64 v[170:171], s[42:43], 0, v[156:157]
	s_add_i32 m0, s52, 0xe000
	s_nop 0
	global_load_lds_dwordx4 v[170:171], off
	s_waitcnt lgkmcnt(8)
	s_barrier
	s_waitcnt lgkmcnt(0)
	s_setprio 1
	s_waitcnt lgkmcnt(0)
	v_mfma_f32_16x16x32_bf16 v[126:129], v[130:133], v[158:161], v[126:129]
	v_mfma_f32_16x16x32_bf16 v[122:125], v[138:141], v[158:161], v[122:125]
	v_mfma_f32_16x16x32_bf16 v[118:121], v[130:133], v[166:169], v[118:121]
	v_mfma_f32_16x16x32_bf16 v[114:117], v[138:141], v[166:169], v[114:117]
	v_mfma_f32_16x16x32_bf16 v[110:113], v[130:133], v[180:183], v[110:113]
	v_mfma_f32_16x16x32_bf16 v[106:109], v[138:141], v[180:183], v[106:109]
	v_mfma_f32_16x16x32_bf16 v[102:105], v[130:133], v[192:195], v[102:105]
	v_mfma_f32_16x16x32_bf16 v[98:101], v[138:141], v[192:195], v[98:101]
	v_mfma_f32_16x16x32_bf16 v[126:129], v[134:137], v[162:165], v[126:129]
	v_mfma_f32_16x16x32_bf16 v[122:125], v[142:145], v[162:165], v[122:125]
	v_mfma_f32_16x16x32_bf16 v[118:121], v[134:137], v[176:179], v[118:121]
	v_mfma_f32_16x16x32_bf16 v[114:117], v[142:145], v[176:179], v[114:117]
	v_mfma_f32_16x16x32_bf16 v[110:113], v[134:137], v[184:187], v[110:113]
	v_mfma_f32_16x16x32_bf16 v[106:109], v[142:145], v[184:187], v[106:109]
	v_mfma_f32_16x16x32_bf16 v[102:105], v[134:137], v[196:199], v[102:105]
	v_mfma_f32_16x16x32_bf16 v[98:101], v[142:145], v[196:199], v[98:101]
	s_setprio 0
	s_barrier
	v_add_u32_e32 v170, s59, v172
	s_add_i32 s0, s58, s51
	ds_read_b128 v[200:203], v170
	ds_read_b128 v[204:207], v170 offset:1024
	ds_read_b128 v[208:211], v170 offset:2048
	ds_read_b128 v[212:215], v170 offset:3072
	v_lshl_add_u64 v[170:171], s[46:47], 0, v[148:149]
	s_mov_b32 m0, s0
	v_lshl_add_u64 v[188:189], s[46:47], 0, v[152:153]
	global_load_lds_dwordx4 v[170:171], off
	s_add_i32 m0, s0, 0x2000
	s_nop 0
	global_load_lds_dwordx4 v[188:189], off
	s_barrier
	s_waitcnt lgkmcnt(0)
	s_setprio 1
	s_waitcnt lgkmcnt(0)
	v_mfma_f32_16x16x32_bf16 v[94:97], v[200:203], v[158:161], v[94:97]
	v_mfma_f32_16x16x32_bf16 v[90:93], v[208:211], v[158:161], v[90:93]
	v_mfma_f32_16x16x32_bf16 v[86:89], v[200:203], v[166:169], v[86:89]
	v_mfma_f32_16x16x32_bf16 v[82:85], v[208:211], v[166:169], v[82:85]
	v_mfma_f32_16x16x32_bf16 v[78:81], v[200:203], v[180:183], v[78:81]
	v_mfma_f32_16x16x32_bf16 v[74:77], v[208:211], v[180:183], v[74:77]
	v_mfma_f32_16x16x32_bf16 v[70:73], v[200:203], v[192:195], v[70:73]
	v_mfma_f32_16x16x32_bf16 v[66:69], v[208:211], v[192:195], v[66:69]
	v_mfma_f32_16x16x32_bf16 v[94:97], v[204:207], v[162:165], v[94:97]
	v_mfma_f32_16x16x32_bf16 v[90:93], v[212:215], v[162:165], v[90:93]
	v_mfma_f32_16x16x32_bf16 v[86:89], v[204:207], v[176:179], v[86:89]
	v_mfma_f32_16x16x32_bf16 v[82:85], v[212:215], v[176:179], v[82:85]
	v_mfma_f32_16x16x32_bf16 v[78:81], v[204:207], v[184:187], v[78:81]
	v_mfma_f32_16x16x32_bf16 v[74:77], v[212:215], v[184:187], v[74:77]
	v_mfma_f32_16x16x32_bf16 v[70:73], v[204:207], v[196:199], v[70:73]
	v_mfma_f32_16x16x32_bf16 v[66:69], v[212:215], v[196:199], v[66:69]
	s_setprio 0
	s_mov_b32 m0, s52
	v_lshl_add_u64 v[216:217], s[48:49], 0, v[146:147]
	s_barrier
	ds_read_b128 v[158:161], v174 offset:16384
	ds_read_b128 v[162:165], v174 offset:17408
	ds_read_b128 v[166:169], v174 offset:18432
	ds_read_b128 v[176:179], v174 offset:19456
	ds_read_b128 v[180:183], v174 offset:20480
	ds_read_b128 v[184:187], v174 offset:21504
	ds_read_b128 v[192:195], v174 offset:22528
	ds_read_b128 v[196:199], v174 offset:23552
	global_load_lds_dwordx4 v[216:217], off
	v_lshl_add_u64 v[218:219], s[48:49], 0, v[150:151]
	s_mov_b32 m0, s53
	s_nop 0
	global_load_lds_dwordx4 v[218:219], off
	s_barrier
	s_waitcnt lgkmcnt(0)
	s_setprio 1
	s_waitcnt lgkmcnt(0)
	v_mfma_f32_16x16x32_bf16 v[62:65], v[130:133], v[158:161], v[62:65]
	v_mfma_f32_16x16x32_bf16 v[58:61], v[138:141], v[158:161], v[58:61]
	v_mfma_f32_16x16x32_bf16 v[54:57], v[130:133], v[166:169], v[54:57]
	v_mfma_f32_16x16x32_bf16 v[50:53], v[138:141], v[166:169], v[50:53]
	v_mfma_f32_16x16x32_bf16 v[46:49], v[130:133], v[180:183], v[46:49]
	v_mfma_f32_16x16x32_bf16 v[42:45], v[138:141], v[180:183], v[42:45]
	v_mfma_f32_16x16x32_bf16 v[38:41], v[130:133], v[192:195], v[38:41]
	v_mfma_f32_16x16x32_bf16 v[34:37], v[138:141], v[192:195], v[34:37]
	v_mfma_f32_16x16x32_bf16 v[62:65], v[134:137], v[162:165], v[62:65]
	v_mfma_f32_16x16x32_bf16 v[58:61], v[142:145], v[162:165], v[58:61]
	v_mfma_f32_16x16x32_bf16 v[54:57], v[134:137], v[176:179], v[54:57]
	v_mfma_f32_16x16x32_bf16 v[50:53], v[142:145], v[176:179], v[50:53]
	v_mfma_f32_16x16x32_bf16 v[46:49], v[134:137], v[184:187], v[46:49]
	v_mfma_f32_16x16x32_bf16 v[42:45], v[142:145], v[184:187], v[42:45]
	v_mfma_f32_16x16x32_bf16 v[38:41], v[134:137], v[196:199], v[38:41]
	v_mfma_f32_16x16x32_bf16 v[34:37], v[142:145], v[196:199], v[34:37]
	s_setprio 0
	s_barrier
; #define G_STAGE(bufoff, gbase, voff) do { _Pragma("unroll") for (int _i = 0; _i < 2; ++_i) \
;         __builtin_amdgcn_global_load_lds((const unsigned*)((const char*)(gbase) + (voff)[_i]), (LAS unsigned*)(lds + (bufoff) + ldsw + _i * 8192), 16, 0, 0); } while (0)
; #define G_WAIT_V(n) asm volatile("s_waitcnt vmcnt(" #n ")" ::: "memory")
; #define G_WAIT_L(n) asm volatile("s_waitcnt lgkmcnt(" #n ")" ::: "memory")
; #define G_BAR __builtin_amdgcn_s_barrier()
; #define G_SCHED __builtin_amdgcn_sched_barrier(0)
; template <int MODE  , class Epi, class Sched>
; __device__ __forceinline__ void gemm_phase(LAS unsigned char* lds, const GemmDesc g, const Sched& S, const Epi& E) {
;     ...
;             G_BAR; G_WAIT_L(0); G_MMA(1, 0, At, B0); G_BAR; G_SCHED;
;             G_STAGE(G_SB(0, 1), b2 + hstepB, voffB);
;             G_WAIT_V(6); G_BAR; G_MMA(1, 1, At, B1); G_BAR;
;             G_LDB(B0, 1, 0); G_SCHED; G_LDA(At, 1, 0); G_STAGE(G_SA(0, 1), a2 + hstepA, voffA);
;             G_WAIT_L(8); G_BAR; G_WAIT_L(0); G_MMA(0, 0, At, B0); G_BAR; G_SCHED;
	s_add_u32 s0, s46, 0x84000
	s_addc_u32 s1, s47, 0
	s_add_i32 s10, s59, s51
	v_lshl_add_u64 v[130:131], s[0:1], 0, v[148:149]
	s_mov_b32 m0, s10
	s_nop 0
	global_load_lds_dwordx4 v[130:131], off
	v_lshl_add_u64 v[130:131], s[0:1], 0, v[152:153]
	s_add_i32 m0, s10, 0x2000
	s_nop 0
	global_load_lds_dwordx4 v[130:131], off
	s_waitcnt vmcnt(6)
	s_barrier
	s_setprio 1
	v_mfma_f32_16x16x32_bf16 v[30:33], v[200:203], v[158:161], v[30:33]
	v_mfma_f32_16x16x32_bf16 v[26:29], v[208:211], v[158:161], v[26:29]
	v_mfma_f32_16x16x32_bf16 v[22:25], v[200:203], v[166:169], v[22:25]
	v_mfma_f32_16x16x32_bf16 v[18:21], v[208:211], v[166:169], v[18:21]
	v_mfma_f32_16x16x32_bf16 v[14:17], v[200:203], v[180:183], v[14:17]
	v_mfma_f32_16x16x32_bf16 v[10:13], v[208:211], v[180:183], v[10:13]
	v_mfma_f32_16x16x32_bf16 v[6:9], v[200:203], v[192:195], v[6:9]
	v_mfma_f32_16x16x32_bf16 v[2:5], v[208:211], v[192:195], v[2:5]
	v_mfma_f32_16x16x32_bf16 v[30:33], v[204:207], v[162:165], v[30:33]
	v_mfma_f32_16x16x32_bf16 v[26:29], v[212:215], v[162:165], v[26:29]
	v_mfma_f32_16x16x32_bf16 v[22:25], v[204:207], v[176:179], v[22:25]
	v_mfma_f32_16x16x32_bf16 v[18:21], v[212:215], v[176:179], v[18:21]
	v_mfma_f32_16x16x32_bf16 v[14:17], v[204:207], v[184:187], v[14:17]
	v_mfma_f32_16x16x32_bf16 v[10:13], v[212:215], v[184:187], v[10:13]
	v_mfma_f32_16x16x32_bf16 v[6:9], v[204:207], v[196:199], v[6:9]
	v_mfma_f32_16x16x32_bf16 v[2:5], v[212:215], v[196:199], v[2:5]
	s_setprio 0
	s_add_i32 s10, 0, 0x18000
	v_add_u32_e32 v142, s10, v172
	s_barrier
	ds_read_b128 v[130:133], v142
	ds_read_b128 v[134:137], v142 offset:1024
	ds_read_b128 v[138:141], v142 offset:2048
	ds_read_b128 v[142:145], v142 offset:3072
	s_add_u32 s0, s48, 0x84000
	s_addc_u32 s1, s49, 0
	s_mov_b32 m0, s54
	v_lshl_add_u64 v[200:201], s[0:1], 0, v[146:147]
	ds_read_b128 v[158:161], v174 offset:32768
	ds_read_b128 v[162:165], v174 offset:33792
	ds_read_b128 v[166:169], v174 offset:34816
	ds_read_b128 v[176:179], v174 offset:35840
	ds_read_b128 v[180:183], v174 offset:36864
	ds_read_b128 v[184:187], v174 offset:37888
	ds_read_b128 v[192:195], v174 offset:38912
	ds_read_b128 v[196:199], v174 offset:39936
	global_load_lds_dwordx4 v[200:201], off
	v_lshl_add_u64 v[200:201], s[0:1], 0, v[150:151]
	s_mov_b32 m0, s55
	s_nop 0
	global_load_lds_dwordx4 v[200:201], off
	s_waitcnt lgkmcnt(8)
	s_barrier
	s_waitcnt lgkmcnt(0)
	s_setprio 1
	s_waitcnt lgkmcnt(0)
	v_mfma_f32_16x16x32_bf16 v[126:129], v[130:133], v[158:161], v[126:129]
	v_mfma_f32_16x16x32_bf16 v[122:125], v[138:141], v[158:161], v[122:125]
	v_mfma_f32_16x16x32_bf16 v[118:121], v[130:133], v[166:169], v[118:121]
	v_mfma_f32_16x16x32_bf16 v[114:117], v[138:141], v[166:169], v[114:117]
	v_mfma_f32_16x16x32_bf16 v[110:113], v[130:133], v[180:183], v[110:113]
	v_mfma_f32_16x16x32_bf16 v[106:109], v[138:141], v[180:183], v[106:109]
	v_mfma_f32_16x16x32_bf16 v[102:105], v[130:133], v[192:195], v[102:105]
	v_mfma_f32_16x16x32_bf16 v[98:101], v[138:141], v[192:195], v[98:101]
	v_mfma_f32_16x16x32_bf16 v[126:129], v[134:137], v[162:165], v[126:129]
	v_mfma_f32_16x16x32_bf16 v[122:125], v[142:145], v[162:165], v[122:125]
	v_mfma_f32_16x16x32_bf16 v[118:121], v[134:137], v[176:179], v[118:121]
	v_mfma_f32_16x16x32_bf16 v[114:117], v[142:145], v[176:179], v[114:117]
	v_mfma_f32_16x16x32_bf16 v[110:113], v[134:137], v[184:187], v[110:113]
	v_mfma_f32_16x16x32_bf16 v[106:109], v[142:145], v[184:187], v[106:109]
	v_mfma_f32_16x16x32_bf16 v[102:105], v[134:137], v[196:199], v[102:105]
	v_mfma_f32_16x16x32_bf16 v[98:101], v[142:145], v[196:199], v[98:101]
	s_setprio 0
	s_barrier
	s_add_i32 s11, 0, 0x1c000
	s_add_i32 s0, s10, s51
	v_add_u32_e32 v175, s11, v172
	v_lshl_add_u64 v[170:171], v[170:171], 0, s[18:19]
	s_mov_b32 m0, s0
	ds_read_b128 v[200:203], v175
	ds_read_b128 v[204:207], v175 offset:1024
	ds_read_b128 v[208:211], v175 offset:2048
	ds_read_b128 v[212:215], v175 offset:3072
	global_load_lds_dwordx4 v[170:171], off
	v_lshl_add_u64 v[170:171], v[188:189], 0, s[18:19]
	s_add_i32 m0, s0, 0x2000
	s_nop 0
	global_load_lds_dwordx4 v[170:171], off
	s_barrier
; #define G_STAGE(bufoff, gbase, voff) do { _Pragma("unroll") for (int _i = 0; _i < 2; ++_i) \
;         __builtin_amdgcn_global_load_lds((const unsigned*)((const char*)(gbase) + (voff)[_i]), (LAS unsigned*)(lds + (bufoff) + ldsw + _i * 8192), 16, 0, 0); } while (0)
; #define G_WAIT_V(n) asm volatile("s_waitcnt vmcnt(" #n ")" ::: "memory")
; #define G_WAIT_L(n) asm volatile("s_waitcnt lgkmcnt(" #n ")" ::: "memory")
; #define G_BAR __builtin_amdgcn_s_barrier()
; #define G_SCHED __builtin_amdgcn_sched_barrier(0)
; template <int MODE  , class Epi, class Sched>
; __device__ __forceinline__ void gemm_phase(LAS unsigned char* lds, const GemmDesc g, const Sched& S, const Epi& E) {
;     ...
;             G_LDB(B1, 1, 1); G_STAGE(G_SB(1, 0), b3, voffB);
;             G_BAR; G_WAIT_L(0); G_MMA(0, 1, At, B1); G_BAR;
;             G_LDA(At, 1, 1); G_STAGE(G_SA(1, 0), a3, voffA);
;             G_BAR; G_WAIT_L(0); G_MMA(1, 0, At, B0); G_BAR; G_SCHED;
;             G_STAGE(G_SB(1, 1), b3 + hstepB, voffB);
;             G_WAIT_V(6); G_BAR; G_MMA(1, 1, At, B1); G_BAR;
	s_waitcnt lgkmcnt(0)
	s_setprio 1
	s_waitcnt lgkmcnt(0)
	v_mfma_f32_16x16x32_bf16 v[94:97], v[200:203], v[158:161], v[94:97]
	v_mfma_f32_16x16x32_bf16 v[90:93], v[208:211], v[158:161], v[90:93]
	v_mfma_f32_16x16x32_bf16 v[86:89], v[200:203], v[166:169], v[86:89]
	v_mfma_f32_16x16x32_bf16 v[82:85], v[208:211], v[166:169], v[82:85]
	v_mfma_f32_16x16x32_bf16 v[78:81], v[200:203], v[180:183], v[78:81]
	v_mfma_f32_16x16x32_bf16 v[74:77], v[208:211], v[180:183], v[74:77]
	v_mfma_f32_16x16x32_bf16 v[70:73], v[200:203], v[192:195], v[70:73]
	v_mfma_f32_16x16x32_bf16 v[66:69], v[208:211], v[192:195], v[66:69]
	v_mfma_f32_16x16x32_bf16 v[94:97], v[204:207], v[162:165], v[94:97]
	v_mfma_f32_16x16x32_bf16 v[90:93], v[212:215], v[162:165], v[90:93]
	v_mfma_f32_16x16x32_bf16 v[86:89], v[204:207], v[176:179], v[86:89]
	v_mfma_f32_16x16x32_bf16 v[82:85], v[212:215], v[176:179], v[82:85]
	v_mfma_f32_16x16x32_bf16 v[78:81], v[204:207], v[184:187], v[78:81]
	v_mfma_f32_16x16x32_bf16 v[74:77], v[212:215], v[184:187], v[74:77]
	v_mfma_f32_16x16x32_bf16 v[70:73], v[204:207], v[196:199], v[70:73]
	v_mfma_f32_16x16x32_bf16 v[66:69], v[212:215], v[196:199], v[66:69]
	s_setprio 0
	s_mov_b32 m0, s56
	v_lshl_add_u64 v[170:171], v[216:217], 0, s[18:19]
	s_barrier
	ds_read_b128 v[158:161], v174 offset:49152
	ds_read_b128 v[162:165], v174 offset:50176
	ds_read_b128 v[166:169], v174 offset:51200
	ds_read_b128 v[176:179], v174 offset:52224
	ds_read_b128 v[180:183], v174 offset:53248
	ds_read_b128 v[184:187], v174 offset:54272
	ds_read_b128 v[192:195], v174 offset:55296
	ds_read_b128 v[196:199], v174 offset:56320
	global_load_lds_dwordx4 v[170:171], off
	v_lshl_add_u64 v[170:171], v[218:219], 0, s[18:19]
	s_mov_b32 m0, s57
	s_nop 0
	global_load_lds_dwordx4 v[170:171], off
	s_barrier
	s_waitcnt lgkmcnt(0)
	s_setprio 1
	s_waitcnt lgkmcnt(0)
	v_mfma_f32_16x16x32_bf16 v[62:65], v[130:133], v[158:161], v[62:65]
	v_mfma_f32_16x16x32_bf16 v[58:61], v[138:141], v[158:161], v[58:61]
	v_mfma_f32_16x16x32_bf16 v[54:57], v[130:133], v[166:169], v[54:57]
	v_mfma_f32_16x16x32_bf16 v[50:53], v[138:141], v[166:169], v[50:53]
	v_mfma_f32_16x16x32_bf16 v[46:49], v[130:133], v[180:183], v[46:49]
	v_mfma_f32_16x16x32_bf16 v[42:45], v[138:141], v[180:183], v[42:45]
	v_mfma_f32_16x16x32_bf16 v[38:41], v[130:133], v[192:195], v[38:41]
	v_mfma_f32_16x16x32_bf16 v[34:37], v[138:141], v[192:195], v[34:37]
	v_mfma_f32_16x16x32_bf16 v[62:65], v[134:137], v[162:165], v[62:65]
	v_mfma_f32_16x16x32_bf16 v[58:61], v[142:145], v[162:165], v[58:61]
	v_mfma_f32_16x16x32_bf16 v[54:57], v[134:137], v[176:179], v[54:57]
	v_mfma_f32_16x16x32_bf16 v[50:53], v[142:145], v[176:179], v[50:53]
	v_mfma_f32_16x16x32_bf16 v[46:49], v[134:137], v[184:187], v[46:49]
	v_mfma_f32_16x16x32_bf16 v[42:45], v[142:145], v[184:187], v[42:45]
	v_mfma_f32_16x16x32_bf16 v[38:41], v[134:137], v[196:199], v[38:41]
	v_mfma_f32_16x16x32_bf16 v[34:37], v[142:145], v[196:199], v[34:37]
	s_setprio 0
	s_barrier
	s_add_u32 s0, s46, 0x84080
	s_addc_u32 s1, s47, 0
	s_add_i32 s10, s11, s51
	v_lshl_add_u64 v[130:131], s[0:1], 0, v[148:149]
	s_mov_b32 m0, s10
	s_nop 0
	global_load_lds_dwordx4 v[130:131], off
	v_lshl_add_u64 v[130:131], s[0:1], 0, v[152:153]
	s_add_i32 m0, s10, 0x2000
	s_nop 0
	global_load_lds_dwordx4 v[130:131], off
	s_waitcnt vmcnt(6)
	s_barrier
	s_setprio 1
	v_mfma_f32_16x16x32_bf16 v[30:33], v[200:203], v[158:161], v[30:33]
	v_mfma_f32_16x16x32_bf16 v[26:29], v[208:211], v[158:161], v[26:29]
	v_mfma_f32_16x16x32_bf16 v[22:25], v[200:203], v[166:169], v[22:25]
	v_mfma_f32_16x16x32_bf16 v[18:21], v[208:211], v[166:169], v[18:21]
	v_mfma_f32_16x16x32_bf16 v[14:17], v[200:203], v[180:183], v[14:17]
	v_mfma_f32_16x16x32_bf16 v[10:13], v[208:211], v[180:183], v[10:13]
	v_mfma_f32_16x16x32_bf16 v[6:9], v[200:203], v[192:195], v[6:9]
	v_mfma_f32_16x16x32_bf16 v[2:5], v[208:211], v[192:195], v[2:5]
	v_mfma_f32_16x16x32_bf16 v[30:33], v[204:207], v[162:165], v[30:33]
	v_mfma_f32_16x16x32_bf16 v[26:29], v[212:215], v[162:165], v[26:29]
	v_mfma_f32_16x16x32_bf16 v[22:25], v[204:207], v[176:179], v[22:25]
	v_mfma_f32_16x16x32_bf16 v[18:21], v[212:215], v[176:179], v[18:21]
	v_mfma_f32_16x16x32_bf16 v[14:17], v[204:207], v[184:187], v[14:17]
	v_mfma_f32_16x16x32_bf16 v[10:13], v[212:215], v[184:187], v[10:13]
	v_mfma_f32_16x16x32_bf16 v[6:9], v[204:207], v[196:199], v[6:9]
	v_mfma_f32_16x16x32_bf16 v[2:5], v[212:215], v[196:199], v[2:5]
	s_setprio 0
	s_add_i32 s68, s68, 2
	s_add_u32 s21, s21, 0x100
	s_addc_u32 s67, s67, 0
	s_cmp_gt_u32 s68, 13
	s_mov_b64 s[42:43], s[44:45]
	s_cbranch_scc1 .Lkdone_sa
	s_barrier
	s_branch .LBB0_815
.Lkdone_sa:
	s_cmpk_gt_u32 s50, 0xff
	s_cselect_b32 s101, 1, 0
	s_cbranch_scc1 .Lkepi_sa
	s_barrier

;     __device__ __forceinline__ bool next(int i, Unit& u) const { const int L = i * G + (G - 1 - c); if (L >= 3264) return false; tile_map(L, 136, 24, u.pm, u.pn); u.pn += 4;     u.kh = 0; u.type = 0; return true; }
;     __device__ __forceinline__ bool next(int i, Unit& u) const { const int L = i * G + (G - 1 - c); if (L >= 2176) return false; tile_map(L, 136, 16, u.pm, u.pn); u.pn += 24; u.kh = 0; u.type = 0; return true; }
;     __device__ __forceinline__ bool next(int i, Unit& u) const { const int L = (i >> 1) * G + c; if (L >= 1024) return false; tile_map(L, 128, 8, u.pm, u.pn); u.kh = i & 1; u.type = 0; return true; }
;     __device__ __forceinline__ bool next(int i, Unit& u) const { const int L = (i >> 1) * G + c; if (L >= 128) return false; tile_map(L, 16, 8, u.pm, u.pn); u.pm += 120; u.kh = i & 1; u.type = 1; return true; }
; template <int MODE  , class Epi, class Sched>
; __device__ __forceinline__ void gemm_phase(LAS unsigned char* lds, const GemmDesc g, const Sched& S, const Epi& E) {
;     ...
;     for (;;) {
;         const bool has_next = S.next(ui + 1, nxt);
;         const char* nA = has_next ? (const char*)(nxt.type ? g.A2 : g.A) + (size_t)nxt.pm * 2 * hstepA + (size_t)nxt.kh * khb : cA;
;         const char* nB = has_next ? (const char*)(nxt.type ? g.Bt2 : g.Bt) + (size_t)nxt.pn * 2 * hstepB + (size_t)nxt.kh * khb : cB;
.LBB0_884:
	s_mov_b64 s[40:41], 0
.LBB0_885:
	s_and_b64 vcc, exec, s[40:41]
	s_mov_b32 s67, s63
	s_mov_b32 s66, s18
	s_mov_b32 s64, s61
	s_mov_b32 s65, s62
	s_mov_b64 s[42:43], s[2:3]
	s_mov_b64 s[40:41], s[20:21]
	s_cbranch_vccnz .LBB0_911

; #define G_STAGE(bufoff, gbase, voff) do { _Pragma("unroll") for (int _i = 0; _i < 2; ++_i) \
;         __builtin_amdgcn_global_load_lds((const unsigned*)((const char*)(gbase) + (voff)[_i]), (LAS unsigned*)(lds + (bufoff) + ldsw + _i * 8192), 16, 0, 0); } while (0)
; #define G_WAIT_L(n) asm volatile("s_waitcnt lgkmcnt(" #n ")" ::: "memory")
; #define G_BAR __builtin_amdgcn_s_barrier()
; #define G_SCHED __builtin_amdgcn_sched_barrier(0)
; template <int MODE  , class Epi, class Sched>
; __device__ __forceinline__ void gemm_phase(LAS unsigned char* lds, const GemmDesc g, const Sched& S, const Epi& E) {
;     ...
;         for (int t = 0; t < nt; t += 2) {
;             const bool last = (t == nt - 2);
;             const char* a1 = cA + (size_t)(t + 1) * kstep;
;             const char* a2 = last ? nA : cA + (size_t)(t + 2) * kstep; const char* b2 = last ? nB : cB + (size_t)(t + 2) * kstep;
;             const char* a3 = a2 + kstep; const char* b3 = b2 + kstep;
;             G_LDB(B0, 0, 0); G_SCHED; G_LDA(At, 0, 0); G_STAGE(G_SA(1, 1), a1 + hstepA, voffA);
;             G_WAIT_L(8); G_BAR; G_WAIT_L(0); G_MMA(0, 0, At, B0); G_BAR; G_SCHED;
;             G_LDB(B1, 0, 1); G_STAGE(G_SB(0, 0), b2, voffB);
;             G_BAR; G_WAIT_L(0); G_MMA(0, 1, At, B1); G_BAR;
.LBB0_896:
	s_add_u32 s19, s42, 0x100
	s_addc_u32 s70, s43, 0
	s_mov_b32 s71, -2
	s_cmp_eq_u32 s101, 1
	s_cbranch_scc0 .Lnodb_sb
	s_barrier
	s_mov_b32 s101, 0
.Lnodb_sb:
.LBB0_897:
	v_add_u32_e32 v142, s57, v174
	ds_read_b128 v[130:133], v142
	ds_read_b128 v[134:137], v142 offset:1024
	ds_read_b128 v[138:141], v142 offset:2048
	ds_read_b128 v[142:145], v142 offset:3072
	s_add_u32 s42, s40, 0x100
	s_addc_u32 s43, s41, 0
	s_cmp_eq_u32 s71, 12
	s_cselect_b32 s47, s21, s43
	s_cselect_b32 s46, s20, s42
	s_cselect_b32 s45, s3, s70
	s_cselect_b32 s44, s2, s19
	v_lshl_add_u64 v[196:197], s[40:41], 0, v[154:155]
	s_add_i32 m0, s50, 0xc000
	ds_read_b128 v[158:161], v176
	ds_read_b128 v[162:165], v176 offset:1024
	ds_read_b128 v[166:169], v176 offset:2048
	ds_read_b128 v[170:173], v176 offset:3072
	ds_read_b128 v[178:181], v176 offset:4096
	ds_read_b128 v[182:185], v176 offset:5120
	ds_read_b128 v[186:189], v176 offset:6144
	ds_read_b128 v[192:195], v176 offset:7168
	global_load_lds_dwordx4 v[196:197], off
	v_lshl_add_u64 v[196:197], s[40:41], 0, v[156:157]
	s_add_i32 m0, s50, 0xe000
	s_nop 0
	global_load_lds_dwordx4 v[196:197], off
	s_waitcnt lgkmcnt(8)
	s_barrier
	s_waitcnt lgkmcnt(0)
	s_setprio 1
	s_waitcnt lgkmcnt(0)
	v_mfma_f32_16x16x32_bf16 v[126:129], v[130:133], v[158:161], v[126:129]
	v_mfma_f32_16x16x32_bf16 v[122:125], v[138:141], v[158:161], v[122:125]
	v_mfma_f32_16x16x32_bf16 v[118:121], v[130:133], v[166:169], v[118:121]
	v_mfma_f32_16x16x32_bf16 v[114:117], v[138:141], v[166:169], v[114:117]
	v_mfma_f32_16x16x32_bf16 v[110:113], v[130:133], v[178:181], v[110:113]
	v_mfma_f32_16x16x32_bf16 v[106:109], v[138:141], v[178:181], v[106:109]
	v_mfma_f32_16x16x32_bf16 v[102:105], v[130:133], v[186:189], v[102:105]
	v_mfma_f32_16x16x32_bf16 v[98:101], v[138:141], v[186:189], v[98:101]
	v_mfma_f32_16x16x32_bf16 v[126:129], v[134:137], v[162:165], v[126:129]
	v_mfma_f32_16x16x32_bf16 v[122:125], v[142:145], v[162:165], v[122:125]
	v_mfma_f32_16x16x32_bf16 v[118:121], v[134:137], v[170:173], v[118:121]
	v_mfma_f32_16x16x32_bf16 v[114:117], v[142:145], v[170:173], v[114:117]
	v_mfma_f32_16x16x32_bf16 v[110:113], v[134:137], v[182:185], v[110:113]
	v_mfma_f32_16x16x32_bf16 v[106:109], v[142:145], v[182:185], v[106:109]
	v_mfma_f32_16x16x32_bf16 v[102:105], v[134:137], v[192:195], v[102:105]
	v_mfma_f32_16x16x32_bf16 v[98:101], v[142:145], v[192:195], v[98:101]
	s_setprio 0
	s_barrier
	s_add_i32 s0, s57, s49
	v_add_u32_e32 v177, s58, v174
	v_lshl_add_u64 v[212:213], s[44:45], 0, v[148:149]
	s_mov_b32 m0, s0
	ds_read_b128 v[196:199], v177
	ds_read_b128 v[200:203], v177 offset:1024
	ds_read_b128 v[204:207], v177 offset:2048
	ds_read_b128 v[208:211], v177 offset:3072
	global_load_lds_dwordx4 v[212:213], off
	v_lshl_add_u64 v[214:215], s[44:45], 0, v[152:153]
	s_add_i32 m0, s0, 0x2000
	s_nop 0
	global_load_lds_dwordx4 v[214:215], off
	s_barrier
	s_waitcnt lgkmcnt(0)
	s_setprio 1
	s_waitcnt lgkmcnt(0)
	v_mfma_f32_16x16x32_bf16 v[94:97], v[196:199], v[158:161], v[94:97]
	v_mfma_f32_16x16x32_bf16 v[90:93], v[204:207], v[158:161], v[90:93]
	v_mfma_f32_16x16x32_bf16 v[86:89], v[196:199], v[166:169], v[86:89]
	v_mfma_f32_16x16x32_bf16 v[82:85], v[204:207], v[166:169], v[82:85]
	v_mfma_f32_16x16x32_bf16 v[78:81], v[196:199], v[178:181], v[78:81]
	v_mfma_f32_16x16x32_bf16 v[74:77], v[204:207], v[178:181], v[74:77]
	v_mfma_f32_16x16x32_bf16 v[70:73], v[196:199], v[186:189], v[70:73]
	v_mfma_f32_16x16x32_bf16 v[66:69], v[204:207], v[186:189], v[66:69]
	v_mfma_f32_16x16x32_bf16 v[94:97], v[200:203], v[162:165], v[94:97]
	v_mfma_f32_16x16x32_bf16 v[90:93], v[208:211], v[162:165], v[90:93]
	v_mfma_f32_16x16x32_bf16 v[86:89], v[200:203], v[170:173], v[86:89]
	v_mfma_f32_16x16x32_bf16 v[82:85], v[208:211], v[170:173], v[82:85]
	v_mfma_f32_16x16x32_bf16 v[78:81], v[200:203], v[182:185], v[78:81]
	v_mfma_f32_16x16x32_bf16 v[74:77], v[208:211], v[182:185], v[74:77]
	v_mfma_f32_16x16x32_bf16 v[70:73], v[200:203], v[192:195], v[70:73]
	v_mfma_f32_16x16x32_bf16 v[66:69], v[208:211], v[192:195], v[66:69]
	s_setprio 0
	s_mov_b32 m0, s50
	v_lshl_add_u64 v[216:217], s[46:47], 0, v[146:147]
	s_barrier
	ds_read_b128 v[158:161], v176 offset:16384
	ds_read_b128 v[162:165], v176 offset:17408
	ds_read_b128 v[166:169], v176 offset:18432
	ds_read_b128 v[170:173], v176 offset:19456
	ds_read_b128 v[178:181], v176 offset:20480
	ds_read_b128 v[182:185], v176 offset:21504
	ds_read_b128 v[186:189], v176 offset:22528
	ds_read_b128 v[192:195], v176 offset:23552
	global_load_lds_dwordx4 v[216:217], off
	v_lshl_add_u64 v[218:219], s[46:47], 0, v[150:151]
	s_mov_b32 m0, s51
	s_nop 0
	global_load_lds_dwordx4 v[218:219], off
	s_barrier
	s_waitcnt lgkmcnt(0)
	s_setprio 1
	s_waitcnt lgkmcnt(0)
	v_mfma_f32_16x16x32_bf16 v[62:65], v[130:133], v[158:161], v[62:65]
	v_mfma_f32_16x16x32_bf16 v[58:61], v[138:141], v[158:161], v[58:61]
	v_mfma_f32_16x16x32_bf16 v[54:57], v[130:133], v[166:169], v[54:57]
	v_mfma_f32_16x16x32_bf16 v[50:53], v[138:141], v[166:169], v[50:53]
	v_mfma_f32_16x16x32_bf16 v[46:49], v[130:133], v[178:181], v[46:49]
	v_mfma_f32_16x16x32_bf16 v[42:45], v[138:141], v[178:181], v[42:45]
	v_mfma_f32_16x16x32_bf16 v[38:41], v[130:133], v[186:189], v[38:41]
	v_mfma_f32_16x16x32_bf16 v[34:37], v[138:141], v[186:189], v[34:37]
	v_mfma_f32_16x16x32_bf16 v[62:65], v[134:137], v[162:165], v[62:65]
	v_mfma_f32_16x16x32_bf16 v[58:61], v[142:145], v[162:165], v[58:61]
	v_mfma_f32_16x16x32_bf16 v[54:57], v[134:137], v[170:173], v[54:57]
	v_mfma_f32_16x16x32_bf16 v[50:53], v[142:145], v[170:173], v[50:53]
	v_mfma_f32_16x16x32_bf16 v[46:49], v[134:137], v[182:185], v[46:49]
	v_mfma_f32_16x16x32_bf16 v[42:45], v[142:145], v[182:185], v[42:45]
	v_mfma_f32_16x16x32_bf16 v[38:41], v[134:137], v[192:195], v[38:41]
	v_mfma_f32_16x16x32_bf16 v[34:37], v[142:145], v[192:195], v[34:37]
	s_setprio 0
	s_barrier
; #define G_STAGE(bufoff, gbase, voff) do { _Pragma("unroll") for (int _i = 0; _i < 2; ++_i) \
;         __builtin_amdgcn_global_load_lds((const unsigned*)((const char*)(gbase) + (voff)[_i]), (LAS unsigned*)(lds + (bufoff) + ldsw + _i * 8192), 16, 0, 0); } while (0)
; #define G_WAIT_V(n) asm volatile("s_waitcnt vmcnt(" #n ")" ::: "memory")
; #define G_WAIT_L(n) asm volatile("s_waitcnt lgkmcnt(" #n ")" ::: "memory")
; #define G_BAR __builtin_amdgcn_s_barrier()
; #define G_SCHED __builtin_amdgcn_sched_barrier(0)
; template <int MODE  , class Epi, class Sched>
; __device__ __forceinline__ void gemm_phase(LAS unsigned char* lds, const GemmDesc g, const Sched& S, const Epi& E) {
;     ...
;             G_BAR; G_WAIT_L(0); G_MMA(1, 0, At, B0); G_BAR; G_SCHED;
;             G_STAGE(G_SB(0, 1), b2 + hstepB, voffB);
;             G_WAIT_V(6); G_BAR; G_MMA(1, 1, At, B1); G_BAR;
;             G_LDB(B0, 1, 0); G_SCHED; G_LDA(At, 1, 0); G_STAGE(G_SA(0, 1), a2 + hstepA, voffA);
;             G_WAIT_L(8); G_BAR; G_WAIT_L(0); G_MMA(0, 0, At, B0); G_BAR; G_SCHED;
	s_add_u32 s0, s44, 0x84000
	s_addc_u32 s1, s45, 0
	s_add_i32 s10, s58, s49
	v_lshl_add_u64 v[130:131], s[0:1], 0, v[148:149]
	s_mov_b32 m0, s10
	s_nop 0
	global_load_lds_dwordx4 v[130:131], off
	v_lshl_add_u64 v[130:131], s[0:1], 0, v[152:153]
	s_add_i32 m0, s10, 0x2000
	s_nop 0
	global_load_lds_dwordx4 v[130:131], off
	s_waitcnt vmcnt(6)
	s_barrier
	s_setprio 1
	v_mfma_f32_16x16x32_bf16 v[30:33], v[196:199], v[158:161], v[30:33]
	v_mfma_f32_16x16x32_bf16 v[26:29], v[204:207], v[158:161], v[26:29]
	v_mfma_f32_16x16x32_bf16 v[22:25], v[196:199], v[166:169], v[22:25]
	v_mfma_f32_16x16x32_bf16 v[18:21], v[204:207], v[166:169], v[18:21]
	v_mfma_f32_16x16x32_bf16 v[14:17], v[196:199], v[178:181], v[14:17]
	v_mfma_f32_16x16x32_bf16 v[10:13], v[204:207], v[178:181], v[10:13]
	v_mfma_f32_16x16x32_bf16 v[6:9], v[196:199], v[186:189], v[6:9]
	v_mfma_f32_16x16x32_bf16 v[2:5], v[204:207], v[186:189], v[2:5]
	v_mfma_f32_16x16x32_bf16 v[30:33], v[200:203], v[162:165], v[30:33]
	v_mfma_f32_16x16x32_bf16 v[26:29], v[208:211], v[162:165], v[26:29]
	v_mfma_f32_16x16x32_bf16 v[22:25], v[200:203], v[170:173], v[22:25]
	v_mfma_f32_16x16x32_bf16 v[18:21], v[208:211], v[170:173], v[18:21]
	v_mfma_f32_16x16x32_bf16 v[14:17], v[200:203], v[182:185], v[14:17]
	v_mfma_f32_16x16x32_bf16 v[10:13], v[208:211], v[182:185], v[10:13]
	v_mfma_f32_16x16x32_bf16 v[6:9], v[200:203], v[192:195], v[6:9]
	v_mfma_f32_16x16x32_bf16 v[2:5], v[208:211], v[192:195], v[2:5]
	s_setprio 0
	s_add_i32 s10, 0, 0x18000
	v_add_u32_e32 v142, s10, v174
	s_barrier
	ds_read_b128 v[130:133], v142
	ds_read_b128 v[134:137], v142 offset:1024
	ds_read_b128 v[138:141], v142 offset:2048
	ds_read_b128 v[142:145], v142 offset:3072
	s_add_u32 s0, s46, 0x84000
	s_addc_u32 s1, s47, 0
	s_mov_b32 m0, s52
	v_lshl_add_u64 v[196:197], s[0:1], 0, v[146:147]
	ds_read_b128 v[158:161], v176 offset:32768
	ds_read_b128 v[162:165], v176 offset:33792
	ds_read_b128 v[166:169], v176 offset:34816
	ds_read_b128 v[170:173], v176 offset:35840
	ds_read_b128 v[178:181], v176 offset:36864
	ds_read_b128 v[182:185], v176 offset:37888
	ds_read_b128 v[186:189], v176 offset:38912
	ds_read_b128 v[192:195], v176 offset:39936
	global_load_lds_dwordx4 v[196:197], off
	v_lshl_add_u64 v[196:197], s[0:1], 0, v[150:151]
	s_mov_b32 m0, s53
	s_nop 0
	global_load_lds_dwordx4 v[196:197], off
	s_waitcnt lgkmcnt(8)
	s_barrier
	s_waitcnt lgkmcnt(0)
	s_setprio 1
	s_waitcnt lgkmcnt(0)
	v_mfma_f32_16x16x32_bf16 v[126:129], v[130:133], v[158:161], v[126:129]
	v_mfma_f32_16x16x32_bf16 v[122:125], v[138:141], v[158:161], v[122:125]
	v_mfma_f32_16x16x32_bf16 v[118:121], v[130:133], v[166:169], v[118:121]
	v_mfma_f32_16x16x32_bf16 v[114:117], v[138:141], v[166:169], v[114:117]
	v_mfma_f32_16x16x32_bf16 v[110:113], v[130:133], v[178:181], v[110:113]
	v_mfma_f32_16x16x32_bf16 v[106:109], v[138:141], v[178:181], v[106:109]
	v_mfma_f32_16x16x32_bf16 v[102:105], v[130:133], v[186:189], v[102:105]
	v_mfma_f32_16x16x32_bf16 v[98:101], v[138:141], v[186:189], v[98:101]
	v_mfma_f32_16x16x32_bf16 v[126:129], v[134:137], v[162:165], v[126:129]
	v_mfma_f32_16x16x32_bf16 v[122:125], v[142:145], v[162:165], v[122:125]
	v_mfma_f32_16x16x32_bf16 v[118:121], v[134:137], v[170:173], v[118:121]
	v_mfma_f32_16x16x32_bf16 v[114:117], v[142:145], v[170:173], v[114:117]
	v_mfma_f32_16x16x32_bf16 v[110:113], v[134:137], v[182:185], v[110:113]
	v_mfma_f32_16x16x32_bf16 v[106:109], v[142:145], v[182:185], v[106:109]
	v_mfma_f32_16x16x32_bf16 v[102:105], v[134:137], v[192:195], v[102:105]
	v_mfma_f32_16x16x32_bf16 v[98:101], v[142:145], v[192:195], v[98:101]
	s_setprio 0
	s_barrier
	s_add_i32 s11, 0, 0x1c000
	s_add_i32 s0, s10, s49
	v_add_u32_e32 v177, s11, v174
	v_lshl_add_u64 v[212:213], v[212:213], 0, s[16:17]
	s_mov_b32 m0, s0
	ds_read_b128 v[196:199], v177
	ds_read_b128 v[200:203], v177 offset:1024
	ds_read_b128 v[204:207], v177 offset:2048
	ds_read_b128 v[208:211], v177 offset:3072
	global_load_lds_dwordx4 v[212:213], off
	v_lshl_add_u64 v[212:213], v[214:215], 0, s[16:17]
	s_add_i32 m0, s0, 0x2000
	s_nop 0
	global_load_lds_dwordx4 v[212:213], off
	s_barrier
; #define G_STAGE(bufoff, gbase, voff) do { _Pragma("unroll") for (int _i = 0; _i < 2; ++_i) \
;         __builtin_amdgcn_global_load_lds((const unsigned*)((const char*)(gbase) + (voff)[_i]), (LAS unsigned*)(lds + (bufoff) + ldsw + _i * 8192), 16, 0, 0); } while (0)
; #define G_WAIT_V(n) asm volatile("s_waitcnt vmcnt(" #n ")" ::: "memory")
; #define G_WAIT_L(n) asm volatile("s_waitcnt lgkmcnt(" #n ")" ::: "memory")
; #define G_BAR __builtin_amdgcn_s_barrier()
; #define G_SCHED __builtin_amdgcn_sched_barrier(0)
; template <int MODE  , class Epi, class Sched>
; __device__ __forceinline__ void gemm_phase(LAS unsigned char* lds, const GemmDesc g, const Sched& S, const Epi& E) {
;     ...
;             G_LDB(B1, 1, 1); G_STAGE(G_SB(1, 0), b3, voffB);
;             G_BAR; G_WAIT_L(0); G_MMA(0, 1, At, B1); G_BAR;
;             G_LDA(At, 1, 1); G_STAGE(G_SA(1, 0), a3, voffA);
;             G_BAR; G_WAIT_L(0); G_MMA(1, 0, At, B0); G_BAR; G_SCHED;
;             G_STAGE(G_SB(1, 1), b3 + hstepB, voffB);
;             G_WAIT_V(6); G_BAR; G_MMA(1, 1, At, B1); G_BAR;
	s_waitcnt lgkmcnt(0)
	s_setprio 1
	s_waitcnt lgkmcnt(0)
	v_mfma_f32_16x16x32_bf16 v[94:97], v[196:199], v[158:161], v[94:97]
	v_mfma_f32_16x16x32_bf16 v[90:93], v[204:207], v[158:161], v[90:93]
	v_mfma_f32_16x16x32_bf16 v[86:89], v[196:199], v[166:169], v[86:89]
	v_mfma_f32_16x16x32_bf16 v[82:85], v[204:207], v[166:169], v[82:85]
	v_mfma_f32_16x16x32_bf16 v[78:81], v[196:199], v[178:181], v[78:81]
	v_mfma_f32_16x16x32_bf16 v[74:77], v[204:207], v[178:181], v[74:77]
	v_mfma_f32_16x16x32_bf16 v[70:73], v[196:199], v[186:189], v[70:73]
	v_mfma_f32_16x16x32_bf16 v[66:69], v[204:207], v[186:189], v[66:69]
	v_mfma_f32_16x16x32_bf16 v[94:97], v[200:203], v[162:165], v[94:97]
	v_mfma_f32_16x16x32_bf16 v[90:93], v[208:211], v[162:165], v[90:93]
	v_mfma_f32_16x16x32_bf16 v[86:89], v[200:203], v[170:173], v[86:89]
	v_mfma_f32_16x16x32_bf16 v[82:85], v[208:211], v[170:173], v[82:85]
	v_mfma_f32_16x16x32_bf16 v[78:81], v[200:203], v[182:185], v[78:81]
	v_mfma_f32_16x16x32_bf16 v[74:77], v[208:211], v[182:185], v[74:77]
	v_mfma_f32_16x16x32_bf16 v[70:73], v[200:203], v[192:195], v[70:73]
	v_mfma_f32_16x16x32_bf16 v[66:69], v[208:211], v[192:195], v[66:69]
	s_setprio 0
	s_mov_b32 m0, s54
	v_lshl_add_u64 v[212:213], v[216:217], 0, s[16:17]
	s_barrier
	ds_read_b128 v[158:161], v176 offset:49152
	ds_read_b128 v[162:165], v176 offset:50176
	ds_read_b128 v[166:169], v176 offset:51200
	ds_read_b128 v[170:173], v176 offset:52224
	ds_read_b128 v[178:181], v176 offset:53248
	ds_read_b128 v[182:185], v176 offset:54272
	ds_read_b128 v[186:189], v176 offset:55296
	ds_read_b128 v[192:195], v176 offset:56320
	global_load_lds_dwordx4 v[212:213], off
	v_lshl_add_u64 v[212:213], v[218:219], 0, s[16:17]
	s_mov_b32 m0, s55
	s_nop 0
	global_load_lds_dwordx4 v[212:213], off
	s_barrier
	s_waitcnt lgkmcnt(0)
	s_setprio 1
	s_waitcnt lgkmcnt(0)
	v_mfma_f32_16x16x32_bf16 v[62:65], v[130:133], v[158:161], v[62:65]
	v_mfma_f32_16x16x32_bf16 v[58:61], v[138:141], v[158:161], v[58:61]
	v_mfma_f32_16x16x32_bf16 v[54:57], v[130:133], v[166:169], v[54:57]
	v_mfma_f32_16x16x32_bf16 v[50:53], v[138:141], v[166:169], v[50:53]
	v_mfma_f32_16x16x32_bf16 v[46:49], v[130:133], v[178:181], v[46:49]
	v_mfma_f32_16x16x32_bf16 v[42:45], v[138:141], v[178:181], v[42:45]
	v_mfma_f32_16x16x32_bf16 v[38:41], v[130:133], v[186:189], v[38:41]
	v_mfma_f32_16x16x32_bf16 v[34:37], v[138:141], v[186:189], v[34:37]
	v_mfma_f32_16x16x32_bf16 v[62:65], v[134:137], v[162:165], v[62:65]
	v_mfma_f32_16x16x32_bf16 v[58:61], v[142:145], v[162:165], v[58:61]
	v_mfma_f32_16x16x32_bf16 v[54:57], v[134:137], v[170:173], v[54:57]
	v_mfma_f32_16x16x32_bf16 v[50:53], v[142:145], v[170:173], v[50:53]
	v_mfma_f32_16x16x32_bf16 v[46:49], v[134:137], v[182:185], v[46:49]
	v_mfma_f32_16x16x32_bf16 v[42:45], v[142:145], v[182:185], v[42:45]
	v_mfma_f32_16x16x32_bf16 v[38:41], v[134:137], v[192:195], v[38:41]
	v_mfma_f32_16x16x32_bf16 v[34:37], v[142:145], v[192:195], v[34:37]
	s_setprio 0
	s_barrier
	s_add_u32 s0, s44, 0x84080
	s_addc_u32 s1, s45, 0
	s_add_i32 s10, s11, s49
	v_lshl_add_u64 v[130:131], s[0:1], 0, v[148:149]
	s_mov_b32 m0, s10
	s_nop 0
	global_load_lds_dwordx4 v[130:131], off
	v_lshl_add_u64 v[130:131], s[0:1], 0, v[152:153]
	s_add_i32 m0, s10, 0x2000
	s_nop 0
	global_load_lds_dwordx4 v[130:131], off
	s_waitcnt vmcnt(6)
	s_barrier
	s_setprio 1
	v_mfma_f32_16x16x32_bf16 v[30:33], v[196:199], v[158:161], v[30:33]
	v_mfma_f32_16x16x32_bf16 v[26:29], v[204:207], v[158:161], v[26:29]
	v_mfma_f32_16x16x32_bf16 v[22:25], v[196:199], v[166:169], v[22:25]
	v_mfma_f32_16x16x32_bf16 v[18:21], v[204:207], v[166:169], v[18:21]
	v_mfma_f32_16x16x32_bf16 v[14:17], v[196:199], v[178:181], v[14:17]
	v_mfma_f32_16x16x32_bf16 v[10:13], v[204:207], v[178:181], v[10:13]
	v_mfma_f32_16x16x32_bf16 v[6:9], v[196:199], v[186:189], v[6:9]
	v_mfma_f32_16x16x32_bf16 v[2:5], v[204:207], v[186:189], v[2:5]
	v_mfma_f32_16x16x32_bf16 v[30:33], v[200:203], v[162:165], v[30:33]
	v_mfma_f32_16x16x32_bf16 v[26:29], v[208:211], v[162:165], v[26:29]
	v_mfma_f32_16x16x32_bf16 v[22:25], v[200:203], v[170:173], v[22:25]
	v_mfma_f32_16x16x32_bf16 v[18:21], v[208:211], v[170:173], v[18:21]
	v_mfma_f32_16x16x32_bf16 v[14:17], v[200:203], v[182:185], v[14:17]
	v_mfma_f32_16x16x32_bf16 v[10:13], v[208:211], v[182:185], v[10:13]
	v_mfma_f32_16x16x32_bf16 v[6:9], v[200:203], v[192:195], v[6:9]
	v_mfma_f32_16x16x32_bf16 v[2:5], v[208:211], v[192:195], v[2:5]
	s_setprio 0
	s_add_i32 s71, s71, 2
	s_add_u32 s19, s19, 0x100
	s_addc_u32 s70, s70, 0
	s_cmp_gt_u32 s71, 13
	s_mov_b64 s[40:41], s[42:43]
	s_cbranch_scc1 .Lkdone_sb
	s_barrier
	s_branch .LBB0_897
.Lkdone_sb:
	s_cmpk_gt_u32 s48, 0xff
	s_cselect_b32 s101, 1, 0
	s_cbranch_scc1 .Lkepi_sb
	s_barrier

;     __device__ __forceinline__ bool next(int i, Unit& u) const { const int L = i * G + (G - 1 - c); if (L >= 3264) return false; tile_map(L, 136, 24, u.pm, u.pn); u.pn += 4;     u.kh = 0; u.type = 0; return true; }
;     __device__ __forceinline__ bool next(int i, Unit& u) const { const int L = i * G + (G - 1 - c); if (L >= 2176) return false; tile_map(L, 136, 16, u.pm, u.pn); u.pn += 24; u.kh = 0; u.type = 0; return true; }
;     __device__ __forceinline__ bool next(int i, Unit& u) const { const int L = (i >> 1) * G + c; if (L >= 1024) return false; tile_map(L, 128, 8, u.pm, u.pn); u.kh = i & 1; u.type = 0; return true; }
;     __device__ __forceinline__ bool next(int i, Unit& u) const { const int L = (i >> 1) * G + c; if (L >= 128) return false; tile_map(L, 16, 8, u.pm, u.pn); u.pm += 120; u.kh = i & 1; u.type = 1; return true; }
; template <int MODE  , class Epi, class Sched>
; __device__ __forceinline__ void gemm_phase(LAS unsigned char* lds, const GemmDesc g, const Sched& S, const Epi& E) {
;     ...
;     for (;;) {
;         const bool has_next = S.next(ui + 1, nxt);
;         const char* nA = has_next ? (const char*)(nxt.type ? g.A2 : g.A) + (size_t)nxt.pm * 2 * hstepA + (size_t)nxt.kh * khb : cA;
;         const char* nB = has_next ? (const char*)(nxt.type ? g.Bt2 : g.Bt) + (size_t)nxt.pn * 2 * hstepB + (size_t)nxt.kh * khb : cB;
.LBB0_974:
	s_mov_b64 s[20:21], 0
.LBB0_975:
	s_and_b64 vcc, exec, s[20:21]
	s_mov_b32 s57, s14
	s_mov_b32 s58, s54
	s_mov_b32 s56, s55
	s_mov_b64 s[34:35], s[2:3]
	s_mov_b64 s[20:21], s[16:17]
	s_cbranch_vccnz .LBB0_993

; #define G_STAGE(bufoff, gbase, voff) do { _Pragma("unroll") for (int _i = 0; _i < 2; ++_i) \
;         __builtin_amdgcn_global_load_lds((const unsigned*)((const char*)(gbase) + (voff)[_i]), (LAS unsigned*)(lds + (bufoff) + ldsw + _i * 8192), 16, 0, 0); } while (0)
; #define G_WAIT_L(n) asm volatile("s_waitcnt lgkmcnt(" #n ")" ::: "memory")
; #define G_BAR __builtin_amdgcn_s_barrier()
; #define G_SCHED __builtin_amdgcn_sched_barrier(0)
; template <int MODE  , class Epi, class Sched>
; __device__ __forceinline__ void gemm_phase(LAS unsigned char* lds, const GemmDesc g, const Sched& S, const Epi& E) {
;     ...
;         for (int t = 0; t < nt; t += 2) {
;             const bool last = (t == nt - 2);
;             const char* a1 = cA + (size_t)(t + 1) * kstep;
;             const char* a2 = last ? nA : cA + (size_t)(t + 2) * kstep; const char* b2 = last ? nB : cB + (size_t)(t + 2) * kstep;
;             const char* a3 = a2 + kstep; const char* b3 = b2 + kstep;
;             G_LDB(B0, 0, 0); G_SCHED; G_LDA(At, 0, 0); G_STAGE(G_SA(1, 1), a1 + hstepA, voffA);
;             G_WAIT_L(8); G_BAR; G_WAIT_L(0); G_MMA(0, 0, At, B0); G_BAR; G_SCHED;
;             G_LDB(B1, 0, 1); G_STAGE(G_SB(0, 0), b2, voffB);
;             G_BAR; G_WAIT_L(0); G_MMA(0, 1, At, B1); G_BAR;
.LBB0_986:
	s_add_u32 s15, s34, 0x100
	s_addc_u32 s59, s35, 0
	s_mov_b32 s60, -2
	s_cmp_eq_u32 s101, 1
	s_cbranch_scc0 .Lnodb_sc
	s_barrier
	s_mov_b32 s101, 0
.Lnodb_sc:
.LBB0_987:
	v_add_u32_e32 v145, s50, v142
	ds_read_b128 v[146:149], v145
	ds_read_b128 v[150:153], v145 offset:1024
	ds_read_b128 v[154:157], v145 offset:2048
	ds_read_b128 v[158:161], v145 offset:3072
	s_add_u32 s34, s20, 0x100
	s_addc_u32 s35, s21, 0
	s_cmp_eq_u32 s60, 12
	s_cselect_b32 s43, s17, s35
	s_cselect_b32 s42, s16, s34
	s_cselect_b32 s41, s3, s59
	s_cselect_b32 s40, s2, s15
	v_lshl_add_u64 v[196:197], s[20:21], 0, v[138:139]
	s_add_i32 m0, s44, 0xc000
	ds_read_b128 v[162:165], v144
	ds_read_b128 v[166:169], v144 offset:1024
	ds_read_b128 v[170:173], v144 offset:2048
	ds_read_b128 v[174:177], v144 offset:3072
	ds_read_b128 v[178:181], v144 offset:4096
	ds_read_b128 v[182:185], v144 offset:5120
	ds_read_b128 v[186:189], v144 offset:6144
	ds_read_b128 v[192:195], v144 offset:7168
	global_load_lds_dwordx4 v[196:197], off
	v_lshl_add_u64 v[196:197], s[20:21], 0, v[140:141]
	s_add_i32 m0, s44, 0xe000
	s_nop 0
	global_load_lds_dwordx4 v[196:197], off
	s_waitcnt lgkmcnt(8)
	s_barrier
	s_waitcnt lgkmcnt(0)
	s_setprio 1
	s_waitcnt lgkmcnt(0)
	v_mfma_f32_16x16x32_bf16 v[126:129], v[146:149], v[162:165], v[126:129]
	v_mfma_f32_16x16x32_bf16 v[122:125], v[154:157], v[162:165], v[122:125]
	v_mfma_f32_16x16x32_bf16 v[118:121], v[146:149], v[170:173], v[118:121]
	v_mfma_f32_16x16x32_bf16 v[114:117], v[154:157], v[170:173], v[114:117]
	v_mfma_f32_16x16x32_bf16 v[110:113], v[146:149], v[178:181], v[110:113]
	v_mfma_f32_16x16x32_bf16 v[106:109], v[154:157], v[178:181], v[106:109]
	v_mfma_f32_16x16x32_bf16 v[102:105], v[146:149], v[186:189], v[102:105]
	v_mfma_f32_16x16x32_bf16 v[98:101], v[154:157], v[186:189], v[98:101]
	v_mfma_f32_16x16x32_bf16 v[126:129], v[150:153], v[166:169], v[126:129]
	v_mfma_f32_16x16x32_bf16 v[122:125], v[158:161], v[166:169], v[122:125]
	v_mfma_f32_16x16x32_bf16 v[118:121], v[150:153], v[174:177], v[118:121]
	v_mfma_f32_16x16x32_bf16 v[114:117], v[158:161], v[174:177], v[114:117]
	v_mfma_f32_16x16x32_bf16 v[110:113], v[150:153], v[182:185], v[110:113]
	v_mfma_f32_16x16x32_bf16 v[106:109], v[158:161], v[182:185], v[106:109]
	v_mfma_f32_16x16x32_bf16 v[102:105], v[150:153], v[192:195], v[102:105]
	v_mfma_f32_16x16x32_bf16 v[98:101], v[158:161], v[192:195], v[98:101]
	s_setprio 0
	s_barrier
	s_add_i32 s0, s50, s31
	v_add_u32_e32 v145, s51, v142
	v_lshl_add_u64 v[212:213], s[40:41], 0, v[132:133]
	s_mov_b32 m0, s0
	ds_read_b128 v[196:199], v145
	ds_read_b128 v[200:203], v145 offset:1024
	ds_read_b128 v[204:207], v145 offset:2048
	ds_read_b128 v[208:211], v145 offset:3072
	global_load_lds_dwordx4 v[212:213], off
	v_lshl_add_u64 v[214:215], s[40:41], 0, v[136:137]
	s_add_i32 m0, s0, 0x2000
	s_nop 0
	global_load_lds_dwordx4 v[214:215], off
	s_barrier
	s_waitcnt lgkmcnt(0)
	s_setprio 1
	s_waitcnt lgkmcnt(0)
	v_mfma_f32_16x16x32_bf16 v[94:97], v[196:199], v[162:165], v[94:97]
	v_mfma_f32_16x16x32_bf16 v[90:93], v[204:207], v[162:165], v[90:93]
	v_mfma_f32_16x16x32_bf16 v[86:89], v[196:199], v[170:173], v[86:89]
	v_mfma_f32_16x16x32_bf16 v[82:85], v[204:207], v[170:173], v[82:85]
	v_mfma_f32_16x16x32_bf16 v[78:81], v[196:199], v[178:181], v[78:81]
	v_mfma_f32_16x16x32_bf16 v[74:77], v[204:207], v[178:181], v[74:77]
	v_mfma_f32_16x16x32_bf16 v[70:73], v[196:199], v[186:189], v[70:73]
	v_mfma_f32_16x16x32_bf16 v[66:69], v[204:207], v[186:189], v[66:69]
	v_mfma_f32_16x16x32_bf16 v[94:97], v[200:203], v[166:169], v[94:97]
	v_mfma_f32_16x16x32_bf16 v[90:93], v[208:211], v[166:169], v[90:93]
	v_mfma_f32_16x16x32_bf16 v[86:89], v[200:203], v[174:177], v[86:89]
	v_mfma_f32_16x16x32_bf16 v[82:85], v[208:211], v[174:177], v[82:85]
	v_mfma_f32_16x16x32_bf16 v[78:81], v[200:203], v[182:185], v[78:81]
	v_mfma_f32_16x16x32_bf16 v[74:77], v[208:211], v[182:185], v[74:77]
	v_mfma_f32_16x16x32_bf16 v[70:73], v[200:203], v[192:195], v[70:73]
	v_mfma_f32_16x16x32_bf16 v[66:69], v[208:211], v[192:195], v[66:69]
	s_setprio 0
	s_mov_b32 m0, s44
	v_lshl_add_u64 v[216:217], s[42:43], 0, v[130:131]
	s_barrier
	ds_read_b128 v[162:165], v144 offset:16384
	ds_read_b128 v[166:169], v144 offset:17408
	ds_read_b128 v[170:173], v144 offset:18432
	ds_read_b128 v[174:177], v144 offset:19456
	ds_read_b128 v[178:181], v144 offset:20480
	ds_read_b128 v[182:185], v144 offset:21504
	ds_read_b128 v[186:189], v144 offset:22528
	ds_read_b128 v[192:195], v144 offset:23552
	global_load_lds_dwordx4 v[216:217], off
	v_lshl_add_u64 v[218:219], s[42:43], 0, v[134:135]
	s_mov_b32 m0, s45
	s_nop 0
	global_load_lds_dwordx4 v[218:219], off
	s_barrier
	s_waitcnt lgkmcnt(0)
	s_setprio 1
	s_waitcnt lgkmcnt(0)
	v_mfma_f32_16x16x32_bf16 v[62:65], v[146:149], v[162:165], v[62:65]
	v_mfma_f32_16x16x32_bf16 v[58:61], v[154:157], v[162:165], v[58:61]
	v_mfma_f32_16x16x32_bf16 v[54:57], v[146:149], v[170:173], v[54:57]
	v_mfma_f32_16x16x32_bf16 v[50:53], v[154:157], v[170:173], v[50:53]
	v_mfma_f32_16x16x32_bf16 v[46:49], v[146:149], v[178:181], v[46:49]
	v_mfma_f32_16x16x32_bf16 v[42:45], v[154:157], v[178:181], v[42:45]
	v_mfma_f32_16x16x32_bf16 v[38:41], v[146:149], v[186:189], v[38:41]
	v_mfma_f32_16x16x32_bf16 v[34:37], v[154:157], v[186:189], v[34:37]
	v_mfma_f32_16x16x32_bf16 v[62:65], v[150:153], v[166:169], v[62:65]
	v_mfma_f32_16x16x32_bf16 v[58:61], v[158:161], v[166:169], v[58:61]
	v_mfma_f32_16x16x32_bf16 v[54:57], v[150:153], v[174:177], v[54:57]
	v_mfma_f32_16x16x32_bf16 v[50:53], v[158:161], v[174:177], v[50:53]
	v_mfma_f32_16x16x32_bf16 v[46:49], v[150:153], v[182:185], v[46:49]
	v_mfma_f32_16x16x32_bf16 v[42:45], v[158:161], v[182:185], v[42:45]
	v_mfma_f32_16x16x32_bf16 v[38:41], v[150:153], v[192:195], v[38:41]
	v_mfma_f32_16x16x32_bf16 v[34:37], v[158:161], v[192:195], v[34:37]
	s_setprio 0
	s_barrier
; #define G_STAGE(bufoff, gbase, voff) do { _Pragma("unroll") for (int _i = 0; _i < 2; ++_i) \
;         __builtin_amdgcn_global_load_lds((const unsigned*)((const char*)(gbase) + (voff)[_i]), (LAS unsigned*)(lds + (bufoff) + ldsw + _i * 8192), 16, 0, 0); } while (0)
; #define G_WAIT_V(n) asm volatile("s_waitcnt vmcnt(" #n ")" ::: "memory")
; #define G_WAIT_L(n) asm volatile("s_waitcnt lgkmcnt(" #n ")" ::: "memory")
; #define G_BAR __builtin_amdgcn_s_barrier()
; #define G_SCHED __builtin_amdgcn_sched_barrier(0)
; template <int MODE  , class Epi, class Sched>
; __device__ __forceinline__ void gemm_phase(LAS unsigned char* lds, const GemmDesc g, const Sched& S, const Epi& E) {
;     ...
;             G_BAR; G_WAIT_L(0); G_MMA(1, 0, At, B0); G_BAR; G_SCHED;
;             G_STAGE(G_SB(0, 1), b2 + hstepB, voffB);
;             G_WAIT_V(6); G_BAR; G_MMA(1, 1, At, B1); G_BAR;
;             G_LDB(B0, 1, 0); G_SCHED; G_LDA(At, 1, 0); G_STAGE(G_SA(0, 1), a2 + hstepA, voffA);
;             G_WAIT_L(8); G_BAR; G_WAIT_L(0); G_MMA(0, 0, At, B0); G_BAR; G_SCHED;
	s_add_u32 s0, s40, 0x84000
	s_addc_u32 s1, s41, 0
	s_add_i32 s10, s51, s31
	v_lshl_add_u64 v[146:147], s[0:1], 0, v[132:133]
	s_mov_b32 m0, s10
	s_nop 0
	global_load_lds_dwordx4 v[146:147], off
	v_lshl_add_u64 v[146:147], s[0:1], 0, v[136:137]
	s_add_i32 m0, s10, 0x2000
	s_nop 0
	global_load_lds_dwordx4 v[146:147], off
	s_waitcnt vmcnt(6)
	s_barrier
	s_setprio 1
	v_mfma_f32_16x16x32_bf16 v[30:33], v[196:199], v[162:165], v[30:33]
	v_mfma_f32_16x16x32_bf16 v[26:29], v[204:207], v[162:165], v[26:29]
	v_mfma_f32_16x16x32_bf16 v[22:25], v[196:199], v[170:173], v[22:25]
	v_mfma_f32_16x16x32_bf16 v[18:21], v[204:207], v[170:173], v[18:21]
	v_mfma_f32_16x16x32_bf16 v[14:17], v[196:199], v[178:181], v[14:17]
	v_mfma_f32_16x16x32_bf16 v[10:13], v[204:207], v[178:181], v[10:13]
	v_mfma_f32_16x16x32_bf16 v[6:9], v[196:199], v[186:189], v[6:9]
	v_mfma_f32_16x16x32_bf16 v[2:5], v[204:207], v[186:189], v[2:5]
	v_mfma_f32_16x16x32_bf16 v[30:33], v[200:203], v[166:169], v[30:33]
	v_mfma_f32_16x16x32_bf16 v[26:29], v[208:211], v[166:169], v[26:29]
	v_mfma_f32_16x16x32_bf16 v[22:25], v[200:203], v[174:177], v[22:25]
	v_mfma_f32_16x16x32_bf16 v[18:21], v[208:211], v[174:177], v[18:21]
	v_mfma_f32_16x16x32_bf16 v[14:17], v[200:203], v[182:185], v[14:17]
	v_mfma_f32_16x16x32_bf16 v[10:13], v[208:211], v[182:185], v[10:13]
	v_mfma_f32_16x16x32_bf16 v[6:9], v[200:203], v[192:195], v[6:9]
	v_mfma_f32_16x16x32_bf16 v[2:5], v[208:211], v[192:195], v[2:5]
	s_setprio 0
	s_add_i32 s10, 0, 0x18000
	v_add_u32_e32 v145, s10, v142
	s_barrier
	ds_read_b128 v[146:149], v145
	ds_read_b128 v[150:153], v145 offset:1024
	ds_read_b128 v[154:157], v145 offset:2048
	ds_read_b128 v[158:161], v145 offset:3072
	s_add_u32 s0, s42, 0x84000
	s_addc_u32 s1, s43, 0
	s_mov_b32 m0, s46
	v_lshl_add_u64 v[196:197], s[0:1], 0, v[130:131]
	ds_read_b128 v[162:165], v144 offset:32768
	ds_read_b128 v[166:169], v144 offset:33792
	ds_read_b128 v[170:173], v144 offset:34816
	ds_read_b128 v[174:177], v144 offset:35840
	ds_read_b128 v[178:181], v144 offset:36864
	ds_read_b128 v[182:185], v144 offset:37888
	ds_read_b128 v[186:189], v144 offset:38912
	ds_read_b128 v[192:195], v144 offset:39936
	global_load_lds_dwordx4 v[196:197], off
	v_lshl_add_u64 v[196:197], s[0:1], 0, v[134:135]
	s_mov_b32 m0, s47
	s_nop 0
	global_load_lds_dwordx4 v[196:197], off
	s_waitcnt lgkmcnt(8)
	s_barrier
	s_waitcnt lgkmcnt(0)
	s_setprio 1
	s_waitcnt lgkmcnt(0)
	v_mfma_f32_16x16x32_bf16 v[126:129], v[146:149], v[162:165], v[126:129]
	v_mfma_f32_16x16x32_bf16 v[122:125], v[154:157], v[162:165], v[122:125]
	v_mfma_f32_16x16x32_bf16 v[118:121], v[146:149], v[170:173], v[118:121]
	v_mfma_f32_16x16x32_bf16 v[114:117], v[154:157], v[170:173], v[114:117]
	v_mfma_f32_16x16x32_bf16 v[110:113], v[146:149], v[178:181], v[110:113]
	v_mfma_f32_16x16x32_bf16 v[106:109], v[154:157], v[178:181], v[106:109]
	v_mfma_f32_16x16x32_bf16 v[102:105], v[146:149], v[186:189], v[102:105]
	v_mfma_f32_16x16x32_bf16 v[98:101], v[154:157], v[186:189], v[98:101]
	v_mfma_f32_16x16x32_bf16 v[126:129], v[150:153], v[166:169], v[126:129]
	v_mfma_f32_16x16x32_bf16 v[122:125], v[158:161], v[166:169], v[122:125]
	v_mfma_f32_16x16x32_bf16 v[118:121], v[150:153], v[174:177], v[118:121]
	v_mfma_f32_16x16x32_bf16 v[114:117], v[158:161], v[174:177], v[114:117]
	v_mfma_f32_16x16x32_bf16 v[110:113], v[150:153], v[182:185], v[110:113]
	v_mfma_f32_16x16x32_bf16 v[106:109], v[158:161], v[182:185], v[106:109]
	v_mfma_f32_16x16x32_bf16 v[102:105], v[150:153], v[192:195], v[102:105]
	v_mfma_f32_16x16x32_bf16 v[98:101], v[158:161], v[192:195], v[98:101]
	s_setprio 0
	s_barrier
	s_add_i32 s11, 0, 0x1c000
	s_add_i32 s0, s10, s31
	v_add_u32_e32 v145, s11, v142
	v_lshl_add_u64 v[212:213], v[212:213], 0, s[4:5]
	s_mov_b32 m0, s0
	ds_read_b128 v[196:199], v145
	ds_read_b128 v[200:203], v145 offset:1024
	ds_read_b128 v[204:207], v145 offset:2048
	ds_read_b128 v[208:211], v145 offset:3072
	global_load_lds_dwordx4 v[212:213], off
	v_lshl_add_u64 v[212:213], v[214:215], 0, s[4:5]
	s_add_i32 m0, s0, 0x2000
	s_nop 0
	global_load_lds_dwordx4 v[212:213], off
	s_barrier
; #define G_STAGE(bufoff, gbase, voff) do { _Pragma("unroll") for (int _i = 0; _i < 2; ++_i) \
;         __builtin_amdgcn_global_load_lds((const unsigned*)((const char*)(gbase) + (voff)[_i]), (LAS unsigned*)(lds + (bufoff) + ldsw + _i * 8192), 16, 0, 0); } while (0)
; #define G_WAIT_V(n) asm volatile("s_waitcnt vmcnt(" #n ")" ::: "memory")
; #define G_WAIT_L(n) asm volatile("s_waitcnt lgkmcnt(" #n ")" ::: "memory")
; #define G_BAR __builtin_amdgcn_s_barrier()
; #define G_SCHED __builtin_amdgcn_sched_barrier(0)
; template <int MODE  , class Epi, class Sched>
; __device__ __forceinline__ void gemm_phase(LAS unsigned char* lds, const GemmDesc g, const Sched& S, const Epi& E) {
;     ...
;             G_LDB(B1, 1, 1); G_STAGE(G_SB(1, 0), b3, voffB);
;             G_BAR; G_WAIT_L(0); G_MMA(0, 1, At, B1); G_BAR;
;             G_LDA(At, 1, 1); G_STAGE(G_SA(1, 0), a3, voffA);
;             G_BAR; G_WAIT_L(0); G_MMA(1, 0, At, B0); G_BAR; G_SCHED;
;             G_STAGE(G_SB(1, 1), b3 + hstepB, voffB);
;             G_WAIT_V(6); G_BAR; G_MMA(1, 1, At, B1); G_BAR;
	s_waitcnt lgkmcnt(0)
	s_setprio 1
	s_waitcnt lgkmcnt(0)
	v_mfma_f32_16x16x32_bf16 v[94:97], v[196:199], v[162:165], v[94:97]
	v_mfma_f32_16x16x32_bf16 v[90:93], v[204:207], v[162:165], v[90:93]
	v_mfma_f32_16x16x32_bf16 v[86:89], v[196:199], v[170:173], v[86:89]
	v_mfma_f32_16x16x32_bf16 v[82:85], v[204:207], v[170:173], v[82:85]
	v_mfma_f32_16x16x32_bf16 v[78:81], v[196:199], v[178:181], v[78:81]
	v_mfma_f32_16x16x32_bf16 v[74:77], v[204:207], v[178:181], v[74:77]
	v_mfma_f32_16x16x32_bf16 v[70:73], v[196:199], v[186:189], v[70:73]
	v_mfma_f32_16x16x32_bf16 v[66:69], v[204:207], v[186:189], v[66:69]
	v_mfma_f32_16x16x32_bf16 v[94:97], v[200:203], v[166:169], v[94:97]
	v_mfma_f32_16x16x32_bf16 v[90:93], v[208:211], v[166:169], v[90:93]
	v_mfma_f32_16x16x32_bf16 v[86:89], v[200:203], v[174:177], v[86:89]
	v_mfma_f32_16x16x32_bf16 v[82:85], v[208:211], v[174:177], v[82:85]
	v_mfma_f32_16x16x32_bf16 v[78:81], v[200:203], v[182:185], v[78:81]
	v_mfma_f32_16x16x32_bf16 v[74:77], v[208:211], v[182:185], v[74:77]
	v_mfma_f32_16x16x32_bf16 v[70:73], v[200:203], v[192:195], v[70:73]
	v_mfma_f32_16x16x32_bf16 v[66:69], v[208:211], v[192:195], v[66:69]
	s_setprio 0
	s_mov_b32 m0, s48
	v_lshl_add_u64 v[212:213], v[216:217], 0, s[4:5]
	s_barrier
	ds_read_b128 v[162:165], v144 offset:49152
	ds_read_b128 v[166:169], v144 offset:50176
	ds_read_b128 v[170:173], v144 offset:51200
	ds_read_b128 v[174:177], v144 offset:52224
	ds_read_b128 v[178:181], v144 offset:53248
	ds_read_b128 v[182:185], v144 offset:54272
	ds_read_b128 v[186:189], v144 offset:55296
	ds_read_b128 v[192:195], v144 offset:56320
	global_load_lds_dwordx4 v[212:213], off
	v_lshl_add_u64 v[212:213], v[218:219], 0, s[4:5]
	s_mov_b32 m0, s49
	s_nop 0
	global_load_lds_dwordx4 v[212:213], off
	s_barrier
	s_waitcnt lgkmcnt(0)
	s_setprio 1
	s_waitcnt lgkmcnt(0)
	v_mfma_f32_16x16x32_bf16 v[62:65], v[146:149], v[162:165], v[62:65]
	v_mfma_f32_16x16x32_bf16 v[58:61], v[154:157], v[162:165], v[58:61]
	v_mfma_f32_16x16x32_bf16 v[54:57], v[146:149], v[170:173], v[54:57]
	v_mfma_f32_16x16x32_bf16 v[50:53], v[154:157], v[170:173], v[50:53]
	v_mfma_f32_16x16x32_bf16 v[46:49], v[146:149], v[178:181], v[46:49]
	v_mfma_f32_16x16x32_bf16 v[42:45], v[154:157], v[178:181], v[42:45]
	v_mfma_f32_16x16x32_bf16 v[38:41], v[146:149], v[186:189], v[38:41]
	v_mfma_f32_16x16x32_bf16 v[34:37], v[154:157], v[186:189], v[34:37]
	v_mfma_f32_16x16x32_bf16 v[62:65], v[150:153], v[166:169], v[62:65]
	v_mfma_f32_16x16x32_bf16 v[58:61], v[158:161], v[166:169], v[58:61]
	v_mfma_f32_16x16x32_bf16 v[54:57], v[150:153], v[174:177], v[54:57]
	v_mfma_f32_16x16x32_bf16 v[50:53], v[158:161], v[174:177], v[50:53]
	v_mfma_f32_16x16x32_bf16 v[46:49], v[150:153], v[182:185], v[46:49]
	v_mfma_f32_16x16x32_bf16 v[42:45], v[158:161], v[182:185], v[42:45]
	v_mfma_f32_16x16x32_bf16 v[38:41], v[150:153], v[192:195], v[38:41]
	v_mfma_f32_16x16x32_bf16 v[34:37], v[158:161], v[192:195], v[34:37]
	s_setprio 0
	s_barrier
	s_add_u32 s0, s40, 0x84080
	s_addc_u32 s1, s41, 0
	s_add_i32 s10, s11, s31
	v_lshl_add_u64 v[146:147], s[0:1], 0, v[132:133]
	s_mov_b32 m0, s10
	s_nop 0
	global_load_lds_dwordx4 v[146:147], off
	v_lshl_add_u64 v[146:147], s[0:1], 0, v[136:137]
	s_add_i32 m0, s10, 0x2000
	s_nop 0
	global_load_lds_dwordx4 v[146:147], off
	s_waitcnt vmcnt(6)
	s_barrier
	s_setprio 1
	v_mfma_f32_16x16x32_bf16 v[30:33], v[196:199], v[162:165], v[30:33]
	v_mfma_f32_16x16x32_bf16 v[26:29], v[204:207], v[162:165], v[26:29]
	v_mfma_f32_16x16x32_bf16 v[22:25], v[196:199], v[170:173], v[22:25]
	v_mfma_f32_16x16x32_bf16 v[18:21], v[204:207], v[170:173], v[18:21]
	v_mfma_f32_16x16x32_bf16 v[14:17], v[196:199], v[178:181], v[14:17]
	v_mfma_f32_16x16x32_bf16 v[10:13], v[204:207], v[178:181], v[10:13]
	v_mfma_f32_16x16x32_bf16 v[6:9], v[196:199], v[186:189], v[6:9]
	v_mfma_f32_16x16x32_bf16 v[2:5], v[204:207], v[186:189], v[2:5]
	v_mfma_f32_16x16x32_bf16 v[30:33], v[200:203], v[166:169], v[30:33]
	v_mfma_f32_16x16x32_bf16 v[26:29], v[208:211], v[166:169], v[26:29]
	v_mfma_f32_16x16x32_bf16 v[22:25], v[200:203], v[174:177], v[22:25]
	v_mfma_f32_16x16x32_bf16 v[18:21], v[208:211], v[174:177], v[18:21]
	v_mfma_f32_16x16x32_bf16 v[14:17], v[200:203], v[182:185], v[14:17]
	v_mfma_f32_16x16x32_bf16 v[10:13], v[208:211], v[182:185], v[10:13]
	v_mfma_f32_16x16x32_bf16 v[6:9], v[200:203], v[192:195], v[6:9]
	v_mfma_f32_16x16x32_bf16 v[2:5], v[208:211], v[192:195], v[2:5]
	s_setprio 0
	s_add_i32 s60, s60, 2
	s_add_u32 s15, s15, 0x100
	s_addc_u32 s59, s59, 0
	s_cmp_gt_u32 s60, 13
	s_mov_b64 s[20:21], s[34:35]
	s_cbranch_scc1 .Lkdone_sc
	s_barrier
	s_branch .LBB0_987
.Lkdone_sc:
	s_cmpk_gt_u32 s9, 0xff
	s_cselect_b32 s101, 1, 0
	s_cbranch_scc1 .Lkepi_sc
	s_barrier

; __device__ __forceinline__ unsigned pk_bf16(float lo, float hi) { const f32x2_t v = {lo, hi}; return __builtin_bit_cast(unsigned, __builtin_convertvector(v, bf16x2_t)); }
;     __device__ __forceinline__ bool next(int i, Unit& u) const { const int L = i * G + (G - 1 - c); if (L >= 3264) return false; tile_map(L, 136, 24, u.pm, u.pn); u.pn += 4;     u.kh = 0; u.type = 0; return true; }
;     __device__ __forceinline__ bool next(int i, Unit& u) const { const int L = i * G + (G - 1 - c); if (L >= 2176) return false; tile_map(L, 136, 16, u.pm, u.pn); u.pn += 24; u.kh = 0; u.type = 0; return true; }
;     __device__ __forceinline__ bool next(int i, Unit& u) const { const int L = (i >> 1) * G + c; if (L >= 1024) return false; tile_map(L, 128, 8, u.pm, u.pn); u.kh = i & 1; u.type = 0; return true; }
;     __device__ __forceinline__ bool next(int i, Unit& u) const { const int L = (i >> 1) * G + c; if (L >= 128) return false; tile_map(L, 16, 8, u.pm, u.pn); u.pm += 120; u.kh = i & 1; u.type = 1; return true; }
; template <int MODE  , class Epi, class Sched>
; __device__ __forceinline__ void gemm_phase(LAS unsigned char* lds, const GemmDesc g, const Sched& S, const Epi& E) {
;     ...
;     for (;;) {
;         const bool has_next = S.next(ui + 1, nxt);
;         const char* nA = has_next ? (const char*)(nxt.type ? g.A2 : g.A) + (size_t)nxt.pm * 2 * hstepA + (size_t)nxt.kh * khb : cA;
;         const char* nB = has_next ? (const char*)(nxt.type ? g.Bt2 : g.Bt) + (size_t)nxt.pn * 2 * hstepB + (size_t)nxt.kh * khb : cB;
;     __device__ __forceinline__ bool operator()(f32x4 (&acc)[2][2][4][2], const Unit& u, int wr, int wc, int fr, int fq) const {
;     ...
;                         u32x4 w; w.x = pk_bf16(v0[0], v0[1]); w.y = pk_bf16(v0[2], v0[3]); w.z = pk_bf16(v1[0], v1[1]); w.w = pk_bf16(v1[2], v1[3]);
;                         *(u32x4*)(rowp + bj * HALF) = w; } }
.LBB0_1005:
	v_lshl_add_u64 v[10:11], v[18:19], 0, s[42:43]
	v_cvt_pk_bf16_f32 v6, v6, v7
	v_cvt_pk_bf16_f32 v7, v8, v9
	v_cvt_pk_bf16_f32 v8, v2, v3
	v_cvt_pk_bf16_f32 v9, v4, v5
	global_store_dwordx4 v[10:11], v[6:9], off offset:256
.LBB0_1006:
	s_and_b64 vcc, exec, s[44:45]
	s_mov_b32 s81, s78
	s_mov_b32 s84, s79
	s_mov_b32 s83, s80
	s_mov_b64 s[4:5], s[48:49]
	s_mov_b64 s[2:3], s[46:47]
	s_cbranch_vccnz .LBB0_1132

; #define G_STAGE(bufoff, gbase, voff) do { _Pragma("unroll") for (int _i = 0; _i < 2; ++_i) \
;         __builtin_amdgcn_global_load_lds((const unsigned*)((const char*)(gbase) + (voff)[_i]), (LAS unsigned*)(lds + (bufoff) + ldsw + _i * 8192), 16, 0, 0); } while (0)
; #define G_WAIT_L(n) asm volatile("s_waitcnt lgkmcnt(" #n ")" ::: "memory")
; #define G_BAR __builtin_amdgcn_s_barrier()
; #define G_SCHED __builtin_amdgcn_sched_barrier(0)
; template <int MODE  , class Epi, class Sched>
; __device__ __forceinline__ void gemm_phase(LAS unsigned char* lds, const GemmDesc g, const Sched& S, const Epi& E) {
;     ...
;             G_LDB(B0, 0, 0); G_SCHED; G_LDA(At, 0, 0); G_STAGE(G_SA(1, 1), a1 + hstepA, voffA);
;             G_WAIT_L(8); G_BAR; G_WAIT_L(0); G_MMA(0, 0, At, B0); G_BAR; G_SCHED;
;             G_LDB(B1, 0, 1); G_STAGE(G_SB(0, 0), b2, voffB);
;             G_BAR; G_WAIT_L(0); G_MMA(0, 1, At, B1); G_BAR;
;     ...
;         if (zero) {
; #pragma unroll
;             for (int a = 0; a < 2; ++a)
; #pragma unroll
;                 for (int b = 0; b < 2; ++b)
; #pragma unroll
;                     for (int m = 0; m < 4; ++m)
; #pragma unroll
;                         for (int n = 0; n < 2; ++n) acc[a][b][m][n] = (f32x4){0.f, 0.f, 0.f, 0.f};
;         }
.LBB0_1016:
	s_add_u32 s85, s4, 0x100
	v_mov_b32_e32 v2, 0
	s_addc_u32 s86, s5, 0
	s_mov_b32 s87, -2
	v_mov_b32_e32 v3, v2
	v_mov_b64_e32 v[4:5], v[2:3]
	v_mov_b64_e32 v[6:7], v[2:3]
	v_mov_b64_e32 v[8:9], v[2:3]
	v_mov_b64_e32 v[18:19], v[2:3]
	v_mov_b64_e32 v[20:21], v[2:3]
	v_mov_b64_e32 v[22:23], v[2:3]
	v_mov_b64_e32 v[24:25], v[2:3]
	v_mov_b64_e32 v[34:35], v[2:3]
	v_mov_b64_e32 v[36:37], v[2:3]
	v_mov_b64_e32 v[38:39], v[2:3]
	v_mov_b64_e32 v[40:41], v[2:3]
	v_mov_b64_e32 v[50:51], v[2:3]
	v_mov_b64_e32 v[52:53], v[2:3]
	v_mov_b64_e32 v[54:55], v[2:3]
	v_mov_b64_e32 v[56:57], v[2:3]
	v_mov_b64_e32 v[10:11], v[2:3]
	v_mov_b64_e32 v[12:13], v[2:3]
	v_mov_b64_e32 v[14:15], v[2:3]
	v_mov_b64_e32 v[16:17], v[2:3]
	v_mov_b64_e32 v[26:27], v[2:3]
	v_mov_b64_e32 v[28:29], v[2:3]
	v_mov_b64_e32 v[30:31], v[2:3]
	v_mov_b64_e32 v[32:33], v[2:3]
	v_mov_b64_e32 v[42:43], v[2:3]
	v_mov_b64_e32 v[44:45], v[2:3]
	v_mov_b64_e32 v[46:47], v[2:3]
	v_mov_b64_e32 v[48:49], v[2:3]
	v_mov_b64_e32 v[58:59], v[2:3]
	v_mov_b64_e32 v[60:61], v[2:3]
	v_mov_b64_e32 v[62:63], v[2:3]
	v_mov_b64_e32 v[64:65], v[2:3]
	v_mov_b64_e32 v[66:67], v[2:3]
	v_mov_b64_e32 v[68:69], v[2:3]
	v_mov_b64_e32 v[70:71], v[2:3]
	v_mov_b64_e32 v[72:73], v[2:3]
	v_mov_b64_e32 v[82:83], v[2:3]
	v_mov_b64_e32 v[84:85], v[2:3]
	v_mov_b64_e32 v[86:87], v[2:3]
	v_mov_b64_e32 v[88:89], v[2:3]
	v_mov_b64_e32 v[98:99], v[2:3]
	v_mov_b64_e32 v[100:101], v[2:3]
	v_mov_b64_e32 v[102:103], v[2:3]
	v_mov_b64_e32 v[104:105], v[2:3]
	v_mov_b64_e32 v[114:115], v[2:3]
	v_mov_b64_e32 v[116:117], v[2:3]
	v_mov_b64_e32 v[118:119], v[2:3]
	v_mov_b64_e32 v[120:121], v[2:3]
	v_mov_b64_e32 v[74:75], v[2:3]
	v_mov_b64_e32 v[76:77], v[2:3]
	v_mov_b64_e32 v[78:79], v[2:3]
	v_mov_b64_e32 v[80:81], v[2:3]
	v_mov_b64_e32 v[90:91], v[2:3]
	v_mov_b64_e32 v[92:93], v[2:3]
	v_mov_b64_e32 v[94:95], v[2:3]
	v_mov_b64_e32 v[96:97], v[2:3]
	v_mov_b64_e32 v[106:107], v[2:3]
	v_mov_b64_e32 v[108:109], v[2:3]
	v_mov_b64_e32 v[110:111], v[2:3]
	v_mov_b64_e32 v[112:113], v[2:3]
	v_mov_b64_e32 v[122:123], v[2:3]
	v_mov_b64_e32 v[124:125], v[2:3]
	v_mov_b64_e32 v[126:127], v[2:3]
	v_mov_b64_e32 v[128:129], v[2:3]
	s_cmp_eq_u32 s101, 1
	s_cbranch_scc0 .Lnodb_s1a
	s_barrier
	s_mov_b32 s101, 0
.Lnodb_s1a:
.LBB0_1017:
	ds_read_b128 v[130:133], v163
	ds_read_b128 v[134:137], v163 offset:1024
	ds_read_b128 v[154:157], v163 offset:2048
	ds_read_b128 v[170:173], v163 offset:3072
	s_add_u32 s4, s2, 0x100
	s_addc_u32 s5, s3, 0
	s_cmp_eq_u32 s87, 28
	s_cselect_b32 s53, s47, s5
	s_cselect_b32 s52, s46, s4
	s_cselect_b32 s51, s49, s86
	s_cselect_b32 s50, s48, s85
	v_lshl_add_u64 v[158:159], s[2:3], 0, v[150:151]
	s_add_i32 m0, s58, 0xc000
	ds_read_b128 v[174:177], v164
	ds_read_b128 v[178:181], v164 offset:1024
	ds_read_b128 v[182:185], v164 offset:2048
	ds_read_b128 v[186:189], v164 offset:3072
	ds_read_b128 v[192:195], v164 offset:4096
	ds_read_b128 v[196:199], v164 offset:5120
	ds_read_b128 v[200:203], v164 offset:6144
	ds_read_b128 v[204:207], v164 offset:7168
	global_load_lds_dwordx4 v[158:159], off
	v_lshl_add_u64 v[158:159], s[2:3], 0, v[152:153]
	s_add_i32 m0, s58, 0xe000
	s_nop 0
	global_load_lds_dwordx4 v[158:159], off
	s_waitcnt lgkmcnt(8)
	s_barrier
	s_waitcnt lgkmcnt(0)
	s_setprio 1
	s_waitcnt lgkmcnt(0)
	v_mfma_f32_16x16x32_bf16 v[126:129], v[130:133], v[174:177], v[126:129]
	v_mfma_f32_16x16x32_bf16 v[122:125], v[154:157], v[174:177], v[122:125]
	v_mfma_f32_16x16x32_bf16 v[110:113], v[130:133], v[182:185], v[110:113]
	v_mfma_f32_16x16x32_bf16 v[106:109], v[154:157], v[182:185], v[106:109]
	v_mfma_f32_16x16x32_bf16 v[94:97], v[130:133], v[192:195], v[94:97]
	v_mfma_f32_16x16x32_bf16 v[90:93], v[154:157], v[192:195], v[90:93]
	v_mfma_f32_16x16x32_bf16 v[78:81], v[130:133], v[200:203], v[78:81]
	v_mfma_f32_16x16x32_bf16 v[74:77], v[154:157], v[200:203], v[74:77]
	v_mfma_f32_16x16x32_bf16 v[126:129], v[134:137], v[178:181], v[126:129]
	v_mfma_f32_16x16x32_bf16 v[122:125], v[170:173], v[178:181], v[122:125]
	v_mfma_f32_16x16x32_bf16 v[110:113], v[134:137], v[186:189], v[110:113]
	v_mfma_f32_16x16x32_bf16 v[106:109], v[170:173], v[186:189], v[106:109]
	v_mfma_f32_16x16x32_bf16 v[94:97], v[134:137], v[196:199], v[94:97]
	v_mfma_f32_16x16x32_bf16 v[90:93], v[170:173], v[196:199], v[90:93]
	v_mfma_f32_16x16x32_bf16 v[78:81], v[134:137], v[204:207], v[78:81]
	v_mfma_f32_16x16x32_bf16 v[74:77], v[170:173], v[204:207], v[74:77]
	s_setprio 0
	s_barrier
	s_add_i32 s0, s66, s57
	v_lshl_add_u64 v[158:159], s[50:51], 0, v[140:141]
	s_mov_b32 m0, s0
	ds_read_b128 v[208:211], v165
	ds_read_b128 v[212:215], v165 offset:1024
	ds_read_b128 v[216:219], v165 offset:2048
	ds_read_b128 v[220:223], v165 offset:3072
	global_load_lds_dwordx4 v[158:159], off
	v_lshl_add_u64 v[224:225], s[50:51], 0, v[144:145]
	s_add_i32 m0, s0, 0x2000
	s_nop 0
	global_load_lds_dwordx4 v[224:225], off
	s_barrier
	s_waitcnt lgkmcnt(0)
	s_setprio 1
	s_waitcnt lgkmcnt(0)
	v_mfma_f32_16x16x32_bf16 v[118:121], v[208:211], v[174:177], v[118:121]
	v_mfma_f32_16x16x32_bf16 v[114:117], v[216:219], v[174:177], v[114:117]
	v_mfma_f32_16x16x32_bf16 v[102:105], v[208:211], v[182:185], v[102:105]
	v_mfma_f32_16x16x32_bf16 v[98:101], v[216:219], v[182:185], v[98:101]
	v_mfma_f32_16x16x32_bf16 v[86:89], v[208:211], v[192:195], v[86:89]
	v_mfma_f32_16x16x32_bf16 v[82:85], v[216:219], v[192:195], v[82:85]
	v_mfma_f32_16x16x32_bf16 v[70:73], v[208:211], v[200:203], v[70:73]
	v_mfma_f32_16x16x32_bf16 v[66:69], v[216:219], v[200:203], v[66:69]
	v_mfma_f32_16x16x32_bf16 v[118:121], v[212:215], v[178:181], v[118:121]
	v_mfma_f32_16x16x32_bf16 v[114:117], v[220:223], v[178:181], v[114:117]
	v_mfma_f32_16x16x32_bf16 v[102:105], v[212:215], v[186:189], v[102:105]
	v_mfma_f32_16x16x32_bf16 v[98:101], v[220:223], v[186:189], v[98:101]
	v_mfma_f32_16x16x32_bf16 v[86:89], v[212:215], v[196:199], v[86:89]
	v_mfma_f32_16x16x32_bf16 v[82:85], v[220:223], v[196:199], v[82:85]
	v_mfma_f32_16x16x32_bf16 v[70:73], v[212:215], v[204:207], v[70:73]
	v_mfma_f32_16x16x32_bf16 v[66:69], v[220:223], v[204:207], v[66:69]
	s_setprio 0
	s_mov_b32 m0, s58
	v_lshl_add_u64 v[226:227], s[52:53], 0, v[138:139]
	s_barrier
; #define G_STAGE(bufoff, gbase, voff) do { _Pragma("unroll") for (int _i = 0; _i < 2; ++_i) \
;         __builtin_amdgcn_global_load_lds((const unsigned*)((const char*)(gbase) + (voff)[_i]), (LAS unsigned*)(lds + (bufoff) + ldsw + _i * 8192), 16, 0, 0); } while (0)
; #define G_WAIT_V(n) asm volatile("s_waitcnt vmcnt(" #n ")" ::: "memory")
; #define G_WAIT_L(n) asm volatile("s_waitcnt lgkmcnt(" #n ")" ::: "memory")
; #define G_BAR __builtin_amdgcn_s_barrier()
; #define G_SCHED __builtin_amdgcn_sched_barrier(0)
; template <int MODE  , class Epi, class Sched>
; __device__ __forceinline__ void gemm_phase(LAS unsigned char* lds, const GemmDesc g, const Sched& S, const Epi& E) {
;     ...
;             G_LDA(At, 0, 1); G_STAGE(G_SA(0, 0), a2, voffA);
;             G_BAR; G_WAIT_L(0); G_MMA(1, 0, At, B0); G_BAR; G_SCHED;
;             G_STAGE(G_SB(0, 1), b2 + hstepB, voffB);
;             G_WAIT_V(6); G_BAR; G_MMA(1, 1, At, B1); G_BAR;
;             G_LDB(B0, 1, 0); G_SCHED; G_LDA(At, 1, 0); G_STAGE(G_SA(0, 1), a2 + hstepA, voffA);
;             G_WAIT_L(8); G_BAR; G_WAIT_L(0); G_MMA(0, 0, At, B0); G_BAR; G_SCHED;
	ds_read_b128 v[174:177], v164 offset:16384
	ds_read_b128 v[178:181], v164 offset:17408
	ds_read_b128 v[182:185], v164 offset:18432
	ds_read_b128 v[186:189], v164 offset:19456
	ds_read_b128 v[192:195], v164 offset:20480
	ds_read_b128 v[196:199], v164 offset:21504
	ds_read_b128 v[200:203], v164 offset:22528
	ds_read_b128 v[204:207], v164 offset:23552
	global_load_lds_dwordx4 v[226:227], off
	v_lshl_add_u64 v[228:229], s[52:53], 0, v[142:143]
	s_mov_b32 m0, s59
	s_nop 0
	global_load_lds_dwordx4 v[228:229], off
	s_barrier
	s_waitcnt lgkmcnt(0)
	s_setprio 1
	s_waitcnt lgkmcnt(0)
	v_mfma_f32_16x16x32_bf16 v[62:65], v[130:133], v[174:177], v[62:65]
	v_mfma_f32_16x16x32_bf16 v[58:61], v[154:157], v[174:177], v[58:61]
	v_mfma_f32_16x16x32_bf16 v[46:49], v[130:133], v[182:185], v[46:49]
	v_mfma_f32_16x16x32_bf16 v[42:45], v[154:157], v[182:185], v[42:45]
	v_mfma_f32_16x16x32_bf16 v[30:33], v[130:133], v[192:195], v[30:33]
	v_mfma_f32_16x16x32_bf16 v[26:29], v[154:157], v[192:195], v[26:29]
	v_mfma_f32_16x16x32_bf16 v[14:17], v[130:133], v[200:203], v[14:17]
	v_mfma_f32_16x16x32_bf16 v[10:13], v[154:157], v[200:203], v[10:13]
	v_mfma_f32_16x16x32_bf16 v[62:65], v[134:137], v[178:181], v[62:65]
	v_mfma_f32_16x16x32_bf16 v[58:61], v[170:173], v[178:181], v[58:61]
	v_mfma_f32_16x16x32_bf16 v[46:49], v[134:137], v[186:189], v[46:49]
	v_mfma_f32_16x16x32_bf16 v[42:45], v[170:173], v[186:189], v[42:45]
	v_mfma_f32_16x16x32_bf16 v[30:33], v[134:137], v[196:199], v[30:33]
	v_mfma_f32_16x16x32_bf16 v[26:29], v[170:173], v[196:199], v[26:29]
	v_mfma_f32_16x16x32_bf16 v[14:17], v[134:137], v[204:207], v[14:17]
	v_mfma_f32_16x16x32_bf16 v[10:13], v[170:173], v[204:207], v[10:13]
	s_setprio 0
	s_barrier
	s_add_u32 s0, s50, 0x84000
	s_addc_u32 s1, s51, 0
	s_add_i32 s2, s67, s57
	v_lshl_add_u64 v[130:131], s[0:1], 0, v[140:141]
	s_mov_b32 m0, s2
	s_nop 0
	global_load_lds_dwordx4 v[130:131], off
	v_lshl_add_u64 v[130:131], s[0:1], 0, v[144:145]
	s_add_i32 m0, s2, 0x2000
	s_nop 0
	global_load_lds_dwordx4 v[130:131], off
	s_waitcnt vmcnt(6)
	s_barrier
	s_setprio 1
	v_mfma_f32_16x16x32_bf16 v[54:57], v[208:211], v[174:177], v[54:57]
	v_mfma_f32_16x16x32_bf16 v[50:53], v[216:219], v[174:177], v[50:53]
	v_mfma_f32_16x16x32_bf16 v[38:41], v[208:211], v[182:185], v[38:41]
	v_mfma_f32_16x16x32_bf16 v[34:37], v[216:219], v[182:185], v[34:37]
	v_mfma_f32_16x16x32_bf16 v[22:25], v[208:211], v[192:195], v[22:25]
	v_mfma_f32_16x16x32_bf16 v[18:21], v[216:219], v[192:195], v[18:21]
	v_mfma_f32_16x16x32_bf16 v[6:9], v[208:211], v[200:203], v[6:9]
	v_mfma_f32_16x16x32_bf16 v[2:5], v[216:219], v[200:203], v[2:5]
	v_mfma_f32_16x16x32_bf16 v[54:57], v[212:215], v[178:181], v[54:57]
	v_mfma_f32_16x16x32_bf16 v[50:53], v[220:223], v[178:181], v[50:53]
	v_mfma_f32_16x16x32_bf16 v[38:41], v[212:215], v[186:189], v[38:41]
	v_mfma_f32_16x16x32_bf16 v[34:37], v[220:223], v[186:189], v[34:37]
	v_mfma_f32_16x16x32_bf16 v[22:25], v[212:215], v[196:199], v[22:25]
	v_mfma_f32_16x16x32_bf16 v[18:21], v[220:223], v[196:199], v[18:21]
	v_mfma_f32_16x16x32_bf16 v[6:9], v[212:215], v[204:207], v[6:9]
	v_mfma_f32_16x16x32_bf16 v[2:5], v[220:223], v[204:207], v[2:5]
	s_setprio 0
	s_add_i32 s2, 0, 0x18000
	v_add_u32_e32 v146, s2, v160
	s_barrier
	ds_read_b128 v[130:133], v146
	ds_read_b128 v[134:137], v146 offset:1024
	ds_read_b128 v[154:157], v146 offset:2048
	ds_read_b128 v[170:173], v146 offset:3072
	s_add_u32 s0, s52, 0x84000
	s_addc_u32 s1, s53, 0
	s_mov_b32 m0, s60
	v_lshl_add_u64 v[208:209], s[0:1], 0, v[138:139]
	ds_read_b128 v[174:177], v164 offset:32768
	ds_read_b128 v[178:181], v164 offset:33792
	ds_read_b128 v[182:185], v164 offset:34816
	ds_read_b128 v[186:189], v164 offset:35840
	ds_read_b128 v[192:195], v164 offset:36864
	ds_read_b128 v[196:199], v164 offset:37888
	ds_read_b128 v[200:203], v164 offset:38912
	ds_read_b128 v[204:207], v164 offset:39936
	global_load_lds_dwordx4 v[208:209], off
	v_lshl_add_u64 v[208:209], s[0:1], 0, v[142:143]
	s_mov_b32 m0, s61
	s_nop 0
	global_load_lds_dwordx4 v[208:209], off
	s_waitcnt lgkmcnt(8)
	s_barrier
	s_waitcnt lgkmcnt(0)
	s_setprio 1
	s_waitcnt lgkmcnt(0)
	v_mfma_f32_16x16x32_bf16 v[126:129], v[130:133], v[174:177], v[126:129]
	v_mfma_f32_16x16x32_bf16 v[122:125], v[154:157], v[174:177], v[122:125]
	v_mfma_f32_16x16x32_bf16 v[110:113], v[130:133], v[182:185], v[110:113]
	v_mfma_f32_16x16x32_bf16 v[106:109], v[154:157], v[182:185], v[106:109]
	v_mfma_f32_16x16x32_bf16 v[94:97], v[130:133], v[192:195], v[94:97]
	v_mfma_f32_16x16x32_bf16 v[90:93], v[154:157], v[192:195], v[90:93]
	v_mfma_f32_16x16x32_bf16 v[78:81], v[130:133], v[200:203], v[78:81]
	v_mfma_f32_16x16x32_bf16 v[74:77], v[154:157], v[200:203], v[74:77]
	v_mfma_f32_16x16x32_bf16 v[126:129], v[134:137], v[178:181], v[126:129]
	v_mfma_f32_16x16x32_bf16 v[122:125], v[170:173], v[178:181], v[122:125]
	v_mfma_f32_16x16x32_bf16 v[110:113], v[134:137], v[186:189], v[110:113]
	v_mfma_f32_16x16x32_bf16 v[106:109], v[170:173], v[186:189], v[106:109]
	v_mfma_f32_16x16x32_bf16 v[94:97], v[134:137], v[196:199], v[94:97]
	v_mfma_f32_16x16x32_bf16 v[90:93], v[170:173], v[196:199], v[90:93]
	v_mfma_f32_16x16x32_bf16 v[78:81], v[134:137], v[204:207], v[78:81]
	v_mfma_f32_16x16x32_bf16 v[74:77], v[170:173], v[204:207], v[74:77]
	s_setprio 0
	s_barrier
; #define G_STAGE(bufoff, gbase, voff) do { _Pragma("unroll") for (int _i = 0; _i < 2; ++_i) \
;         __builtin_amdgcn_global_load_lds((const unsigned*)((const char*)(gbase) + (voff)[_i]), (LAS unsigned*)(lds + (bufoff) + ldsw + _i * 8192), 16, 0, 0); } while (0)
; #define G_WAIT_V(n) asm volatile("s_waitcnt vmcnt(" #n ")" ::: "memory")
; #define G_WAIT_L(n) asm volatile("s_waitcnt lgkmcnt(" #n ")" ::: "memory")
; #define G_BAR __builtin_amdgcn_s_barrier()
; #define G_SCHED __builtin_amdgcn_sched_barrier(0)
; template <int MODE  , class Epi, class Sched>
; __device__ __forceinline__ void gemm_phase(LAS unsigned char* lds, const GemmDesc g, const Sched& S, const Epi& E) {
;     ...
;             G_LDB(B1, 1, 1); G_STAGE(G_SB(1, 0), b3, voffB);
;             G_BAR; G_WAIT_L(0); G_MMA(0, 1, At, B1); G_BAR;
;             G_LDA(At, 1, 1); G_STAGE(G_SA(1, 0), a3, voffA);
;             G_BAR; G_WAIT_L(0); G_MMA(1, 0, At, B0); G_BAR; G_SCHED;
;             G_STAGE(G_SB(1, 1), b3 + hstepB, voffB);
;             G_WAIT_V(6); G_BAR; G_MMA(1, 1, At, B1); G_BAR;
;         }
;         if constexpr (MODE == 1) asm volatile("s_nop 15\n\ts_nop 15" ::: "memory");
;         const bool zero = E(acc, cur, wr, wc, fr, fq);
;         if (!has_next) break;
	s_add_i32 s3, 0, 0x1c000
	s_add_i32 s0, s2, s57
	v_add_u32_e32 v146, s3, v160
	v_lshl_add_u64 v[158:159], v[158:159], 0, s[14:15]
	s_mov_b32 m0, s0
	ds_read_b128 v[208:211], v146
	ds_read_b128 v[212:215], v146 offset:1024
	ds_read_b128 v[216:219], v146 offset:2048
	ds_read_b128 v[220:223], v146 offset:3072
	global_load_lds_dwordx4 v[158:159], off
	v_lshl_add_u64 v[158:159], v[224:225], 0, s[14:15]
	s_add_i32 m0, s0, 0x2000
	s_nop 0
	global_load_lds_dwordx4 v[158:159], off
	s_barrier
	s_waitcnt lgkmcnt(0)
	s_setprio 1
	s_waitcnt lgkmcnt(0)
	v_mfma_f32_16x16x32_bf16 v[118:121], v[208:211], v[174:177], v[118:121]
	v_mfma_f32_16x16x32_bf16 v[114:117], v[216:219], v[174:177], v[114:117]
	v_mfma_f32_16x16x32_bf16 v[102:105], v[208:211], v[182:185], v[102:105]
	v_mfma_f32_16x16x32_bf16 v[98:101], v[216:219], v[182:185], v[98:101]
	v_mfma_f32_16x16x32_bf16 v[86:89], v[208:211], v[192:195], v[86:89]
	v_mfma_f32_16x16x32_bf16 v[82:85], v[216:219], v[192:195], v[82:85]
	v_mfma_f32_16x16x32_bf16 v[70:73], v[208:211], v[200:203], v[70:73]
	v_mfma_f32_16x16x32_bf16 v[66:69], v[216:219], v[200:203], v[66:69]
	v_mfma_f32_16x16x32_bf16 v[118:121], v[212:215], v[178:181], v[118:121]
	v_mfma_f32_16x16x32_bf16 v[114:117], v[220:223], v[178:181], v[114:117]
	v_mfma_f32_16x16x32_bf16 v[102:105], v[212:215], v[186:189], v[102:105]
	v_mfma_f32_16x16x32_bf16 v[98:101], v[220:223], v[186:189], v[98:101]
	v_mfma_f32_16x16x32_bf16 v[86:89], v[212:215], v[196:199], v[86:89]
	v_mfma_f32_16x16x32_bf16 v[82:85], v[220:223], v[196:199], v[82:85]
	v_mfma_f32_16x16x32_bf16 v[70:73], v[212:215], v[204:207], v[70:73]
	v_mfma_f32_16x16x32_bf16 v[66:69], v[220:223], v[204:207], v[66:69]
	s_setprio 0
	s_mov_b32 m0, s64
	v_lshl_add_u64 v[158:159], v[226:227], 0, s[14:15]
	s_barrier
	ds_read_b128 v[174:177], v164 offset:49152
	ds_read_b128 v[178:181], v164 offset:50176
	ds_read_b128 v[182:185], v164 offset:51200
	ds_read_b128 v[186:189], v164 offset:52224
	ds_read_b128 v[192:195], v164 offset:53248
	ds_read_b128 v[196:199], v164 offset:54272
	ds_read_b128 v[200:203], v164 offset:55296
	ds_read_b128 v[204:207], v164 offset:56320
	global_load_lds_dwordx4 v[158:159], off
	v_lshl_add_u64 v[158:159], v[228:229], 0, s[14:15]
	s_mov_b32 m0, s65
	s_nop 0
	global_load_lds_dwordx4 v[158:159], off
	s_barrier
	s_waitcnt lgkmcnt(0)
	s_setprio 1
	s_waitcnt lgkmcnt(0)
	v_mfma_f32_16x16x32_bf16 v[62:65], v[130:133], v[174:177], v[62:65]
	v_mfma_f32_16x16x32_bf16 v[58:61], v[154:157], v[174:177], v[58:61]
	v_mfma_f32_16x16x32_bf16 v[46:49], v[130:133], v[182:185], v[46:49]
	v_mfma_f32_16x16x32_bf16 v[42:45], v[154:157], v[182:185], v[42:45]
	v_mfma_f32_16x16x32_bf16 v[30:33], v[130:133], v[192:195], v[30:33]
	v_mfma_f32_16x16x32_bf16 v[26:29], v[154:157], v[192:195], v[26:29]
	v_mfma_f32_16x16x32_bf16 v[14:17], v[130:133], v[200:203], v[14:17]
	v_mfma_f32_16x16x32_bf16 v[10:13], v[154:157], v[200:203], v[10:13]
	v_mfma_f32_16x16x32_bf16 v[62:65], v[134:137], v[178:181], v[62:65]
	v_mfma_f32_16x16x32_bf16 v[58:61], v[170:173], v[178:181], v[58:61]
	v_mfma_f32_16x16x32_bf16 v[46:49], v[134:137], v[186:189], v[46:49]
	v_mfma_f32_16x16x32_bf16 v[42:45], v[170:173], v[186:189], v[42:45]
	v_mfma_f32_16x16x32_bf16 v[30:33], v[134:137], v[196:199], v[30:33]
	v_mfma_f32_16x16x32_bf16 v[26:29], v[170:173], v[196:199], v[26:29]
	v_mfma_f32_16x16x32_bf16 v[14:17], v[134:137], v[204:207], v[14:17]
	v_mfma_f32_16x16x32_bf16 v[10:13], v[170:173], v[204:207], v[10:13]
	s_setprio 0
	s_barrier
	s_add_u32 s0, s50, 0x84080
	s_addc_u32 s1, s51, 0
	s_add_i32 s2, s3, s57
	v_lshl_add_u64 v[130:131], s[0:1], 0, v[140:141]
	s_mov_b32 m0, s2
	s_nop 0
	global_load_lds_dwordx4 v[130:131], off
	v_lshl_add_u64 v[130:131], s[0:1], 0, v[144:145]
	s_add_i32 m0, s2, 0x2000
	s_nop 0
	global_load_lds_dwordx4 v[130:131], off
	s_waitcnt vmcnt(6)
	s_barrier
	s_setprio 1
	v_mfma_f32_16x16x32_bf16 v[54:57], v[208:211], v[174:177], v[54:57]
	v_mfma_f32_16x16x32_bf16 v[50:53], v[216:219], v[174:177], v[50:53]
	v_mfma_f32_16x16x32_bf16 v[38:41], v[208:211], v[182:185], v[38:41]
	v_mfma_f32_16x16x32_bf16 v[34:37], v[216:219], v[182:185], v[34:37]
	v_mfma_f32_16x16x32_bf16 v[22:25], v[208:211], v[192:195], v[22:25]
	v_mfma_f32_16x16x32_bf16 v[18:21], v[216:219], v[192:195], v[18:21]
	v_mfma_f32_16x16x32_bf16 v[6:9], v[208:211], v[200:203], v[6:9]
	v_mfma_f32_16x16x32_bf16 v[2:5], v[216:219], v[200:203], v[2:5]
	v_mfma_f32_16x16x32_bf16 v[54:57], v[212:215], v[178:181], v[54:57]
	v_mfma_f32_16x16x32_bf16 v[50:53], v[220:223], v[178:181], v[50:53]
	v_mfma_f32_16x16x32_bf16 v[38:41], v[212:215], v[186:189], v[38:41]
	v_mfma_f32_16x16x32_bf16 v[34:37], v[220:223], v[186:189], v[34:37]
	v_mfma_f32_16x16x32_bf16 v[22:25], v[212:215], v[196:199], v[22:25]
	v_mfma_f32_16x16x32_bf16 v[18:21], v[220:223], v[196:199], v[18:21]
	v_mfma_f32_16x16x32_bf16 v[6:9], v[212:215], v[204:207], v[6:9]
	v_mfma_f32_16x16x32_bf16 v[2:5], v[220:223], v[204:207], v[2:5]
	s_setprio 0
	s_add_i32 s87, s87, 2
	s_add_u32 s85, s85, 0x100
	s_addc_u32 s86, s86, 0
	s_cmp_gt_u32 s87, 29
	s_mov_b64 s[2:3], s[4:5]
	s_cbranch_scc1 .Lkdone_s1a
	s_barrier
	s_branch .LBB0_1017
.Lkdone_s1a:
	s_cmpk_gt_u32 s54, 0xff
	s_cselect_b32 s101, 1, 0
	s_cbranch_scc1 .Lkepi_s1a
	s_barrier

; __global__ void __launch_bounds__(NTHREADS, 2) fwd_megakernel(Params p) {
	.amdhsa_kernel _Z14fwd_megakernel6Params
		.amdhsa_group_segment_fixed_size 0
		.amdhsa_private_segment_fixed_size 0
		.amdhsa_kernarg_size 384
		.amdhsa_user_sgpr_count 2
		.amdhsa_user_sgpr_dispatch_ptr 0
		.amdhsa_user_sgpr_queue_ptr 0
		.amdhsa_user_sgpr_kernarg_segment_ptr 1
		.amdhsa_user_sgpr_dispatch_id 0
		.amdhsa_user_sgpr_kernarg_preload_length 0
		.amdhsa_user_sgpr_kernarg_preload_offset 0
		.amdhsa_user_sgpr_private_segment_size 0
		.amdhsa_uses_dynamic_stack 0
		.amdhsa_enable_private_segment 0
		.amdhsa_system_sgpr_workgroup_id_x 1
		.amdhsa_system_sgpr_workgroup_id_y 0
		.amdhsa_system_sgpr_workgroup_id_z 0
		.amdhsa_system_sgpr_workgroup_info 0
		.amdhsa_system_vgpr_workitem_id 0
		.amdhsa_next_free_vgpr 256
		.amdhsa_next_free_sgpr 102
		.amdhsa_accum_offset 256
		.amdhsa_reserve_vcc 1
		.amdhsa_float_round_mode_32 0
		.amdhsa_float_round_mode_16_64 0
		.amdhsa_float_denorm_mode_32 3
		.amdhsa_float_denorm_mode_16_64 3
		.amdhsa_dx10_clamp 1
		.amdhsa_ieee_mode 1
		.amdhsa_fp16_overflow 0
		.amdhsa_tg_split 0
		.amdhsa_exception_fp_ieee_invalid_op 0
		.amdhsa_exception_fp_denorm_src 0
		.amdhsa_exception_fp_ieee_div_zero 0
		.amdhsa_exception_fp_ieee_overflow 0
		.amdhsa_exception_fp_ieee_underflow 0
		.amdhsa_exception_fp_ieee_inexact 0
		.amdhsa_exception_int_div_zero 0
	.end_amdhsa_kernel

; __global__ void __launch_bounds__(NTHREADS, 2) fwd_megakernel(Params p) {
.Lfunc_end0:
	.size	_Z14fwd_megakernel6Params, .Lfunc_end0-_Z14fwd_megakernel6Params
	.set _Z14fwd_megakernel6Params.num_vgpr, 256
	.set _Z14fwd_megakernel6Params.num_agpr, 0
	.set _Z14fwd_megakernel6Params.numbered_sgpr, 102
	.set _Z14fwd_megakernel6Params.num_named_barrier, 0
	.set _Z14fwd_megakernel6Params.private_seg_size, 0
	.set _Z14fwd_megakernel6Params.uses_vcc, 1
	.set _Z14fwd_megakernel6Params.uses_flat_scratch, 0
	.set _Z14fwd_megakernel6Params.has_dyn_sized_stack, 0
	.set _Z14fwd_megakernel6Params.has_recursion, 0
	.set _Z14fwd_megakernel6Params.has_indirect_call, 0

; __global__ void __launch_bounds__(NTHREADS, 2) fwd_megakernel(Params p) {
amdhsa.kernels:
  - .agpr_count:     0
    .args:
      - .offset:         0
        .size:           128
        .value_kind:     by_value
      - .offset:         128
        .size:           4
        .value_kind:     hidden_block_count_x
      - .offset:         132
        .size:           4
        .value_kind:     hidden_block_count_y
      - .offset:         136
        .size:           4
        .value_kind:     hidden_block_count_z
      - .offset:         140
        .size:           2
        .value_kind:     hidden_group_size_x
      - .offset:         142
        .size:           2
        .value_kind:     hidden_group_size_y
      - .offset:         144
        .size:           2
        .value_kind:     hidden_group_size_z
      - .offset:         146
        .size:           2
        .value_kind:     hidden_remainder_x
      - .offset:         148
        .size:           2
        .value_kind:     hidden_remainder_y
      - .offset:         150
        .size:           2
        .value_kind:     hidden_remainder_z
      - .offset:         168
        .size:           8
        .value_kind:     hidden_global_offset_x
      - .offset:         176
        .size:           8
        .value_kind:     hidden_global_offset_y
      - .offset:         184
        .size:           8
        .value_kind:     hidden_global_offset_z
      - .offset:         192
        .size:           2
        .value_kind:     hidden_grid_dims
      - .offset:         248
        .size:           4
        .value_kind:     hidden_dynamic_lds_size
    .group_segment_fixed_size: 0
    .kernarg_segment_align: 8
    .kernarg_segment_size: 384
    .language:       OpenCL C
    .language_version:
      - 2
      - 0
    .max_flat_workgroup_size: 512
    .name:           _Z14fwd_megakernel6Params
    .private_segment_fixed_size: 0
    .sgpr_count:     108
    .sgpr_spill_count: 8
    .symbol:         _Z14fwd_megakernel6Params.kd
    .uniform_work_group_size: 1
    .uses_dynamic_stack: false
    .vgpr_count:     256
    .vgpr_spill_count: 0
    .wavefront_size: 64
